# e30 lever 4: GEMM K-loops - per-segment s_setprio flips removed, one static s_setprio 1 for waves 4-7 before each K-loop (reset after)
# speedup vs baseline: 1.0043x; 1.0018x over previous
; template <class Epi, class Sched, bool ALIGN_EPI = false, bool SP2 = false>
; __device__ __forceinline__ void gemm_phase(PG8_LAS unsigned char* lds, const Gemm g, const Sched& S, const Epi& E) {
;     ...
;     Unit cur, nxt; int ui = 0;
;     if (!S.next(0, cur)) return;
;     f32x4 acc[2][2][4][2];
; #pragma unroll
;     for (int a = 0; a < 2; ++a)
; #pragma unroll
;         for (int b = 0; b < 2; ++b)
; #pragma unroll
;             for (int m = 0; m < 4; ++m)
; #pragma unroll
;                 for (int n = 0; n < 2; ++n) acc[a][b][m][n] = (f32x4){0.f, 0.f, 0.f, 0.f};
;     bf16x8 At[4][2], B0[2][2], B1[2][2];
;     const char* cA = PG8_UA(cur); const char* cB = PG8_UB(cur);
;     ...
;     for (;;) {
;         const bool has_next = S.next(ui + 1, nxt);
;         const char* nA = has_next ? PG8_UA(nxt) : cA; const char* nB = has_next ? PG8_UB(nxt) : cB;
;         for (int t = 0; t < nt; t += 2) {
.LBB0_203:
	s_ashr_i32 s43, s42, 31
	s_lshl_b64 s[4:5], s[42:43], 20
	s_add_u32 s48, s67, s4
	s_addc_u32 s49, s77, s5
	s_and_b64 s[4:5], s[38:39], exec
	s_cselect_b32 s4, s49, s37
	s_cselect_b32 s5, s48, s36
	s_ashr_i32 s21, s20, 31
	s_lshl_b64 s[6:7], s[20:21], 20
	s_add_u32 s50, s0, s6
	s_addc_u32 s51, s1, s7
	s_and_b64 s[6:7], s[38:39], exec
	s_cselect_b32 s6, s51, s57
	s_cselect_b32 s7, s50, s56
	s_add_u32 s36, s36, 0x80080
	s_addc_u32 s37, s37, 0
	s_add_u32 s21, s56, 0x100
	v_mov_b32_e32 v4, 0
	s_addc_u32 s41, s57, 0
	s_mov_b32 s43, -2
	v_mov_b32_e32 v5, v4
	v_mov_b32_e32 v6, v4
	v_mov_b32_e32 v7, v4
	v_mov_b32_e32 v8, v4
	v_mov_b32_e32 v9, v4
	v_mov_b32_e32 v10, v4
	v_mov_b32_e32 v11, v4
	v_mov_b32_e32 v20, v4
	v_mov_b32_e32 v21, v4
	v_mov_b32_e32 v22, v4
	v_mov_b32_e32 v23, v4
	v_mov_b32_e32 v24, v4
	v_mov_b32_e32 v25, v4
	v_mov_b32_e32 v26, v4
	v_mov_b32_e32 v27, v4
	v_mov_b32_e32 v36, v4
	v_mov_b32_e32 v37, v4
	v_mov_b32_e32 v38, v4
	v_mov_b32_e32 v39, v4
	v_mov_b32_e32 v40, v4
	v_mov_b32_e32 v41, v4
	v_mov_b32_e32 v42, v4
	v_mov_b32_e32 v43, v4
	v_mov_b32_e32 v52, v4
	v_mov_b32_e32 v53, v4
	v_mov_b32_e32 v54, v4
	v_mov_b32_e32 v55, v4
	v_mov_b32_e32 v56, v4
	v_mov_b32_e32 v57, v4
	v_mov_b32_e32 v58, v4
	v_mov_b32_e32 v59, v4
	v_mov_b32_e32 v12, v4
	v_mov_b32_e32 v13, v4
	v_mov_b32_e32 v14, v4
	v_mov_b32_e32 v15, v4
	v_mov_b32_e32 v16, v4
	v_mov_b32_e32 v17, v4
	v_mov_b32_e32 v18, v4
	v_mov_b32_e32 v19, v4
	v_mov_b32_e32 v28, v4
	v_mov_b32_e32 v29, v4
	v_mov_b32_e32 v30, v4
	v_mov_b32_e32 v31, v4
	v_mov_b32_e32 v32, v4
	v_mov_b32_e32 v33, v4
	v_mov_b32_e32 v34, v4
	v_mov_b32_e32 v35, v4
	v_mov_b32_e32 v44, v4
	v_mov_b32_e32 v45, v4
	v_mov_b32_e32 v46, v4
	v_mov_b32_e32 v47, v4
	v_mov_b32_e32 v48, v4
	v_mov_b32_e32 v49, v4
	v_mov_b32_e32 v50, v4
	v_mov_b32_e32 v51, v4
	v_mov_b32_e32 v60, v4
	v_mov_b32_e32 v61, v4
	v_mov_b32_e32 v62, v4
	v_mov_b32_e32 v63, v4
	v_mov_b32_e32 v64, v4
	v_mov_b32_e32 v65, v4
	v_mov_b32_e32 v66, v4
	v_mov_b32_e32 v67, v4
	v_mov_b32_e32 v68, v4
	v_mov_b32_e32 v69, v4
	v_mov_b32_e32 v70, v4
	v_mov_b32_e32 v71, v4
	v_mov_b32_e32 v72, v4
	v_mov_b32_e32 v73, v4
	v_mov_b32_e32 v74, v4
	v_mov_b32_e32 v75, v4
	v_mov_b32_e32 v84, v4
	v_mov_b32_e32 v85, v4
	v_mov_b32_e32 v86, v4
	v_mov_b32_e32 v87, v4
	v_mov_b32_e32 v88, v4
	v_mov_b32_e32 v89, v4
	v_mov_b32_e32 v90, v4
	v_mov_b32_e32 v91, v4
	v_mov_b32_e32 v100, v4
	v_mov_b32_e32 v101, v4
	v_mov_b32_e32 v102, v4
	v_mov_b32_e32 v103, v4
	v_mov_b32_e32 v104, v4
	v_mov_b32_e32 v105, v4
	v_mov_b32_e32 v106, v4
	v_mov_b32_e32 v107, v4
	v_mov_b32_e32 v116, v4
	v_mov_b32_e32 v117, v4
	v_mov_b32_e32 v118, v4
	v_mov_b32_e32 v119, v4
	v_mov_b32_e32 v120, v4
	v_mov_b32_e32 v121, v4
	v_mov_b32_e32 v122, v4
	v_mov_b32_e32 v123, v4
	v_mov_b32_e32 v76, v4
	v_mov_b32_e32 v77, v4
	v_mov_b32_e32 v78, v4
	v_mov_b32_e32 v79, v4
	v_mov_b32_e32 v80, v4
	v_mov_b32_e32 v81, v4
	v_mov_b32_e32 v82, v4
	v_mov_b32_e32 v83, v4
	v_mov_b32_e32 v92, v4
	v_mov_b32_e32 v93, v4
	v_mov_b32_e32 v94, v4
	v_mov_b32_e32 v95, v4
	v_mov_b32_e32 v96, v4
	v_mov_b32_e32 v97, v4
	v_mov_b32_e32 v98, v4
	v_mov_b32_e32 v99, v4
	v_mov_b32_e32 v108, v4
	v_mov_b32_e32 v109, v4
	v_mov_b32_e32 v110, v4
	v_mov_b32_e32 v111, v4
	v_mov_b32_e32 v112, v4
	v_mov_b32_e32 v113, v4
	v_mov_b32_e32 v114, v4
	v_mov_b32_e32 v115, v4
	v_mov_b32_e32 v124, v4
	v_mov_b32_e32 v125, v4
	v_mov_b32_e32 v126, v4
	v_mov_b32_e32 v127, v4
	v_mov_b32_e32 v128, v4
	v_mov_b32_e32 v129, v4
	v_mov_b32_e32 v130, v4
	v_mov_b32_e32 v131, v4
	s_nop 0
	v_readfirstlane_b32 s98, v0
	s_nop 3
	s_lshr_b32 s98, s98, 6
	s_cmp_ge_u32 s98, 4
	s_cbranch_scc0 .Lprio_g0
	s_setprio 1

; #define PG8_STAGE(bufoff, gbase, voff) do { _Pragma("unroll") for (int _i = 0; _i < 2; ++_i) \
;         __builtin_amdgcn_global_load_lds((const unsigned*)((const char*)(gbase) + (voff)[_i]), (PG8_LAS unsigned*)(lds + (bufoff) + ldsw + _i * 8192), 16, 0, 0); } while (0)
; #define PG8_LDA(dst, b, h) do { _Pragma("unroll") for (int m = 0; m < 4; ++m) _Pragma("unroll") for (int k = 0; k < 2; ++k) dst[m][k] = *(const PG8_LAS bf16x8*)(lds + PG8_SA(b, h) + aoff + m * 2048 + k * 1024); } while (0)
; #define PG8_LDB(dst, b, h) do { _Pragma("unroll") for (int n = 0; n < 2; ++n) _Pragma("unroll") for (int k = 0; k < 2; ++k) dst[n][k] = *(const PG8_LAS bf16x8*)(lds + PG8_SB(b, h) + boff + n * 2048 + k * 1024); } while (0)
; #define PG8_MMA(ai, bj, At, Bt) do { __builtin_amdgcn_s_setprio(1); _Pragma("unroll") for (int m = 0; m < 4; ++m) _Pragma("unroll") for (int n = 0; n < 2; ++n) _Pragma("unroll") for (int k = 0; k < 2; ++k) \
;         acc[ai][bj][m][n] = __builtin_amdgcn_mfma_f32_16x16x32_bf16(Bt[n][k], At[m][k], acc[ai][bj][m][n], 0, 0, 0); __builtin_amdgcn_s_setprio(0); } while (0)
; #define PG8_WAIT_V(n) asm volatile("s_waitcnt vmcnt(" #n ")" ::: "memory")
; #define PG8_WAIT_L(n) asm volatile("s_waitcnt lgkmcnt(" #n ")" ::: "memory")
; #define PG8_BAR __builtin_amdgcn_s_barrier()
; #define PG8_SCHED __builtin_amdgcn_sched_barrier(0)
; template <class Epi, class Sched, bool ALIGN_EPI = false, bool SP2 = false>
; __device__ __forceinline__ void gemm_phase(PG8_LAS unsigned char* lds, const Gemm g, const Sched& S, const Epi& E) {
;     ...
;             PG8_LDB(B0, 0, 0); PG8_LDB(B1, 0, 1); PG8_SCHED; PG8_LDA(At, 0, 0); PG8_STAGE(PG8_SA(1, 1), a1 + hstepA, voffA);
;             PG8_WAIT_V(8); PG8_WAIT_L(0); PG8_BAR; PG8_MMA(0, 0, At, B0); PG8_MMA(0, 1, At, B1); PG8_BAR; PG8_SCHED;
;             PG8_LDA(At, 0, 1); PG8_STAGE(PG8_SB(0, 0), b2, voffB); PG8_STAGE(PG8_SB(0, 1), b2 + hstepB, voffB); PG8_STAGE(PG8_SA(0, 0), a2, voffA);
;             PG8_WAIT_V(8); PG8_WAIT_L(0); PG8_BAR; PG8_MMA(1, 0, At, B0); PG8_MMA(1, 1, At, B1); PG8_BAR; PG8_SCHED;
.LBB0_204:
	s_add_u32 s8, s36, 0xfff80080
	s_addc_u32 s9, s37, -1
	s_add_i32 s14, 0, 0x10000
	s_cmp_eq_u32 s43, 28
	s_cselect_b32 s59, s4, s9
	s_cselect_b32 s58, s5, s8
	v_add_u32_e32 v2, s14, v185
	s_cselect_b32 s57, s6, s41
	s_cselect_b32 s56, s7, s21
	s_add_i32 s15, 0, 0x14000
	ds_read_b128 v[172:175], v2
	ds_read_b128 v[176:179], v2 offset:1024
	ds_read_b128 v[180:183], v2 offset:2048
	ds_read_b128 v[188:191], v2 offset:3072
	v_add_u32_e32 v2, s15, v185
	ds_read_b128 v[192:195], v2
	ds_read_b128 v[208:211], v2 offset:1024
	ds_read_b128 v[212:215], v2 offset:2048
	ds_read_b128 v[216:219], v2 offset:3072
	v_lshl_add_u64 v[156:157], s[36:37], 0, v[140:141]
	s_add_i32 m0, s53, 0xc000
	ds_read_b128 v[220:223], v187
	ds_read_b128 v[224:227], v187 offset:1024
	ds_read_b128 v[228:231], v187 offset:2048
	ds_read_b128 v[232:235], v187 offset:3072
	ds_read_b128 v[236:239], v187 offset:4096
	ds_read_b128 v[240:243], v187 offset:5120
	ds_read_b128 v[244:247], v187 offset:6144
	ds_read_b128 v[248:251], v187 offset:7168
	global_load_lds_dwordx4 v[156:157], off
	v_lshl_add_u64 v[156:157], s[36:37], 0, v[142:143]
	s_add_i32 m0, s53, 0xe000
	s_nop 0
	global_load_lds_dwordx4 v[156:157], off
	s_waitcnt vmcnt(8)
	s_waitcnt lgkmcnt(0)
	s_barrier
	s_waitcnt lgkmcnt(0)
	v_mfma_f32_16x16x32_bf16 v[128:131], v[172:175], v[220:223], v[128:131]
	v_mfma_f32_16x16x32_bf16 v[124:127], v[180:183], v[220:223], v[124:127]
	v_mfma_f32_16x16x32_bf16 v[112:115], v[172:175], v[228:231], v[112:115]
	v_mfma_f32_16x16x32_bf16 v[108:111], v[180:183], v[228:231], v[108:111]
	v_mfma_f32_16x16x32_bf16 v[96:99], v[172:175], v[236:239], v[96:99]
	v_mfma_f32_16x16x32_bf16 v[92:95], v[180:183], v[236:239], v[92:95]
	v_mfma_f32_16x16x32_bf16 v[80:83], v[172:175], v[244:247], v[80:83]
	v_mfma_f32_16x16x32_bf16 v[76:79], v[180:183], v[244:247], v[76:79]
	v_mfma_f32_16x16x32_bf16 v[128:131], v[176:179], v[224:227], v[128:131]
	v_mfma_f32_16x16x32_bf16 v[124:127], v[188:191], v[224:227], v[124:127]
	v_mfma_f32_16x16x32_bf16 v[112:115], v[176:179], v[232:235], v[112:115]
	v_mfma_f32_16x16x32_bf16 v[108:111], v[188:191], v[232:235], v[108:111]
	v_mfma_f32_16x16x32_bf16 v[96:99], v[176:179], v[240:243], v[96:99]
	v_mfma_f32_16x16x32_bf16 v[92:95], v[188:191], v[240:243], v[92:95]
	v_mfma_f32_16x16x32_bf16 v[80:83], v[176:179], v[248:251], v[80:83]
	v_mfma_f32_16x16x32_bf16 v[76:79], v[188:191], v[248:251], v[76:79]
	v_mfma_f32_16x16x32_bf16 v[120:123], v[192:195], v[220:223], v[120:123]
	v_mfma_f32_16x16x32_bf16 v[116:119], v[212:215], v[220:223], v[116:119]
	v_mfma_f32_16x16x32_bf16 v[104:107], v[192:195], v[228:231], v[104:107]
	v_mfma_f32_16x16x32_bf16 v[100:103], v[212:215], v[228:231], v[100:103]
	v_mfma_f32_16x16x32_bf16 v[88:91], v[192:195], v[236:239], v[88:91]
	v_mfma_f32_16x16x32_bf16 v[84:87], v[212:215], v[236:239], v[84:87]
	v_mfma_f32_16x16x32_bf16 v[72:75], v[192:195], v[244:247], v[72:75]
	v_mfma_f32_16x16x32_bf16 v[68:71], v[212:215], v[244:247], v[68:71]
	v_mfma_f32_16x16x32_bf16 v[120:123], v[208:211], v[224:227], v[120:123]
	v_mfma_f32_16x16x32_bf16 v[116:119], v[216:219], v[224:227], v[116:119]
	v_mfma_f32_16x16x32_bf16 v[104:107], v[208:211], v[232:235], v[104:107]
	v_mfma_f32_16x16x32_bf16 v[100:103], v[216:219], v[232:235], v[100:103]
	v_mfma_f32_16x16x32_bf16 v[88:91], v[208:211], v[240:243], v[88:91]
	v_mfma_f32_16x16x32_bf16 v[84:87], v[216:219], v[240:243], v[84:87]
	v_mfma_f32_16x16x32_bf16 v[72:75], v[208:211], v[248:251], v[72:75]
	v_mfma_f32_16x16x32_bf16 v[68:71], v[216:219], v[248:251], v[68:71]
	s_barrier
	s_add_i32 s8, s14, s78
	v_lshl_add_u64 v[156:157], s[56:57], 0, v[134:135]
	s_mov_b32 m0, s8
	ds_read_b128 v[220:223], v187 offset:16384
	ds_read_b128 v[224:227], v187 offset:17408
	ds_read_b128 v[228:231], v187 offset:18432
	ds_read_b128 v[232:235], v187 offset:19456
	ds_read_b128 v[236:239], v187 offset:20480
	ds_read_b128 v[240:243], v187 offset:21504
	ds_read_b128 v[244:247], v187 offset:22528
	ds_read_b128 v[248:251], v187 offset:23552
	global_load_lds_dwordx4 v[156:157], off
	s_add_i32 m0, s8, 0x2000
	s_add_u32 s8, s56, 0x80000
	v_lshl_add_u64 v[158:159], s[56:57], 0, v[138:139]
	s_addc_u32 s9, s57, 0
	s_add_i32 s14, s15, s78
	global_load_lds_dwordx4 v[158:159], off
	v_lshl_add_u64 v[164:165], s[8:9], 0, v[134:135]
	s_mov_b32 m0, s14
	v_lshl_add_u64 v[196:197], s[58:59], 0, v[136:137]
	global_load_lds_dwordx4 v[164:165], off
	v_lshl_add_u64 v[164:165], s[8:9], 0, v[138:139]
	s_add_i32 m0, s14, 0x2000
	s_nop 0
	global_load_lds_dwordx4 v[164:165], off
	v_lshl_add_u64 v[164:165], s[58:59], 0, v[132:133]
	s_mov_b32 m0, s53
	s_nop 0
	global_load_lds_dwordx4 v[164:165], off
	s_mov_b32 m0, s79
	s_nop 0
	global_load_lds_dwordx4 v[196:197], off
	s_waitcnt vmcnt(8)
	s_waitcnt lgkmcnt(0)
	s_barrier
; #define PG8_STAGE(bufoff, gbase, voff) do { _Pragma("unroll") for (int _i = 0; _i < 2; ++_i) \
;         __builtin_amdgcn_global_load_lds((const unsigned*)((const char*)(gbase) + (voff)[_i]), (PG8_LAS unsigned*)(lds + (bufoff) + ldsw + _i * 8192), 16, 0, 0); } while (0)
; #define PG8_LDA(dst, b, h) do { _Pragma("unroll") for (int m = 0; m < 4; ++m) _Pragma("unroll") for (int k = 0; k < 2; ++k) dst[m][k] = *(const PG8_LAS bf16x8*)(lds + PG8_SA(b, h) + aoff + m * 2048 + k * 1024); } while (0)
; #define PG8_LDB(dst, b, h) do { _Pragma("unroll") for (int n = 0; n < 2; ++n) _Pragma("unroll") for (int k = 0; k < 2; ++k) dst[n][k] = *(const PG8_LAS bf16x8*)(lds + PG8_SB(b, h) + boff + n * 2048 + k * 1024); } while (0)
; #define PG8_MMA(ai, bj, At, Bt) do { __builtin_amdgcn_s_setprio(1); _Pragma("unroll") for (int m = 0; m < 4; ++m) _Pragma("unroll") for (int n = 0; n < 2; ++n) _Pragma("unroll") for (int k = 0; k < 2; ++k) \
;         acc[ai][bj][m][n] = __builtin_amdgcn_mfma_f32_16x16x32_bf16(Bt[n][k], At[m][k], acc[ai][bj][m][n], 0, 0, 0); __builtin_amdgcn_s_setprio(0); } while (0)
; #define PG8_WAIT_V(n) asm volatile("s_waitcnt vmcnt(" #n ")" ::: "memory")
; #define PG8_WAIT_L(n) asm volatile("s_waitcnt lgkmcnt(" #n ")" ::: "memory")
; #define PG8_BAR __builtin_amdgcn_s_barrier()
; #define PG8_SCHED __builtin_amdgcn_sched_barrier(0)
; template <class Epi, class Sched, bool ALIGN_EPI = false, bool SP2 = false>
; __device__ __forceinline__ void gemm_phase(PG8_LAS unsigned char* lds, const Gemm g, const Sched& S, const Epi& E) {
;     ...
;             PG8_WAIT_V(8); PG8_WAIT_L(0); PG8_BAR; PG8_MMA(1, 0, At, B0); PG8_MMA(1, 1, At, B1); PG8_BAR; PG8_SCHED;
;             PG8_LDB(B0, 1, 0); PG8_LDB(B1, 1, 1); PG8_SCHED; PG8_LDA(At, 1, 0); PG8_STAGE(PG8_SA(0, 1), a2 + hstepA, voffA);
;             PG8_WAIT_V(8); PG8_WAIT_L(0); PG8_BAR; PG8_MMA(0, 0, At, B0); PG8_MMA(0, 1, At, B1); PG8_BAR; PG8_SCHED;
	s_waitcnt lgkmcnt(0)
	v_mfma_f32_16x16x32_bf16 v[64:67], v[172:175], v[220:223], v[64:67]
	v_mfma_f32_16x16x32_bf16 v[60:63], v[180:183], v[220:223], v[60:63]
	v_mfma_f32_16x16x32_bf16 v[48:51], v[172:175], v[228:231], v[48:51]
	v_mfma_f32_16x16x32_bf16 v[44:47], v[180:183], v[228:231], v[44:47]
	v_mfma_f32_16x16x32_bf16 v[32:35], v[172:175], v[236:239], v[32:35]
	v_mfma_f32_16x16x32_bf16 v[28:31], v[180:183], v[236:239], v[28:31]
	v_mfma_f32_16x16x32_bf16 v[16:19], v[172:175], v[244:247], v[16:19]
	v_mfma_f32_16x16x32_bf16 v[12:15], v[180:183], v[244:247], v[12:15]
	v_mfma_f32_16x16x32_bf16 v[64:67], v[176:179], v[224:227], v[64:67]
	v_mfma_f32_16x16x32_bf16 v[60:63], v[188:191], v[224:227], v[60:63]
	v_mfma_f32_16x16x32_bf16 v[48:51], v[176:179], v[232:235], v[48:51]
	v_mfma_f32_16x16x32_bf16 v[44:47], v[188:191], v[232:235], v[44:47]
	v_mfma_f32_16x16x32_bf16 v[32:35], v[176:179], v[240:243], v[32:35]
	v_mfma_f32_16x16x32_bf16 v[28:31], v[188:191], v[240:243], v[28:31]
	v_mfma_f32_16x16x32_bf16 v[16:19], v[176:179], v[248:251], v[16:19]
	v_mfma_f32_16x16x32_bf16 v[12:15], v[188:191], v[248:251], v[12:15]
	v_mfma_f32_16x16x32_bf16 v[56:59], v[192:195], v[220:223], v[56:59]
	v_mfma_f32_16x16x32_bf16 v[52:55], v[212:215], v[220:223], v[52:55]
	v_mfma_f32_16x16x32_bf16 v[40:43], v[192:195], v[228:231], v[40:43]
	v_mfma_f32_16x16x32_bf16 v[36:39], v[212:215], v[228:231], v[36:39]
	v_mfma_f32_16x16x32_bf16 v[24:27], v[192:195], v[236:239], v[24:27]
	v_mfma_f32_16x16x32_bf16 v[20:23], v[212:215], v[236:239], v[20:23]
	v_mfma_f32_16x16x32_bf16 v[8:11], v[192:195], v[244:247], v[8:11]
	v_mfma_f32_16x16x32_bf16 v[4:7], v[212:215], v[244:247], v[4:7]
	v_mfma_f32_16x16x32_bf16 v[56:59], v[208:211], v[224:227], v[56:59]
	v_mfma_f32_16x16x32_bf16 v[52:55], v[216:219], v[224:227], v[52:55]
	v_mfma_f32_16x16x32_bf16 v[40:43], v[208:211], v[232:235], v[40:43]
	v_mfma_f32_16x16x32_bf16 v[36:39], v[216:219], v[232:235], v[36:39]
	v_mfma_f32_16x16x32_bf16 v[24:27], v[208:211], v[240:243], v[24:27]
	v_mfma_f32_16x16x32_bf16 v[20:23], v[216:219], v[240:243], v[20:23]
	v_mfma_f32_16x16x32_bf16 v[8:11], v[208:211], v[248:251], v[8:11]
	v_mfma_f32_16x16x32_bf16 v[4:7], v[216:219], v[248:251], v[4:7]
	s_barrier
	s_add_i32 s14, 0, 0x18000
	v_add_u32_e32 v2, s14, v185
	s_add_i32 s15, 0, 0x1c000
	ds_read_b128 v[172:175], v2
	ds_read_b128 v[176:179], v2 offset:1024
	ds_read_b128 v[180:183], v2 offset:2048
	ds_read_b128 v[188:191], v2 offset:3072
	v_add_u32_e32 v2, s15, v185
	ds_read_b128 v[192:195], v2
	ds_read_b128 v[208:211], v2 offset:1024
	ds_read_b128 v[212:215], v2 offset:2048
	ds_read_b128 v[216:219], v2 offset:3072
	s_add_u32 s8, s58, 0x80000
	s_addc_u32 s9, s59, 0
	s_mov_b32 m0, s80
	v_lshl_add_u64 v[200:201], s[8:9], 0, v[132:133]
	ds_read_b128 v[220:223], v187 offset:32768
	ds_read_b128 v[224:227], v187 offset:33792
	ds_read_b128 v[228:231], v187 offset:34816
	ds_read_b128 v[232:235], v187 offset:35840
	ds_read_b128 v[236:239], v187 offset:36864
	ds_read_b128 v[240:243], v187 offset:37888
	ds_read_b128 v[244:247], v187 offset:38912
	ds_read_b128 v[248:251], v187 offset:39936
	global_load_lds_dwordx4 v[200:201], off
	v_lshl_add_u64 v[200:201], s[8:9], 0, v[136:137]
	s_mov_b32 m0, s81
	s_nop 0
	global_load_lds_dwordx4 v[200:201], off
	s_waitcnt vmcnt(8)
	s_waitcnt lgkmcnt(0)
	s_barrier
	s_waitcnt lgkmcnt(0)
	v_mfma_f32_16x16x32_bf16 v[128:131], v[172:175], v[220:223], v[128:131]
	v_mfma_f32_16x16x32_bf16 v[124:127], v[180:183], v[220:223], v[124:127]
	v_mfma_f32_16x16x32_bf16 v[112:115], v[172:175], v[228:231], v[112:115]
	v_mfma_f32_16x16x32_bf16 v[108:111], v[180:183], v[228:231], v[108:111]
	v_mfma_f32_16x16x32_bf16 v[96:99], v[172:175], v[236:239], v[96:99]
	v_mfma_f32_16x16x32_bf16 v[92:95], v[180:183], v[236:239], v[92:95]
	v_mfma_f32_16x16x32_bf16 v[80:83], v[172:175], v[244:247], v[80:83]
	v_mfma_f32_16x16x32_bf16 v[76:79], v[180:183], v[244:247], v[76:79]
	v_mfma_f32_16x16x32_bf16 v[128:131], v[176:179], v[224:227], v[128:131]
	v_mfma_f32_16x16x32_bf16 v[124:127], v[188:191], v[224:227], v[124:127]
	v_mfma_f32_16x16x32_bf16 v[112:115], v[176:179], v[232:235], v[112:115]
	v_mfma_f32_16x16x32_bf16 v[108:111], v[188:191], v[232:235], v[108:111]
	v_mfma_f32_16x16x32_bf16 v[96:99], v[176:179], v[240:243], v[96:99]
	v_mfma_f32_16x16x32_bf16 v[92:95], v[188:191], v[240:243], v[92:95]
	v_mfma_f32_16x16x32_bf16 v[80:83], v[176:179], v[248:251], v[80:83]
	v_mfma_f32_16x16x32_bf16 v[76:79], v[188:191], v[248:251], v[76:79]
	v_mfma_f32_16x16x32_bf16 v[120:123], v[192:195], v[220:223], v[120:123]
	v_mfma_f32_16x16x32_bf16 v[116:119], v[212:215], v[220:223], v[116:119]
	v_mfma_f32_16x16x32_bf16 v[104:107], v[192:195], v[228:231], v[104:107]
	v_mfma_f32_16x16x32_bf16 v[100:103], v[212:215], v[228:231], v[100:103]
	v_mfma_f32_16x16x32_bf16 v[88:91], v[192:195], v[236:239], v[88:91]
	v_mfma_f32_16x16x32_bf16 v[84:87], v[212:215], v[236:239], v[84:87]
	v_mfma_f32_16x16x32_bf16 v[72:75], v[192:195], v[244:247], v[72:75]
	v_mfma_f32_16x16x32_bf16 v[68:71], v[212:215], v[244:247], v[68:71]
	v_mfma_f32_16x16x32_bf16 v[120:123], v[208:211], v[224:227], v[120:123]
	v_mfma_f32_16x16x32_bf16 v[116:119], v[216:219], v[224:227], v[116:119]
	v_mfma_f32_16x16x32_bf16 v[104:107], v[208:211], v[232:235], v[104:107]
	v_mfma_f32_16x16x32_bf16 v[100:103], v[216:219], v[232:235], v[100:103]
	v_mfma_f32_16x16x32_bf16 v[88:91], v[208:211], v[240:243], v[88:91]
	v_mfma_f32_16x16x32_bf16 v[84:87], v[216:219], v[240:243], v[84:87]
	v_mfma_f32_16x16x32_bf16 v[72:75], v[208:211], v[248:251], v[72:75]
	v_mfma_f32_16x16x32_bf16 v[68:71], v[216:219], v[248:251], v[68:71]
	s_barrier
; #define PG8_WAIT_V(n) asm volatile("s_waitcnt vmcnt(" #n ")" ::: "memory")
; #define PG8_BAR __builtin_amdgcn_s_barrier()
; template <class Epi, class Sched, bool ALIGN_EPI = false, bool SP2 = false>
; __device__ __forceinline__ void gemm_phase(PG8_LAS unsigned char* lds, const Gemm g, const Sched& S, const Epi& E) {
;     ...
;             PG8_LDA(At, 1, 1); PG8_STAGE(PG8_SB(1, 0), b3, voffB); PG8_STAGE(PG8_SB(1, 1), b3 + hstepB, voffB); PG8_STAGE(PG8_SA(1, 0), a3, voffA);
;             PG8_WAIT_V(8); PG8_WAIT_L(0); PG8_BAR; PG8_MMA(1, 0, At, B0); PG8_MMA(1, 1, At, B1); PG8_BAR; PG8_SCHED;
;             } else {
;             PG8_LDB(B0, 0, 0); PG8_SCHED; PG8_LDA(At, 0, 0); PG8_STAGE(PG8_SA(1, 1), a1 + hstepA, voffA);
;             PG8_WAIT_L(8); PG8_BAR; PG8_WAIT_L(0); PG8_MMA(0, 0, At, B0); PG8_BAR; PG8_SCHED;
;             PG8_LDB(B1, 0, 1); PG8_STAGE(PG8_SB(0, 0), b2, voffB);
;             PG8_BAR; PG8_WAIT_L(0); PG8_MMA(0, 1, At, B1); PG8_BAR;
;             PG8_LDA(At, 0, 1); PG8_STAGE(PG8_SA(0, 0), a2, voffA);
;             PG8_BAR; PG8_WAIT_L(0); PG8_MMA(1, 0, At, B0); PG8_BAR; PG8_SCHED;
;             PG8_STAGE(PG8_SB(0, 1), b2 + hstepB, voffB);
;             PG8_WAIT_V(6); PG8_BAR; PG8_MMA(1, 1, At, B1); PG8_BAR;
;             PG8_LDB(B0, 1, 0); PG8_SCHED; PG8_LDA(At, 1, 0); PG8_STAGE(PG8_SA(0, 1), a2 + hstepA, voffA);
;             PG8_WAIT_L(8); PG8_BAR; PG8_WAIT_L(0); PG8_MMA(0, 0, At, B0); PG8_BAR; PG8_SCHED;
;             PG8_LDB(B1, 1, 1); PG8_STAGE(PG8_SB(1, 0), b3, voffB);
;             PG8_BAR; PG8_WAIT_L(0); PG8_MMA(0, 1, At, B1); PG8_BAR;
;             PG8_LDA(At, 1, 1); PG8_STAGE(PG8_SA(1, 0), a3, voffA);
;             PG8_BAR; PG8_WAIT_L(0); PG8_MMA(1, 0, At, B0); PG8_BAR; PG8_SCHED;
;             PG8_STAGE(PG8_SB(1, 1), b3 + hstepB, voffB);
;             PG8_WAIT_V(6); PG8_BAR; PG8_MMA(1, 1, At, B1); PG8_BAR;
;             }
;         }
;         if constexpr (ALIGN_EPI) { if (wr == 0) PG8_BAR; }
;     __device__ __forceinline__ void operator()(const f32x4 (&acc)[2][2][4][2], const Unit& u, int wr, int wc, int fr, int fq, const float (&rsv)[2][4]) const {
;         const int seg = u.pn >> 3, row0 = u.pm * BM + wr * 64 + fr, col0 = (u.pn & 7) * BM + wc * 32 + 8 * fq;
;         bf16_t* dst = (bf16_t*)((char*)Q + (size_t)(seg + (seg >> 1)) * (65 * MiB));
;         const bool smp = u.pm >= 64; const int frow0 = smp ? row0 - MP : row0;
	s_add_i32 s8, s14, s78
	v_lshl_add_u64 v[156:157], v[156:157], 0, s[24:25]
	s_mov_b32 m0, s8
	ds_read_b128 v[220:223], v187 offset:49152
	ds_read_b128 v[224:227], v187 offset:50176
	ds_read_b128 v[228:231], v187 offset:51200
	ds_read_b128 v[232:235], v187 offset:52224
	ds_read_b128 v[236:239], v187 offset:53248
	ds_read_b128 v[240:243], v187 offset:54272
	ds_read_b128 v[244:247], v187 offset:55296
	ds_read_b128 v[248:251], v187 offset:56320
	global_load_lds_dwordx4 v[156:157], off
	s_add_i32 m0, s8, 0x2000
	s_add_u32 s8, s56, 0x80080
	v_lshl_add_u64 v[156:157], v[158:159], 0, s[24:25]
	s_addc_u32 s9, s57, 0
	s_add_i32 s14, s15, s78
	global_load_lds_dwordx4 v[156:157], off
	v_lshl_add_u64 v[156:157], s[8:9], 0, v[134:135]
	s_mov_b32 m0, s14
	s_nop 0
	global_load_lds_dwordx4 v[156:157], off
	v_lshl_add_u64 v[156:157], s[8:9], 0, v[138:139]
	s_add_i32 m0, s14, 0x2000
	s_nop 0
	global_load_lds_dwordx4 v[156:157], off
	v_lshl_add_u64 v[156:157], v[164:165], 0, s[24:25]
	s_mov_b32 m0, s82
	s_nop 0
	global_load_lds_dwordx4 v[156:157], off
	v_lshl_add_u64 v[156:157], v[196:197], 0, s[24:25]
	s_mov_b32 m0, s83
	s_nop 0
	global_load_lds_dwordx4 v[156:157], off
	s_waitcnt vmcnt(8)
	s_waitcnt lgkmcnt(0)
	s_barrier
	s_waitcnt lgkmcnt(0)
	v_mfma_f32_16x16x32_bf16 v[64:67], v[172:175], v[220:223], v[64:67]
	v_mfma_f32_16x16x32_bf16 v[60:63], v[180:183], v[220:223], v[60:63]
	v_mfma_f32_16x16x32_bf16 v[48:51], v[172:175], v[228:231], v[48:51]
	v_mfma_f32_16x16x32_bf16 v[44:47], v[180:183], v[228:231], v[44:47]
	v_mfma_f32_16x16x32_bf16 v[32:35], v[172:175], v[236:239], v[32:35]
	v_mfma_f32_16x16x32_bf16 v[28:31], v[180:183], v[236:239], v[28:31]
	v_mfma_f32_16x16x32_bf16 v[16:19], v[172:175], v[244:247], v[16:19]
	v_mfma_f32_16x16x32_bf16 v[12:15], v[180:183], v[244:247], v[12:15]
	v_mfma_f32_16x16x32_bf16 v[64:67], v[176:179], v[224:227], v[64:67]
	v_mfma_f32_16x16x32_bf16 v[60:63], v[188:191], v[224:227], v[60:63]
	v_mfma_f32_16x16x32_bf16 v[48:51], v[176:179], v[232:235], v[48:51]
	v_mfma_f32_16x16x32_bf16 v[44:47], v[188:191], v[232:235], v[44:47]
	v_mfma_f32_16x16x32_bf16 v[32:35], v[176:179], v[240:243], v[32:35]
	v_mfma_f32_16x16x32_bf16 v[28:31], v[188:191], v[240:243], v[28:31]
	v_mfma_f32_16x16x32_bf16 v[16:19], v[176:179], v[248:251], v[16:19]
	v_mfma_f32_16x16x32_bf16 v[12:15], v[188:191], v[248:251], v[12:15]
	v_mfma_f32_16x16x32_bf16 v[56:59], v[192:195], v[220:223], v[56:59]
	v_mfma_f32_16x16x32_bf16 v[52:55], v[212:215], v[220:223], v[52:55]
	v_mfma_f32_16x16x32_bf16 v[40:43], v[192:195], v[228:231], v[40:43]
	v_mfma_f32_16x16x32_bf16 v[36:39], v[212:215], v[228:231], v[36:39]
	v_mfma_f32_16x16x32_bf16 v[24:27], v[192:195], v[236:239], v[24:27]
	v_mfma_f32_16x16x32_bf16 v[20:23], v[212:215], v[236:239], v[20:23]
	v_mfma_f32_16x16x32_bf16 v[8:11], v[192:195], v[244:247], v[8:11]
	v_mfma_f32_16x16x32_bf16 v[4:7], v[212:215], v[244:247], v[4:7]
	v_mfma_f32_16x16x32_bf16 v[56:59], v[208:211], v[224:227], v[56:59]
	v_mfma_f32_16x16x32_bf16 v[52:55], v[216:219], v[224:227], v[52:55]
	v_mfma_f32_16x16x32_bf16 v[40:43], v[208:211], v[232:235], v[40:43]
	v_mfma_f32_16x16x32_bf16 v[36:39], v[216:219], v[232:235], v[36:39]
	v_mfma_f32_16x16x32_bf16 v[24:27], v[208:211], v[240:243], v[24:27]
	v_mfma_f32_16x16x32_bf16 v[20:23], v[216:219], v[240:243], v[20:23]
	v_mfma_f32_16x16x32_bf16 v[8:11], v[208:211], v[248:251], v[8:11]
	v_mfma_f32_16x16x32_bf16 v[4:7], v[216:219], v[248:251], v[4:7]
	s_barrier
	s_add_i32 s43, s43, 2
	s_add_u32 s36, s36, 0x100
	s_addc_u32 s37, s37, 0
	s_add_u32 s21, s21, 0x100
	s_addc_u32 s41, s41, 0
	s_cmp_gt_u32 s43, 29
	s_cbranch_scc0 .LBB0_204
	s_and_b64 vcc, exec, s[18:19]
	s_cbranch_vccz .LBB0_207
	s_barrier
.LBB0_207:
	s_setprio 0
	s_lshl_b32 s4, s40, 8
	s_and_b32 s4, s4, 0x700
	s_ashr_i32 s8, s40, 3
	v_or_b32_e32 v147, s4, v186
	s_ashr_i32 s4, s40, 4
	s_add_i32 s4, s8, s4
	s_mul_hi_i32 s5, s4, 0x4100000
	s_mul_i32 s4, s4, 0x4100000
	s_add_u32 s4, s63, s4
	s_addc_u32 s5, s64, s5
	s_cmp_gt_i32 s52, 63
	s_cselect_b64 vcc, -1, 0
	s_and_b64 s[6:7], vcc, exec
	s_mov_b32 s6, 0x1a5fe000
	s_cselect_b32 s6, s6, 0xa5fe000
	s_cselect_b32 s9, 19, 25
	s_add_u32 s14, s44, s6
	s_addc_u32 s15, s45, 0
	s_cmp_gt_u32 s40, 7
	s_cselect_b64 s[36:37], -1, 0
	s_add_i32 s8, s8, -1
	v_lshl_add_u32 v172, s52, 8, v184
	s_cmp_lt_u32 s40, 8
	v_add_u32_e32 v2, 0xffffc000, v172
	s_cselect_b64 s[6:7], -1, 0
	v_cndmask_b32_e32 v174, v172, v2, vcc
	s_and_b64 vcc, s[6:7], exec
	s_cselect_b32 s6, 0, s8
	s_ashr_i32 s7, s6, 31
	s_lshl_b64 s[6:7], s[6:7], s9
	s_lshl_b64 s[6:7], s[6:7], 2
	s_add_u32 s6, s14, s6
	v_lshlrev_b32_e32 v2, 1, v147
	v_ashrrev_i32_e32 v173, 31, v172
	s_addc_u32 s7, s15, s7
	v_lshl_add_u64 v[176:177], s[4:5], 0, v[2:3]
	v_lshlrev_b32_e32 v2, 2, v147
	v_lshlrev_b64 v[156:157], 12, v[172:173]
	v_ashrrev_i32_e32 v175, 31, v174
	v_lshl_add_u64 v[178:179], s[6:7], 0, v[2:3]
	v_lshl_add_u64 v[182:183], v[176:177], 0, v[156:157]
	v_lshlrev_b64 v[156:157], 13, v[174:175]
	v_lshl_add_u64 v[180:181], v[178:179], 0, v[156:157]
	v_pk_mul_f32 v[130:131], v[154:155], v[130:131] op_sel_hi:[0,1]
	v_pk_mul_f32 v[128:129], v[154:155], v[128:129] op_sel_hi:[0,1]
	v_pk_mul_f32 v[126:127], v[154:155], v[126:127] op_sel_hi:[0,1]
	v_pk_mul_f32 v[124:125], v[154:155], v[124:125] op_sel_hi:[0,1]
	v_cvt_pk_bf16_f32 v188, v128, v129
	v_cvt_pk_bf16_f32 v189, v130, v131
	v_cvt_pk_bf16_f32 v190, v124, v125
	v_cvt_pk_bf16_f32 v191, v126, v127
	global_store_dwordx4 v[182:183], v[188:191], off
	s_cbranch_vccnz .LBB0_209
	global_store_dwordx4 v[180:181], v[128:131], off nt
	global_store_dwordx4 v[180:181], v[124:127], off offset:16 nt

; __device__ __forceinline__ int crow(int r, int hi) { return (r & 3) + 8 * (r >> 2) + 4 * hi; }
; __device__ __forceinline__ int crow(int r, int hi) { return (r & 3) + 8 * (r >> 2) + 4 * hi; }
; #define DMA_K(j_, b_) do { const char* kb_ = (const char*)Kh + (size_t)(j_) * (64 * LD * 2); _Pragma("unroll") for (int i = 0; i < 4; ++i) \
;     __builtin_amdgcn_global_load_lds((const unsigned*)(kb_ + kgo[i]), (LAS unsigned*)(K_las + (b_) * 16384 + (4 * a + i) * 1024), 16, 0, 0); } while (0)
; #define DMA_V(j_, b_) do { const char* vb_ = (const char*)Vh + (size_t)(j_) * (64 * LD * 2); _Pragma("unroll") for (int hf = 0; hf < 2; ++hf) _Pragma("unroll") for (int i = 0; i < 4; ++i) \
;     __builtin_amdgcn_global_load_lds((const unsigned*)(vb_ + hf * 256 + vgo[i]), (LAS unsigned*)(V_las + (b_) * 32768 + hf * 16384 + (4 * a + i) * 1024), 16, 0, 0); } while (0)
; __device__ __forceinline__ void attn_unit2(const bf16* __restrict__ Qb, const bf16* __restrict__ Kh, const bf16* __restrict__ Vh, bf16* __restrict__ Ob,
;                                            int NT, int lim, int qrow0, const float* lut, char* lds, float* scr) {
;     ...
;     for (int j = 0; j <= NT; ++j) {
;       if (j + 1 < NT) DMA_K(j + 1, (j + 1) & 1);
;       if (j < NT) DMA_V(j, j & 1);
;       if (j >= 1) {
;         const float* al = al0 + ((j - 1) & 1) * 128;
;         if (__any(al[r32] < 1.f) || __any(al[32 + r32] < 1.f)) {
; #pragma unroll
;           for (int rb = 0; rb < 2; ++rb)
; #pragma unroll
;             for (int d = 0; d < 4; ++d)
; #pragma unroll
;               for (int r = 0; r < 16; ++r) o[rb][d][r] *= al[rb * 32 + crow(r, hi)]; }
.LBB0_432:
	s_and_b32 s14, s7, 0x4000
	s_add_i32 s14, s6, s14
	v_lshl_add_u64 v[156:157], v[148:149], 0, s[36:37]
	s_mov_b32 m0, s14
	s_nop 0
	global_load_lds_dwordx4 v[156:157], off
	v_lshl_add_u64 v[156:157], v[150:151], 0, s[36:37]
	s_add_i32 m0, s14, 0x400
	s_nop 0
	global_load_lds_dwordx4 v[156:157], off
	v_lshl_add_u64 v[156:157], v[152:153], 0, s[36:37]
	s_add_i32 m0, s14, 0x800
	s_nop 0
	s_nop 0
	global_load_lds_dwordx4 v[156:157], off
	v_lshl_add_u64 v[156:157], v[154:155], 0, s[36:37]
	s_add_i32 m0, s14, 0xc00
	s_nop 0
	global_load_lds_dwordx4 v[156:157], off
.LBB0_433:
	s_and_b32 s14, s10, 1
	s_lshl_b32 s15, s14, 9
	s_add_i32 s15, s4, s15
	v_lshl_add_u32 v177, v172, 2, s15
	ds_read_b32 v200, v177
	s_and_b32 s23, s9, 0x8000
	s_add_i32 s23, s6, s23
	v_lshl_add_u64 v[156:157], v[138:139], 0, s[36:37]
	s_add_i32 m0, s23, 0x8000
	v_lshl_add_u64 v[158:159], v[156:157], 0, s[54:55]
	global_load_lds_dwordx4 v[158:159], off
	v_lshl_add_u64 v[158:159], v[142:143], 0, s[36:37]
	v_lshl_add_u64 v[164:165], v[158:159], 0, s[54:55]
	s_nop 0
	s_add_i32 m0, s23, 0x8400
	v_lshl_add_u64 v[156:157], v[156:157], 0, s[68:69]
	global_load_lds_dwordx4 v[164:165], off
	v_lshl_add_u64 v[164:165], v[144:145], 0, s[36:37]
	v_lshl_add_u64 v[178:179], v[164:165], 0, s[54:55]
	s_add_i32 m0, s23, 0x8800
	s_nop 0
	global_load_lds_dwordx4 v[178:179], off
	s_nop 0
	v_lshl_add_u64 v[178:179], v[146:147], 0, s[36:37]
	v_lshl_add_u64 v[180:181], v[178:179], 0, s[54:55]
	s_add_i32 m0, s23, 0x8c00
	s_nop 0
	global_load_lds_dwordx4 v[180:181], off
	v_lshl_add_u64 v[158:159], v[158:159], 0, s[68:69]
	v_lshl_add_u64 v[164:165], v[164:165], 0, s[68:69]
	v_lshl_add_u64 v[252:253], v[178:179], 0, s[68:69]
	s_waitcnt lgkmcnt(0)
	v_cmp_gt_f32_e32 vcc, 1.0, v200
	s_cmp_lg_u64 vcc, 0
	s_cselect_b64 s[46:47], -1, 0
	s_cbranch_vccz .LBB0_438
	s_andn2_b64 vcc, exec, s[46:47]
	s_cbranch_vccnz .LBB0_436
.LBB0_435:
	v_add_u32_e32 v201, s15, v140
	ds_read_b128 v[178:181], v201
	ds_read_b128 v[182:185], v201 offset:32
	ds_read_b128 v[186:189], v201 offset:64
	ds_read_b128 v[190:193], v201 offset:96
	s_waitcnt lgkmcnt(0)
	v_pk_mul_f32 v[118:119], v[118:119], v[180:181]
	v_pk_mul_f32 v[120:121], v[120:121], v[182:183]
	v_pk_mul_f32 v[124:125], v[124:125], v[186:187]
	v_pk_mul_f32 v[128:129], v[128:129], v[190:191]
	v_pk_mul_f32 v[130:131], v[130:131], v[192:193]
	v_pk_mul_f32 v[126:127], v[126:127], v[188:189]
	v_pk_mul_f32 v[122:123], v[122:123], v[184:185]
	v_pk_mul_f32 v[116:117], v[116:117], v[178:179]
	v_pk_mul_f32 v[112:113], v[112:113], v[190:191]
	v_pk_mul_f32 v[108:109], v[108:109], v[186:187]
	v_pk_mul_f32 v[104:105], v[104:105], v[182:183]
	v_pk_mul_f32 v[114:115], v[114:115], v[192:193]
	v_pk_mul_f32 v[110:111], v[110:111], v[188:189]
	v_pk_mul_f32 v[106:107], v[106:107], v[184:185]
	v_pk_mul_f32 v[102:103], v[102:103], v[180:181]
	v_pk_mul_f32 v[100:101], v[100:101], v[178:179]
	v_pk_mul_f32 v[96:97], v[96:97], v[190:191]
	v_pk_mul_f32 v[92:93], v[92:93], v[186:187]
	v_pk_mul_f32 v[88:89], v[88:89], v[182:183]
	v_pk_mul_f32 v[98:99], v[98:99], v[192:193]
	v_pk_mul_f32 v[94:95], v[94:95], v[188:189]
	v_pk_mul_f32 v[90:91], v[90:91], v[184:185]
	v_pk_mul_f32 v[86:87], v[86:87], v[180:181]
	v_pk_mul_f32 v[84:85], v[84:85], v[178:179]
	v_pk_mul_f32 v[80:81], v[80:81], v[190:191]
	v_pk_mul_f32 v[76:77], v[76:77], v[186:187]
	v_pk_mul_f32 v[72:73], v[72:73], v[182:183]
	v_pk_mul_f32 v[82:83], v[82:83], v[192:193]
	v_pk_mul_f32 v[78:79], v[78:79], v[188:189]
	v_pk_mul_f32 v[74:75], v[74:75], v[184:185]
	v_pk_mul_f32 v[70:71], v[70:71], v[180:181]
	v_pk_mul_f32 v[68:69], v[68:69], v[178:179]
	ds_read_b128 v[178:181], v201 offset:128
	ds_read_b128 v[182:185], v201 offset:160
	ds_read_b128 v[186:189], v201 offset:192
	ds_read_b128 v[190:193], v201 offset:224
	s_waitcnt lgkmcnt(0)
	v_pk_mul_f32 v[54:55], v[54:55], v[180:181]
	v_pk_mul_f32 v[56:57], v[56:57], v[182:183]
	v_pk_mul_f32 v[60:61], v[60:61], v[186:187]
	s_nop 0
	v_pk_mul_f32 v[64:65], v[64:65], v[190:191]
	v_pk_mul_f32 v[66:67], v[66:67], v[192:193]
	v_pk_mul_f32 v[62:63], v[62:63], v[188:189]
	v_pk_mul_f32 v[58:59], v[58:59], v[184:185]
	v_pk_mul_f32 v[52:53], v[52:53], v[178:179]
	v_pk_mul_f32 v[48:49], v[48:49], v[190:191]
	v_pk_mul_f32 v[44:45], v[44:45], v[186:187]
	v_pk_mul_f32 v[40:41], v[40:41], v[182:183]
	v_pk_mul_f32 v[50:51], v[50:51], v[192:193]
	v_pk_mul_f32 v[46:47], v[46:47], v[188:189]
	v_pk_mul_f32 v[42:43], v[42:43], v[184:185]
	v_pk_mul_f32 v[38:39], v[38:39], v[180:181]
	v_pk_mul_f32 v[36:37], v[36:37], v[178:179]
	v_pk_mul_f32 v[32:33], v[32:33], v[190:191]
	v_pk_mul_f32 v[28:29], v[28:29], v[186:187]
	v_pk_mul_f32 v[24:25], v[24:25], v[182:183]
	v_pk_mul_f32 v[34:35], v[34:35], v[192:193]
	v_pk_mul_f32 v[30:31], v[30:31], v[188:189]
	v_pk_mul_f32 v[26:27], v[26:27], v[184:185]
	v_pk_mul_f32 v[22:23], v[22:23], v[180:181]
	v_pk_mul_f32 v[20:21], v[20:21], v[178:179]
	v_pk_mul_f32 v[16:17], v[16:17], v[190:191]
	v_pk_mul_f32 v[12:13], v[12:13], v[186:187]
	v_pk_mul_f32 v[8:9], v[8:9], v[182:183]
	v_pk_mul_f32 v[18:19], v[18:19], v[192:193]
	v_pk_mul_f32 v[14:15], v[14:15], v[188:189]
	v_pk_mul_f32 v[10:11], v[10:11], v[184:185]
	v_pk_mul_f32 v[6:7], v[6:7], v[180:181]
	v_pk_mul_f32 v[4:5], v[4:5], v[178:179]
; #define SBAR() __builtin_amdgcn_sched_barrier(0)
; #define VRD(D0, L) const s16x4 L##0 = tr_read<v_rd_off(D0, 0, 0)>(vb), L##1 = tr_read<v_rd_off(D0, 0, 1)>(vb), L##2 = tr_read<v_rd_off(D0, 1, 0)>(vb), L##3 = tr_read<v_rd_off(D0, 1, 1)>(vb), \
;                          L##4 = tr_read<v_rd_off(D0, 2, 0)>(vb), L##5 = tr_read<v_rd_off(D0, 2, 1)>(vb), L##6 = tr_read<v_rd_off(D0, 3, 0)>(vb), L##7 = tr_read<v_rd_off(D0, 3, 1)>(vb)
; __device__ __forceinline__ void pv_four(f32x16 (&o)[2][4], int vb, bf16x8 pa0, bf16x8 pa1, bf16x8 pa2, bf16x8 pa3, bf16x8 pb0, bf16x8 pb1, bf16x8 pb2, bf16x8 pb3) {
;     ...
;   VRD(0, x); SBAR();
;   VRD(1, y); asm volatile("s_waitcnt lgkmcnt(8)" ::: "memory"); SBAR(); MMA(0, x); SBAR();
;   VRD(2, z); asm volatile("s_waitcnt lgkmcnt(8)" ::: "memory"); SBAR(); MMA(1, y); SBAR();
;   VRD(3, w); asm volatile("s_waitcnt lgkmcnt(8)" ::: "memory"); SBAR(); MMA(2, z); SBAR();
;   asm volatile("s_waitcnt lgkmcnt(0)" ::: "memory"); SBAR(); MMA(3, w);
;     ...
; }
; __device__ __forceinline__ void attn_unit2(const bf16* __restrict__ Qb, const bf16* __restrict__ Kh, const bf16* __restrict__ Vh, bf16* __restrict__ Ob,
;                                            int NT, int lim, int qrow0, const float* lut, char* lds, float* scr) {
;     ...
;         const char* ps = P0 + ((j - 1) & 1) * 16384 + lane * 16;
;         const bf16x8 pa0 = *(const bf16x8*)(ps), pa1 = *(const bf16x8*)(ps + 1024), pa2 = *(const bf16x8*)(ps + 2048), pa3 = *(const bf16x8*)(ps + 3072);
;         const bf16x8 pb0 = *(const bf16x8*)(ps + 4096), pb1 = *(const bf16x8*)(ps + 4096 + 1024), pb2 = *(const bf16x8*)(ps + 4096 + 2048), pb3 = *(const bf16x8*)(ps + 4096 + 3072);
;         const int vb = vrb + ((j - 1) & 1) * 32768 + ch * 16384;
;         pv_four(o, vb, pa0, pa1, pa2, pa3, pb0, pb1, pb2, pb3);
;       }
;       asm volatile("s_waitcnt vmcnt(0)" ::: "memory");
;       __syncthreads();
.LBB0_436:
	v_lshl_add_u32 v201, s14, 14, v175
	ds_read_b128 v[178:181], v201
	ds_read_b128 v[182:185], v201 offset:1024
	ds_read_b128 v[186:189], v201 offset:2048
	ds_read_b128 v[190:193], v201 offset:3072
	ds_read_b128 v[194:197], v201 offset:4096
	ds_read_b128 v[208:211], v201 offset:5120
	ds_read_b128 v[212:215], v201 offset:6144
	ds_read_b128 v[216:219], v201 offset:7168
	v_lshl_add_u32 v207, s14, 15, v176
	ds_read_b64_tr_b16 v[220:221], v207 offset:0
	ds_read_b64_tr_b16 v[222:223], v207 offset:0x800
	ds_read_b64_tr_b16 v[224:225], v207 offset:0x1000
	ds_read_b64_tr_b16 v[226:227], v207 offset:0x1800
	ds_read_b64_tr_b16 v[228:229], v207 offset:0x2000
	ds_read_b64_tr_b16 v[230:231], v207 offset:0x2800
	ds_read_b64_tr_b16 v[232:233], v207 offset:0x3000
	ds_read_b64_tr_b16 v[234:235], v207 offset:0x3800
	ds_read_b64_tr_b16 v[236:237], v207 offset:0x200
	ds_read_b64_tr_b16 v[238:239], v207 offset:0xa00
	ds_read_b64_tr_b16 v[240:241], v207 offset:0x1200
	ds_read_b64_tr_b16 v[242:243], v207 offset:0x1a00
	ds_read_b64_tr_b16 v[244:245], v207 offset:0x2200
	ds_read_b64_tr_b16 v[246:247], v207 offset:0x2a00
	ds_read_b64_tr_b16 v[248:249], v207 offset:0x3200
	ds_read_b64_tr_b16 v[250:251], v207 offset:0x3a00
	s_add_i32 m0, s23, 0xc000
	s_nop 0
	global_load_lds_dwordx4 v[156:157], off
	s_add_i32 m0, s23, 0xc400
	s_nop 0
	global_load_lds_dwordx4 v[158:159], off
	s_add_i32 m0, s23, 0xc800
	s_nop 0
	global_load_lds_dwordx4 v[164:165], off
	s_add_i32 m0, s23, 0xcc00
	s_nop 0
	global_load_lds_dwordx4 v[252:253], off
	s_waitcnt lgkmcnt(8)
	s_waitcnt lgkmcnt(0)
	v_mfma_f32_32x32x16_bf16 v[116:131], v[178:181], v[220:223], v[116:131]
	v_mfma_f32_32x32x16_bf16 v[52:67], v[194:197], v[220:223], v[52:67]
	v_mfma_f32_32x32x16_bf16 v[116:131], v[182:185], v[224:227], v[116:131]
	v_mfma_f32_32x32x16_bf16 v[52:67], v[208:211], v[224:227], v[52:67]
	v_mfma_f32_32x32x16_bf16 v[116:131], v[186:189], v[228:231], v[116:131]
	v_mfma_f32_32x32x16_bf16 v[52:67], v[212:215], v[228:231], v[52:67]
	v_mfma_f32_32x32x16_bf16 v[116:131], v[190:193], v[232:235], v[116:131]
	v_mfma_f32_32x32x16_bf16 v[52:67], v[216:219], v[232:235], v[52:67]
	ds_read_b64_tr_b16 v[220:221], v207 offset:0x400
	ds_read_b64_tr_b16 v[222:223], v207 offset:0xc00
	ds_read_b64_tr_b16 v[224:225], v207 offset:0x1400
	ds_read_b64_tr_b16 v[226:227], v207 offset:0x1c00
	ds_read_b64_tr_b16 v[228:229], v207 offset:0x2400
	ds_read_b64_tr_b16 v[230:231], v207 offset:0x2c00
	ds_read_b64_tr_b16 v[232:233], v207 offset:0x3400
	ds_read_b64_tr_b16 v[234:235], v207 offset:0x3c00
	s_waitcnt lgkmcnt(8)
	v_mfma_f32_32x32x16_bf16 v[100:115], v[178:181], v[236:239], v[100:115]
	v_mfma_f32_32x32x16_bf16 v[36:51], v[194:197], v[236:239], v[36:51]
	v_mfma_f32_32x32x16_bf16 v[100:115], v[182:185], v[240:243], v[100:115]
	v_mfma_f32_32x32x16_bf16 v[36:51], v[208:211], v[240:243], v[36:51]
	v_mfma_f32_32x32x16_bf16 v[100:115], v[186:189], v[244:247], v[100:115]
	s_nop 0
	v_mfma_f32_32x32x16_bf16 v[36:51], v[212:215], v[244:247], v[36:51]
	v_mfma_f32_32x32x16_bf16 v[100:115], v[190:193], v[248:251], v[100:115]
	v_mfma_f32_32x32x16_bf16 v[36:51], v[216:219], v[248:251], v[36:51]
	ds_read_b64_tr_b16 v[236:237], v207 offset:0x600
	ds_read_b64_tr_b16 v[238:239], v207 offset:0xe00
	ds_read_b64_tr_b16 v[240:241], v207 offset:0x1600
	ds_read_b64_tr_b16 v[242:243], v207 offset:0x1e00
	ds_read_b64_tr_b16 v[244:245], v207 offset:0x2600
	ds_read_b64_tr_b16 v[246:247], v207 offset:0x2e00
	ds_read_b64_tr_b16 v[248:249], v207 offset:0x3600
	ds_read_b64_tr_b16 v[250:251], v207 offset:0x3e00
	s_waitcnt lgkmcnt(8)
	v_mfma_f32_32x32x16_bf16 v[84:99], v[178:181], v[220:223], v[84:99]
	v_mfma_f32_32x32x16_bf16 v[20:35], v[194:197], v[220:223], v[20:35]
	v_mfma_f32_32x32x16_bf16 v[84:99], v[182:185], v[224:227], v[84:99]
	v_mfma_f32_32x32x16_bf16 v[20:35], v[208:211], v[224:227], v[20:35]
	s_nop 0
	v_mfma_f32_32x32x16_bf16 v[84:99], v[186:189], v[228:231], v[84:99]
	v_mfma_f32_32x32x16_bf16 v[20:35], v[212:215], v[228:231], v[20:35]
	v_mfma_f32_32x32x16_bf16 v[84:99], v[190:193], v[232:235], v[84:99]
	v_mfma_f32_32x32x16_bf16 v[20:35], v[216:219], v[232:235], v[20:35]
	s_waitcnt lgkmcnt(0)
	v_mfma_f32_32x32x16_bf16 v[68:83], v[178:181], v[236:239], v[68:83]
	s_add_i32 s9, s9, 0x8000
	s_waitcnt vmcnt(0)
	s_add_u32 s36, s36, 0x40000
	s_addc_u32 s37, s37, 0
	s_add_i32 s14, s10, 1
	s_addk_i32 s7, 0x4000
	s_cmp_eq_u32 s8, s36
	v_mfma_f32_32x32x16_bf16 v[4:19], v[194:197], v[236:239], v[4:19]
	s_waitcnt vmcnt(0)
	s_barrier
	v_mfma_f32_32x32x16_bf16 v[68:83], v[182:185], v[240:243], v[68:83]
	v_mfma_f32_32x32x16_bf16 v[4:19], v[208:211], v[240:243], v[4:19]
	v_mfma_f32_32x32x16_bf16 v[68:83], v[186:189], v[244:247], v[68:83]
	v_mfma_f32_32x32x16_bf16 v[4:19], v[212:215], v[244:247], v[4:19]
	v_mfma_f32_32x32x16_bf16 v[68:83], v[190:193], v[248:251], v[68:83]
	v_mfma_f32_32x32x16_bf16 v[4:19], v[216:219], v[248:251], v[4:19]
	s_cbranch_scc1 .LBB0_439
	s_mov_b32 s10, s14
	s_cmp_lt_u32 s10, s5
	s_cselect_b64 s[38:39], -1, 0
	s_cmp_ge_u32 s10, s5
	s_cbranch_scc0 .LBB0_432
	s_branch .LBB0_433

; template <class Epi, class Sched, bool ALIGN_EPI = false, bool SP2 = false>
; __device__ __forceinline__ void gemm_phase(PG8_LAS unsigned char* lds, const Gemm g, const Sched& S, const Epi& E) {
;     ...
;         const bool has_next = S.next(ui + 1, nxt);
;         const char* nA = has_next ? PG8_UA(nxt) : cA; const char* nB = has_next ? PG8_UB(nxt) : cB;
;     ...
; #pragma unroll
;         for (int a = 0; a < 2; ++a)
; #pragma unroll
;             for (int b = 0; b < 2; ++b)
; #pragma unroll
;                 for (int m = 0; m < 4; ++m)
; #pragma unroll
;                     for (int n = 0; n < 2; ++n) acc[a][b][m][n] = (f32x4){0.f, 0.f, 0.f, 0.f};
;         cur = nxt; cA = nA; cB = nB; ++ui;
.LBB0_597:
	s_ashr_i32 s49, s48, 31
	s_lshl_b64 s[4:5], s[48:49], 20
	s_add_u32 s50, s67, s4
	s_addc_u32 s51, s77, s5
	s_and_b64 s[4:5], s[40:41], exec
	s_cselect_b32 s4, s51, s57
	s_cselect_b32 s5, s50, s56
	s_ashr_i32 s47, s46, 31
	s_lshl_b64 s[6:7], s[46:47], 20
	s_add_u32 s52, s12, s6
	s_addc_u32 s53, s13, s7
	s_and_b64 s[6:7], s[40:41], exec
	s_cselect_b32 s6, s53, s59
	s_cselect_b32 s7, s52, s58
	s_add_u32 s56, s56, 0x80080
	s_addc_u32 s57, s57, 0
	s_add_u32 s19, s58, 0x100
	v_mov_b32_e32 v4, 0
	s_addc_u32 s37, s59, 0
	s_mov_b32 s47, -2
	s_waitcnt lgkmcnt(0)
	v_mov_b32_e32 v5, v4
	v_mov_b32_e32 v6, v4
	v_mov_b32_e32 v7, v4
	v_mov_b32_e32 v8, v4
	v_mov_b32_e32 v9, v4
	v_mov_b32_e32 v10, v4
	v_mov_b32_e32 v11, v4
	v_mov_b32_e32 v20, v4
	v_mov_b32_e32 v21, v4
	v_mov_b32_e32 v22, v4
	v_mov_b32_e32 v23, v4
	v_mov_b32_e32 v24, v4
	v_mov_b32_e32 v25, v4
	v_mov_b32_e32 v26, v4
	v_mov_b32_e32 v27, v4
	v_mov_b32_e32 v36, v4
	v_mov_b32_e32 v37, v4
	v_mov_b32_e32 v38, v4
	v_mov_b32_e32 v39, v4
	v_mov_b32_e32 v40, v4
	v_mov_b32_e32 v41, v4
	v_mov_b32_e32 v42, v4
	v_mov_b32_e32 v43, v4
	v_mov_b32_e32 v52, v4
	v_mov_b32_e32 v53, v4
	v_mov_b32_e32 v54, v4
	v_mov_b32_e32 v55, v4
	v_mov_b32_e32 v56, v4
	v_mov_b32_e32 v57, v4
	v_mov_b32_e32 v58, v4
	v_mov_b32_e32 v59, v4
	v_mov_b32_e32 v12, v4
	v_mov_b32_e32 v13, v4
	v_mov_b32_e32 v14, v4
	v_mov_b32_e32 v15, v4
	v_mov_b32_e32 v16, v4
	v_mov_b32_e32 v17, v4
	v_mov_b32_e32 v18, v4
	v_mov_b32_e32 v19, v4
	v_mov_b32_e32 v28, v4
	v_mov_b32_e32 v29, v4
	v_mov_b32_e32 v30, v4
	v_mov_b32_e32 v31, v4
	v_mov_b32_e32 v32, v4
	v_mov_b32_e32 v33, v4
	v_mov_b32_e32 v34, v4
	v_mov_b32_e32 v35, v4
	v_mov_b32_e32 v44, v4
	v_mov_b32_e32 v45, v4
	v_mov_b32_e32 v46, v4
	v_mov_b32_e32 v47, v4
	v_mov_b32_e32 v48, v4
	v_mov_b32_e32 v49, v4
	v_mov_b32_e32 v50, v4
	v_mov_b32_e32 v51, v4
	v_mov_b32_e32 v60, v4
	v_mov_b32_e32 v61, v4
	v_mov_b32_e32 v62, v4
	v_mov_b32_e32 v63, v4
	v_mov_b32_e32 v64, v4
	v_mov_b32_e32 v65, v4
	v_mov_b32_e32 v66, v4
	v_mov_b32_e32 v67, v4
	v_mov_b32_e32 v68, v4
	v_mov_b32_e32 v69, v4
	v_mov_b32_e32 v70, v4
	v_mov_b32_e32 v71, v4
	v_mov_b32_e32 v72, v4
	v_mov_b32_e32 v73, v4
	v_mov_b32_e32 v74, v4
	v_mov_b32_e32 v75, v4
	v_mov_b32_e32 v84, v4
	v_mov_b32_e32 v85, v4
	v_mov_b32_e32 v86, v4
	v_mov_b32_e32 v87, v4
	v_mov_b32_e32 v88, v4
	v_mov_b32_e32 v89, v4
	v_mov_b32_e32 v90, v4
	v_mov_b32_e32 v91, v4
	v_mov_b32_e32 v100, v4
	v_mov_b32_e32 v101, v4
	v_mov_b32_e32 v102, v4
	v_mov_b32_e32 v103, v4
	v_mov_b32_e32 v104, v4
	v_mov_b32_e32 v105, v4
	v_mov_b32_e32 v106, v4
	v_mov_b32_e32 v107, v4
	v_mov_b32_e32 v116, v4
	v_mov_b32_e32 v117, v4
	v_mov_b32_e32 v118, v4
	v_mov_b32_e32 v119, v4
	v_mov_b32_e32 v120, v4
	v_mov_b32_e32 v121, v4
	v_mov_b32_e32 v122, v4
	v_mov_b32_e32 v123, v4
	v_mov_b32_e32 v76, v4
	v_mov_b32_e32 v77, v4
	v_mov_b32_e32 v78, v4
	v_mov_b32_e32 v79, v4
	v_mov_b32_e32 v80, v4
	v_mov_b32_e32 v81, v4
	v_mov_b32_e32 v82, v4
	v_mov_b32_e32 v83, v4
	v_mov_b32_e32 v92, v4
	v_mov_b32_e32 v93, v4
	v_mov_b32_e32 v94, v4
	v_mov_b32_e32 v95, v4
	v_mov_b32_e32 v96, v4
	v_mov_b32_e32 v97, v4
	v_mov_b32_e32 v98, v4
	v_mov_b32_e32 v99, v4
	v_mov_b32_e32 v108, v4
	v_mov_b32_e32 v109, v4
	v_mov_b32_e32 v110, v4
	v_mov_b32_e32 v111, v4
	v_mov_b32_e32 v112, v4
	v_mov_b32_e32 v113, v4
	v_mov_b32_e32 v114, v4
	v_mov_b32_e32 v115, v4
	v_mov_b32_e32 v124, v4
	v_mov_b32_e32 v125, v4
	v_mov_b32_e32 v126, v4
	v_mov_b32_e32 v127, v4
	v_mov_b32_e32 v128, v4
	v_mov_b32_e32 v129, v4
	v_mov_b32_e32 v130, v4
	v_mov_b32_e32 v131, v4
	v_readfirstlane_b32 s98, v0
	s_nop 3
	s_lshr_b32 s98, s98, 6
	s_cmp_ge_u32 s98, 4
	s_cbranch_scc0 .Lprio_g1
	s_setprio 1

; #define PG8_STAGE(bufoff, gbase, voff) do { _Pragma("unroll") for (int _i = 0; _i < 2; ++_i) \
;         __builtin_amdgcn_global_load_lds((const unsigned*)((const char*)(gbase) + (voff)[_i]), (PG8_LAS unsigned*)(lds + (bufoff) + ldsw + _i * 8192), 16, 0, 0); } while (0)
; #define PG8_LDA(dst, b, h) do { _Pragma("unroll") for (int m = 0; m < 4; ++m) _Pragma("unroll") for (int k = 0; k < 2; ++k) dst[m][k] = *(const PG8_LAS bf16x8*)(lds + PG8_SA(b, h) + aoff + m * 2048 + k * 1024); } while (0)
; #define PG8_LDB(dst, b, h) do { _Pragma("unroll") for (int n = 0; n < 2; ++n) _Pragma("unroll") for (int k = 0; k < 2; ++k) dst[n][k] = *(const PG8_LAS bf16x8*)(lds + PG8_SB(b, h) + boff + n * 2048 + k * 1024); } while (0)
; #define PG8_MMA(ai, bj, At, Bt) do { __builtin_amdgcn_s_setprio(1); _Pragma("unroll") for (int m = 0; m < 4; ++m) _Pragma("unroll") for (int n = 0; n < 2; ++n) _Pragma("unroll") for (int k = 0; k < 2; ++k) \
;         acc[ai][bj][m][n] = __builtin_amdgcn_mfma_f32_16x16x32_bf16(Bt[n][k], At[m][k], acc[ai][bj][m][n], 0, 0, 0); __builtin_amdgcn_s_setprio(0); } while (0)
; #define PG8_WAIT_V(n) asm volatile("s_waitcnt vmcnt(" #n ")" ::: "memory")
; #define PG8_WAIT_L(n) asm volatile("s_waitcnt lgkmcnt(" #n ")" ::: "memory")
; #define PG8_BAR __builtin_amdgcn_s_barrier()
; #define PG8_SCHED __builtin_amdgcn_sched_barrier(0)
; template <class Epi, class Sched, bool ALIGN_EPI = false, bool SP2 = false>
; __device__ __forceinline__ void gemm_phase(PG8_LAS unsigned char* lds, const Gemm g, const Sched& S, const Epi& E) {
;     ...
;             PG8_LDB(B0, 0, 0); PG8_LDB(B1, 0, 1); PG8_SCHED; PG8_LDA(At, 0, 0); PG8_STAGE(PG8_SA(1, 1), a1 + hstepA, voffA);
;             PG8_WAIT_V(8); PG8_WAIT_L(0); PG8_BAR; PG8_MMA(0, 0, At, B0); PG8_MMA(0, 1, At, B1); PG8_BAR; PG8_SCHED;
;             PG8_LDA(At, 0, 1); PG8_STAGE(PG8_SB(0, 0), b2, voffB); PG8_STAGE(PG8_SB(0, 1), b2 + hstepB, voffB); PG8_STAGE(PG8_SA(0, 0), a2, voffA);
;             PG8_WAIT_V(8); PG8_WAIT_L(0); PG8_BAR; PG8_MMA(1, 0, At, B0); PG8_MMA(1, 1, At, B1); PG8_BAR; PG8_SCHED;
;             PG8_LDB(B0, 1, 0); PG8_LDB(B1, 1, 1); PG8_SCHED; PG8_LDA(At, 1, 0); PG8_STAGE(PG8_SA(0, 1), a2 + hstepA, voffA);
;             PG8_WAIT_V(8); PG8_WAIT_L(0); PG8_BAR; PG8_MMA(0, 0, At, B0); PG8_MMA(0, 1, At, B1); PG8_BAR; PG8_SCHED;
.LBB0_598:
	s_add_u32 s8, s56, 0xfff80080
	s_addc_u32 s9, s57, -1
	s_add_i32 s14, 0, 0x10000
	s_cmp_eq_u32 s47, 28
	s_cselect_b32 s63, s4, s9
	s_cselect_b32 s62, s5, s8
	v_add_u32_e32 v153, s14, v147
	s_cselect_b32 s59, s6, s37
	s_cselect_b32 s58, s7, s19
	s_add_i32 s15, 0, 0x14000
	ds_read_b128 v[142:145], v153
	ds_read_b128 v[172:175], v153 offset:1024
	ds_read_b128 v[176:179], v153 offset:2048
	ds_read_b128 v[180:183], v153 offset:3072
	v_add_u32_e32 v153, s15, v147
	ds_read_b128 v[184:187], v153
	ds_read_b128 v[188:191], v153 offset:1024
	ds_read_b128 v[192:195], v153 offset:2048
	ds_read_b128 v[208:211], v153 offset:3072
	v_lshl_add_u64 v[154:155], s[56:57], 0, v[138:139]
	s_add_i32 m0, s79, 0xc000
	ds_read_b128 v[212:215], v151
	ds_read_b128 v[216:219], v151 offset:1024
	ds_read_b128 v[220:223], v151 offset:2048
	ds_read_b128 v[224:227], v151 offset:3072
	ds_read_b128 v[228:231], v151 offset:4096
	ds_read_b128 v[232:235], v151 offset:5120
	ds_read_b128 v[236:239], v151 offset:6144
	ds_read_b128 v[240:243], v151 offset:7168
	global_load_lds_dwordx4 v[154:155], off
	v_lshl_add_u64 v[154:155], s[56:57], 0, v[140:141]
	s_add_i32 m0, s79, 0xe000
	s_nop 0
	global_load_lds_dwordx4 v[154:155], off
	s_waitcnt vmcnt(8)
	s_waitcnt lgkmcnt(0)
	s_barrier
	s_waitcnt lgkmcnt(0)
	v_mfma_f32_16x16x32_bf16 v[128:131], v[142:145], v[212:215], v[128:131]
	v_mfma_f32_16x16x32_bf16 v[124:127], v[176:179], v[212:215], v[124:127]
	v_mfma_f32_16x16x32_bf16 v[112:115], v[142:145], v[220:223], v[112:115]
	v_mfma_f32_16x16x32_bf16 v[108:111], v[176:179], v[220:223], v[108:111]
	v_mfma_f32_16x16x32_bf16 v[96:99], v[142:145], v[228:231], v[96:99]
	v_mfma_f32_16x16x32_bf16 v[92:95], v[176:179], v[228:231], v[92:95]
	v_mfma_f32_16x16x32_bf16 v[80:83], v[142:145], v[236:239], v[80:83]
	v_mfma_f32_16x16x32_bf16 v[76:79], v[176:179], v[236:239], v[76:79]
	v_mfma_f32_16x16x32_bf16 v[128:131], v[172:175], v[216:219], v[128:131]
	v_mfma_f32_16x16x32_bf16 v[124:127], v[180:183], v[216:219], v[124:127]
	v_mfma_f32_16x16x32_bf16 v[112:115], v[172:175], v[224:227], v[112:115]
	v_mfma_f32_16x16x32_bf16 v[108:111], v[180:183], v[224:227], v[108:111]
	v_mfma_f32_16x16x32_bf16 v[96:99], v[172:175], v[232:235], v[96:99]
	v_mfma_f32_16x16x32_bf16 v[92:95], v[180:183], v[232:235], v[92:95]
	v_mfma_f32_16x16x32_bf16 v[80:83], v[172:175], v[240:243], v[80:83]
	v_mfma_f32_16x16x32_bf16 v[76:79], v[180:183], v[240:243], v[76:79]
	v_mfma_f32_16x16x32_bf16 v[120:123], v[184:187], v[212:215], v[120:123]
	v_mfma_f32_16x16x32_bf16 v[116:119], v[192:195], v[212:215], v[116:119]
	v_mfma_f32_16x16x32_bf16 v[104:107], v[184:187], v[220:223], v[104:107]
	v_mfma_f32_16x16x32_bf16 v[100:103], v[192:195], v[220:223], v[100:103]
	v_mfma_f32_16x16x32_bf16 v[88:91], v[184:187], v[228:231], v[88:91]
	v_mfma_f32_16x16x32_bf16 v[84:87], v[192:195], v[228:231], v[84:87]
	v_mfma_f32_16x16x32_bf16 v[72:75], v[184:187], v[236:239], v[72:75]
	v_mfma_f32_16x16x32_bf16 v[68:71], v[192:195], v[236:239], v[68:71]
	v_mfma_f32_16x16x32_bf16 v[120:123], v[188:191], v[216:219], v[120:123]
	v_mfma_f32_16x16x32_bf16 v[116:119], v[208:211], v[216:219], v[116:119]
	v_mfma_f32_16x16x32_bf16 v[104:107], v[188:191], v[224:227], v[104:107]
	v_mfma_f32_16x16x32_bf16 v[100:103], v[208:211], v[224:227], v[100:103]
	v_mfma_f32_16x16x32_bf16 v[88:91], v[188:191], v[232:235], v[88:91]
	v_mfma_f32_16x16x32_bf16 v[84:87], v[208:211], v[232:235], v[84:87]
	v_mfma_f32_16x16x32_bf16 v[72:75], v[188:191], v[240:243], v[72:75]
	v_mfma_f32_16x16x32_bf16 v[68:71], v[208:211], v[240:243], v[68:71]
	s_barrier
	s_add_i32 s8, s14, s78
	v_lshl_add_u64 v[154:155], s[58:59], 0, v[2:3]
	s_mov_b32 m0, s8
	ds_read_b128 v[212:215], v151 offset:16384
	ds_read_b128 v[216:219], v151 offset:17408
	ds_read_b128 v[220:223], v151 offset:18432
	ds_read_b128 v[224:227], v151 offset:19456
	ds_read_b128 v[228:231], v151 offset:20480
	ds_read_b128 v[232:235], v151 offset:21504
	ds_read_b128 v[236:239], v151 offset:22528
	ds_read_b128 v[240:243], v151 offset:23552
	global_load_lds_dwordx4 v[154:155], off
	s_add_i32 m0, s8, 0x2000
	s_add_u32 s8, s58, 0x80000
	v_lshl_add_u64 v[156:157], s[58:59], 0, v[136:137]
	s_addc_u32 s9, s59, 0
	s_add_i32 s14, s15, s78
	global_load_lds_dwordx4 v[156:157], off
	v_lshl_add_u64 v[158:159], s[8:9], 0, v[2:3]
	s_mov_b32 m0, s14
	v_lshl_add_u64 v[164:165], s[62:63], 0, v[134:135]
	global_load_lds_dwordx4 v[158:159], off
	v_lshl_add_u64 v[158:159], s[8:9], 0, v[136:137]
	s_add_i32 m0, s14, 0x2000
	s_nop 0
	global_load_lds_dwordx4 v[158:159], off
	v_lshl_add_u64 v[158:159], s[62:63], 0, v[132:133]
	s_mov_b32 m0, s79
	s_nop 0
	global_load_lds_dwordx4 v[158:159], off
	s_mov_b32 m0, s80
	s_nop 0
	global_load_lds_dwordx4 v[164:165], off
	s_waitcnt vmcnt(8)
	s_waitcnt lgkmcnt(0)
	s_barrier
; #define PG8_STAGE(bufoff, gbase, voff) do { _Pragma("unroll") for (int _i = 0; _i < 2; ++_i) \
;         __builtin_amdgcn_global_load_lds((const unsigned*)((const char*)(gbase) + (voff)[_i]), (PG8_LAS unsigned*)(lds + (bufoff) + ldsw + _i * 8192), 16, 0, 0); } while (0)
; #define PG8_LDA(dst, b, h) do { _Pragma("unroll") for (int m = 0; m < 4; ++m) _Pragma("unroll") for (int k = 0; k < 2; ++k) dst[m][k] = *(const PG8_LAS bf16x8*)(lds + PG8_SA(b, h) + aoff + m * 2048 + k * 1024); } while (0)
; #define PG8_LDB(dst, b, h) do { _Pragma("unroll") for (int n = 0; n < 2; ++n) _Pragma("unroll") for (int k = 0; k < 2; ++k) dst[n][k] = *(const PG8_LAS bf16x8*)(lds + PG8_SB(b, h) + boff + n * 2048 + k * 1024); } while (0)
; #define PG8_MMA(ai, bj, At, Bt) do { __builtin_amdgcn_s_setprio(1); _Pragma("unroll") for (int m = 0; m < 4; ++m) _Pragma("unroll") for (int n = 0; n < 2; ++n) _Pragma("unroll") for (int k = 0; k < 2; ++k) \
;         acc[ai][bj][m][n] = __builtin_amdgcn_mfma_f32_16x16x32_bf16(Bt[n][k], At[m][k], acc[ai][bj][m][n], 0, 0, 0); __builtin_amdgcn_s_setprio(0); } while (0)
; #define PG8_WAIT_V(n) asm volatile("s_waitcnt vmcnt(" #n ")" ::: "memory")
; #define PG8_WAIT_L(n) asm volatile("s_waitcnt lgkmcnt(" #n ")" ::: "memory")
; #define PG8_BAR __builtin_amdgcn_s_barrier()
; #define PG8_SCHED __builtin_amdgcn_sched_barrier(0)
; template <class Epi, class Sched, bool ALIGN_EPI = false, bool SP2 = false>
; __device__ __forceinline__ void gemm_phase(PG8_LAS unsigned char* lds, const Gemm g, const Sched& S, const Epi& E) {
;     ...
;             PG8_WAIT_V(8); PG8_WAIT_L(0); PG8_BAR; PG8_MMA(1, 0, At, B0); PG8_MMA(1, 1, At, B1); PG8_BAR; PG8_SCHED;
;             PG8_LDB(B0, 1, 0); PG8_LDB(B1, 1, 1); PG8_SCHED; PG8_LDA(At, 1, 0); PG8_STAGE(PG8_SA(0, 1), a2 + hstepA, voffA);
;             PG8_WAIT_V(8); PG8_WAIT_L(0); PG8_BAR; PG8_MMA(0, 0, At, B0); PG8_MMA(0, 1, At, B1); PG8_BAR; PG8_SCHED;
	s_waitcnt lgkmcnt(0)
	v_mfma_f32_16x16x32_bf16 v[64:67], v[142:145], v[212:215], v[64:67]
	v_mfma_f32_16x16x32_bf16 v[60:63], v[176:179], v[212:215], v[60:63]
	v_mfma_f32_16x16x32_bf16 v[48:51], v[142:145], v[220:223], v[48:51]
	v_mfma_f32_16x16x32_bf16 v[44:47], v[176:179], v[220:223], v[44:47]
	v_mfma_f32_16x16x32_bf16 v[32:35], v[142:145], v[228:231], v[32:35]
	v_mfma_f32_16x16x32_bf16 v[28:31], v[176:179], v[228:231], v[28:31]
	v_mfma_f32_16x16x32_bf16 v[16:19], v[142:145], v[236:239], v[16:19]
	v_mfma_f32_16x16x32_bf16 v[12:15], v[176:179], v[236:239], v[12:15]
	v_mfma_f32_16x16x32_bf16 v[64:67], v[172:175], v[216:219], v[64:67]
	v_mfma_f32_16x16x32_bf16 v[60:63], v[180:183], v[216:219], v[60:63]
	v_mfma_f32_16x16x32_bf16 v[48:51], v[172:175], v[224:227], v[48:51]
	v_mfma_f32_16x16x32_bf16 v[44:47], v[180:183], v[224:227], v[44:47]
	v_mfma_f32_16x16x32_bf16 v[32:35], v[172:175], v[232:235], v[32:35]
	v_mfma_f32_16x16x32_bf16 v[28:31], v[180:183], v[232:235], v[28:31]
	v_mfma_f32_16x16x32_bf16 v[16:19], v[172:175], v[240:243], v[16:19]
	v_mfma_f32_16x16x32_bf16 v[12:15], v[180:183], v[240:243], v[12:15]
	v_mfma_f32_16x16x32_bf16 v[56:59], v[184:187], v[212:215], v[56:59]
	v_mfma_f32_16x16x32_bf16 v[52:55], v[192:195], v[212:215], v[52:55]
	v_mfma_f32_16x16x32_bf16 v[40:43], v[184:187], v[220:223], v[40:43]
	v_mfma_f32_16x16x32_bf16 v[36:39], v[192:195], v[220:223], v[36:39]
	v_mfma_f32_16x16x32_bf16 v[24:27], v[184:187], v[228:231], v[24:27]
	v_mfma_f32_16x16x32_bf16 v[20:23], v[192:195], v[228:231], v[20:23]
	v_mfma_f32_16x16x32_bf16 v[8:11], v[184:187], v[236:239], v[8:11]
	v_mfma_f32_16x16x32_bf16 v[4:7], v[192:195], v[236:239], v[4:7]
	v_mfma_f32_16x16x32_bf16 v[56:59], v[188:191], v[216:219], v[56:59]
	v_mfma_f32_16x16x32_bf16 v[52:55], v[208:211], v[216:219], v[52:55]
	v_mfma_f32_16x16x32_bf16 v[40:43], v[188:191], v[224:227], v[40:43]
	v_mfma_f32_16x16x32_bf16 v[36:39], v[208:211], v[224:227], v[36:39]
	v_mfma_f32_16x16x32_bf16 v[24:27], v[188:191], v[232:235], v[24:27]
	v_mfma_f32_16x16x32_bf16 v[20:23], v[208:211], v[232:235], v[20:23]
	v_mfma_f32_16x16x32_bf16 v[8:11], v[188:191], v[240:243], v[8:11]
	v_mfma_f32_16x16x32_bf16 v[4:7], v[208:211], v[240:243], v[4:7]
	s_barrier
	s_add_i32 s14, 0, 0x18000
	v_add_u32_e32 v153, s14, v147
	s_add_i32 s15, 0, 0x1c000
	ds_read_b128 v[142:145], v153
	ds_read_b128 v[172:175], v153 offset:1024
	ds_read_b128 v[176:179], v153 offset:2048
	ds_read_b128 v[180:183], v153 offset:3072
	v_add_u32_e32 v153, s15, v147
	ds_read_b128 v[184:187], v153
	ds_read_b128 v[188:191], v153 offset:1024
	ds_read_b128 v[192:195], v153 offset:2048
	ds_read_b128 v[208:211], v153 offset:3072
	s_add_u32 s8, s62, 0x80000
	s_addc_u32 s9, s63, 0
	s_mov_b32 m0, s81
	v_lshl_add_u64 v[196:197], s[8:9], 0, v[132:133]
	ds_read_b128 v[212:215], v151 offset:32768
	ds_read_b128 v[216:219], v151 offset:33792
	ds_read_b128 v[220:223], v151 offset:34816
	ds_read_b128 v[224:227], v151 offset:35840
	ds_read_b128 v[228:231], v151 offset:36864
	ds_read_b128 v[232:235], v151 offset:37888
	ds_read_b128 v[236:239], v151 offset:38912
	ds_read_b128 v[240:243], v151 offset:39936
	global_load_lds_dwordx4 v[196:197], off
	v_lshl_add_u64 v[196:197], s[8:9], 0, v[134:135]
	s_mov_b32 m0, s82
	s_nop 0
	global_load_lds_dwordx4 v[196:197], off
	s_waitcnt vmcnt(8)
	s_waitcnt lgkmcnt(0)
	s_barrier
	s_waitcnt lgkmcnt(0)
	v_mfma_f32_16x16x32_bf16 v[128:131], v[142:145], v[212:215], v[128:131]
	v_mfma_f32_16x16x32_bf16 v[124:127], v[176:179], v[212:215], v[124:127]
	v_mfma_f32_16x16x32_bf16 v[112:115], v[142:145], v[220:223], v[112:115]
	v_mfma_f32_16x16x32_bf16 v[108:111], v[176:179], v[220:223], v[108:111]
	v_mfma_f32_16x16x32_bf16 v[96:99], v[142:145], v[228:231], v[96:99]
	v_mfma_f32_16x16x32_bf16 v[92:95], v[176:179], v[228:231], v[92:95]
	v_mfma_f32_16x16x32_bf16 v[80:83], v[142:145], v[236:239], v[80:83]
	v_mfma_f32_16x16x32_bf16 v[76:79], v[176:179], v[236:239], v[76:79]
	v_mfma_f32_16x16x32_bf16 v[128:131], v[172:175], v[216:219], v[128:131]
	v_mfma_f32_16x16x32_bf16 v[124:127], v[180:183], v[216:219], v[124:127]
	v_mfma_f32_16x16x32_bf16 v[112:115], v[172:175], v[224:227], v[112:115]
	v_mfma_f32_16x16x32_bf16 v[108:111], v[180:183], v[224:227], v[108:111]
	v_mfma_f32_16x16x32_bf16 v[96:99], v[172:175], v[232:235], v[96:99]
	v_mfma_f32_16x16x32_bf16 v[92:95], v[180:183], v[232:235], v[92:95]
	v_mfma_f32_16x16x32_bf16 v[80:83], v[172:175], v[240:243], v[80:83]
	v_mfma_f32_16x16x32_bf16 v[76:79], v[180:183], v[240:243], v[76:79]
	v_mfma_f32_16x16x32_bf16 v[120:123], v[184:187], v[212:215], v[120:123]
	v_mfma_f32_16x16x32_bf16 v[116:119], v[192:195], v[212:215], v[116:119]
	v_mfma_f32_16x16x32_bf16 v[104:107], v[184:187], v[220:223], v[104:107]
	v_mfma_f32_16x16x32_bf16 v[100:103], v[192:195], v[220:223], v[100:103]
	v_mfma_f32_16x16x32_bf16 v[88:91], v[184:187], v[228:231], v[88:91]
	v_mfma_f32_16x16x32_bf16 v[84:87], v[192:195], v[228:231], v[84:87]
	v_mfma_f32_16x16x32_bf16 v[72:75], v[184:187], v[236:239], v[72:75]
	v_mfma_f32_16x16x32_bf16 v[68:71], v[192:195], v[236:239], v[68:71]
	v_mfma_f32_16x16x32_bf16 v[120:123], v[188:191], v[216:219], v[120:123]
	v_mfma_f32_16x16x32_bf16 v[116:119], v[208:211], v[216:219], v[116:119]
	v_mfma_f32_16x16x32_bf16 v[104:107], v[188:191], v[224:227], v[104:107]
	v_mfma_f32_16x16x32_bf16 v[100:103], v[208:211], v[224:227], v[100:103]
	v_mfma_f32_16x16x32_bf16 v[88:91], v[188:191], v[232:235], v[88:91]
	v_mfma_f32_16x16x32_bf16 v[84:87], v[208:211], v[232:235], v[84:87]
	v_mfma_f32_16x16x32_bf16 v[72:75], v[188:191], v[240:243], v[72:75]
	v_mfma_f32_16x16x32_bf16 v[68:71], v[208:211], v[240:243], v[68:71]
	s_barrier
; #define PG8_STAGE(bufoff, gbase, voff) do { _Pragma("unroll") for (int _i = 0; _i < 2; ++_i) \
;         __builtin_amdgcn_global_load_lds((const unsigned*)((const char*)(gbase) + (voff)[_i]), (PG8_LAS unsigned*)(lds + (bufoff) + ldsw + _i * 8192), 16, 0, 0); } while (0)
; #define PG8_LDA(dst, b, h) do { _Pragma("unroll") for (int m = 0; m < 4; ++m) _Pragma("unroll") for (int k = 0; k < 2; ++k) dst[m][k] = *(const PG8_LAS bf16x8*)(lds + PG8_SA(b, h) + aoff + m * 2048 + k * 1024); } while (0)
; #define PG8_WAIT_V(n) asm volatile("s_waitcnt vmcnt(" #n ")" ::: "memory")
; template <class Epi, class Sched, bool ALIGN_EPI = false, bool SP2 = false>
; __device__ __forceinline__ void gemm_phase(PG8_LAS unsigned char* lds, const Gemm g, const Sched& S, const Epi& E) {
;     ...
;             PG8_LDA(At, 1, 1); PG8_STAGE(PG8_SB(1, 0), b3, voffB); PG8_STAGE(PG8_SB(1, 1), b3 + hstepB, voffB); PG8_STAGE(PG8_SA(1, 0), a3, voffA);
;             PG8_WAIT_V(8); PG8_WAIT_L(0); PG8_BAR; PG8_MMA(1, 0, At, B0); PG8_MMA(1, 1, At, B1); PG8_BAR; PG8_SCHED;
;             } else {
;             PG8_LDB(B0, 0, 0); PG8_SCHED; PG8_LDA(At, 0, 0); PG8_STAGE(PG8_SA(1, 1), a1 + hstepA, voffA);
;             PG8_WAIT_L(8); PG8_BAR; PG8_WAIT_L(0); PG8_MMA(0, 0, At, B0); PG8_BAR; PG8_SCHED;
;             PG8_LDB(B1, 0, 1); PG8_STAGE(PG8_SB(0, 0), b2, voffB);
;             PG8_BAR; PG8_WAIT_L(0); PG8_MMA(0, 1, At, B1); PG8_BAR;
;             PG8_LDA(At, 0, 1); PG8_STAGE(PG8_SA(0, 0), a2, voffA);
;             PG8_BAR; PG8_WAIT_L(0); PG8_MMA(1, 0, At, B0); PG8_BAR; PG8_SCHED;
;             PG8_STAGE(PG8_SB(0, 1), b2 + hstepB, voffB);
;             PG8_WAIT_V(6); PG8_BAR; PG8_MMA(1, 1, At, B1); PG8_BAR;
;             PG8_LDB(B0, 1, 0); PG8_SCHED; PG8_LDA(At, 1, 0); PG8_STAGE(PG8_SA(0, 1), a2 + hstepA, voffA);
;             PG8_WAIT_L(8); PG8_BAR; PG8_WAIT_L(0); PG8_MMA(0, 0, At, B0); PG8_BAR; PG8_SCHED;
;             PG8_LDB(B1, 1, 1); PG8_STAGE(PG8_SB(1, 0), b3, voffB);
;             PG8_BAR; PG8_WAIT_L(0); PG8_MMA(0, 1, At, B1); PG8_BAR;
;             PG8_LDA(At, 1, 1); PG8_STAGE(PG8_SA(1, 0), a3, voffA);
;             PG8_BAR; PG8_WAIT_L(0); PG8_MMA(1, 0, At, B0); PG8_BAR; PG8_SCHED;
;             PG8_STAGE(PG8_SB(1, 1), b3 + hstepB, voffB);
;             PG8_WAIT_V(6); PG8_BAR; PG8_MMA(1, 1, At, B1); PG8_BAR;
;             }
;         }
;         if constexpr (ALIGN_EPI) { if (wr == 0) PG8_BAR; }
	s_add_i32 s8, s14, s78
	v_lshl_add_u64 v[154:155], v[154:155], 0, s[24:25]
	s_mov_b32 m0, s8
	ds_read_b128 v[212:215], v151 offset:49152
	ds_read_b128 v[216:219], v151 offset:50176
	ds_read_b128 v[220:223], v151 offset:51200
	ds_read_b128 v[224:227], v151 offset:52224
	ds_read_b128 v[228:231], v151 offset:53248
	ds_read_b128 v[232:235], v151 offset:54272
	ds_read_b128 v[236:239], v151 offset:55296
	ds_read_b128 v[240:243], v151 offset:56320
	global_load_lds_dwordx4 v[154:155], off
	s_add_i32 m0, s8, 0x2000
	s_add_u32 s8, s58, 0x80080
	v_lshl_add_u64 v[154:155], v[156:157], 0, s[24:25]
	s_addc_u32 s9, s59, 0
	s_add_i32 s14, s15, s78
	global_load_lds_dwordx4 v[154:155], off
	v_lshl_add_u64 v[154:155], s[8:9], 0, v[2:3]
	s_mov_b32 m0, s14
	s_nop 0
	global_load_lds_dwordx4 v[154:155], off
	v_lshl_add_u64 v[154:155], s[8:9], 0, v[136:137]
	s_add_i32 m0, s14, 0x2000
	s_nop 0
	global_load_lds_dwordx4 v[154:155], off
	v_lshl_add_u64 v[154:155], v[158:159], 0, s[24:25]
	s_mov_b32 m0, s83
	s_nop 0
	global_load_lds_dwordx4 v[154:155], off
	v_lshl_add_u64 v[154:155], v[164:165], 0, s[24:25]
	s_mov_b32 m0, s84
	s_nop 0
	global_load_lds_dwordx4 v[154:155], off
	s_waitcnt vmcnt(8)
	s_waitcnt lgkmcnt(0)
	s_barrier
	s_waitcnt lgkmcnt(0)
	v_mfma_f32_16x16x32_bf16 v[64:67], v[142:145], v[212:215], v[64:67]
	v_mfma_f32_16x16x32_bf16 v[60:63], v[176:179], v[212:215], v[60:63]
	v_mfma_f32_16x16x32_bf16 v[48:51], v[142:145], v[220:223], v[48:51]
	v_mfma_f32_16x16x32_bf16 v[44:47], v[176:179], v[220:223], v[44:47]
	v_mfma_f32_16x16x32_bf16 v[32:35], v[142:145], v[228:231], v[32:35]
	v_mfma_f32_16x16x32_bf16 v[28:31], v[176:179], v[228:231], v[28:31]
	v_mfma_f32_16x16x32_bf16 v[16:19], v[142:145], v[236:239], v[16:19]
	v_mfma_f32_16x16x32_bf16 v[12:15], v[176:179], v[236:239], v[12:15]
	v_mfma_f32_16x16x32_bf16 v[64:67], v[172:175], v[216:219], v[64:67]
	v_mfma_f32_16x16x32_bf16 v[60:63], v[180:183], v[216:219], v[60:63]
	v_mfma_f32_16x16x32_bf16 v[48:51], v[172:175], v[224:227], v[48:51]
	v_mfma_f32_16x16x32_bf16 v[44:47], v[180:183], v[224:227], v[44:47]
	v_mfma_f32_16x16x32_bf16 v[32:35], v[172:175], v[232:235], v[32:35]
	v_mfma_f32_16x16x32_bf16 v[28:31], v[180:183], v[232:235], v[28:31]
	v_mfma_f32_16x16x32_bf16 v[16:19], v[172:175], v[240:243], v[16:19]
	v_mfma_f32_16x16x32_bf16 v[12:15], v[180:183], v[240:243], v[12:15]
	v_mfma_f32_16x16x32_bf16 v[56:59], v[184:187], v[212:215], v[56:59]
	v_mfma_f32_16x16x32_bf16 v[52:55], v[192:195], v[212:215], v[52:55]
	v_mfma_f32_16x16x32_bf16 v[40:43], v[184:187], v[220:223], v[40:43]
	v_mfma_f32_16x16x32_bf16 v[36:39], v[192:195], v[220:223], v[36:39]
	v_mfma_f32_16x16x32_bf16 v[24:27], v[184:187], v[228:231], v[24:27]
	v_mfma_f32_16x16x32_bf16 v[20:23], v[192:195], v[228:231], v[20:23]
	v_mfma_f32_16x16x32_bf16 v[8:11], v[184:187], v[236:239], v[8:11]
	v_mfma_f32_16x16x32_bf16 v[4:7], v[192:195], v[236:239], v[4:7]
	v_mfma_f32_16x16x32_bf16 v[56:59], v[188:191], v[216:219], v[56:59]
	v_mfma_f32_16x16x32_bf16 v[52:55], v[208:211], v[216:219], v[52:55]
	v_mfma_f32_16x16x32_bf16 v[40:43], v[188:191], v[224:227], v[40:43]
	v_mfma_f32_16x16x32_bf16 v[36:39], v[208:211], v[224:227], v[36:39]
	v_mfma_f32_16x16x32_bf16 v[24:27], v[188:191], v[232:235], v[24:27]
	v_mfma_f32_16x16x32_bf16 v[20:23], v[208:211], v[232:235], v[20:23]
	v_mfma_f32_16x16x32_bf16 v[8:11], v[188:191], v[240:243], v[8:11]
	v_mfma_f32_16x16x32_bf16 v[4:7], v[208:211], v[240:243], v[4:7]
	s_barrier
	s_add_i32 s47, s47, 2
	s_add_u32 s56, s56, 0x100
	s_addc_u32 s57, s57, 0
	s_add_u32 s19, s19, 0x100
	s_addc_u32 s37, s37, 0
	s_cmp_gt_u32 s47, 29
	s_cbranch_scc0 .LBB0_598
	s_and_b64 vcc, exec, s[44:45]
	s_cbranch_vccz .LBB0_601
	s_barrier
; __device__ __forceinline__ u32x4 pack8(f32x4 a, f32x4 b) { u32x4 w; w.x = cvt_pk_bf16(a[0], a[1]); w.y = cvt_pk_bf16(a[2], a[3]); w.z = cvt_pk_bf16(b[0], b[1]); w.w = cvt_pk_bf16(b[2], b[3]); return w; }
;     __device__ __forceinline__ void operator()(const f32x4 (&acc)[2][2][4][2], const Unit& u, int wr, int wc, int fr, int fq, const float (&rsv)[2][4]) const {
;         const int row0 = u.pm * BM + wr * 64 + fr, col0 = u.pn * BM + wc * 32 + 8 * fq;
;         f32x4 cv[2][2];
; #pragma unroll
;         for (int bj = 0; bj < 2; ++bj)
; #pragma unroll
;             for (int n = 0; n < 2; ++n) cv[bj][n] = cs ? *(const f32x4*)(cs + col0 + bj * HALF + 4 * n) : (f32x4){1.f, 1.f, 1.f, 1.f};
; #pragma unroll
;         for (int ai = 0; ai < 2; ++ai)
; #pragma unroll
;             for (int m = 0; m < 4; ++m) { const int row = row0 + ai * HALF + m * 16; float ss = 0.f;
; #pragma unroll
;                 for (int bj = 0; bj < 2; ++bj) { bf16_t* xp = XB + (size_t)row * D + col0 + bj * HALF;
;                     f32x4 a, b; unpack8(*(const u32x4*)xp, a, b);
;                     a += acc[ai][bj][m][0] * cv[bj][0]; b += acc[ai][bj][m][1] * cv[bj][1];
;                     const u32x4 w = pack8(a, b); *(u32x4*)xp = w; unpack8(w, a, b);
;                     ss += (a[0] * a[0] + a[1] * a[1]) + (a[2] * a[2] + a[3] * a[3]) + (b[0] * b[0] + b[1] * b[1]) + (b[2] * b[2] + b[3] * b[3]); }
;                 ss += __shfl_xor(ss, 16); ss += __shfl_xor(ss, 32);
;                 if (fq == 0) red[(ai * HALF + wr * 64 + m * 16 + fr) * 4 + wc] = ss;
;                 asm volatile("" ::: "memory"); }
.LBB0_601:
	s_setprio 0
	s_lshl_b32 s19, s36, 8
	v_add_u32_e32 v144, s19, v146
	v_ashrrev_i32_e32 v145, 31, v144
	v_lshl_or_b32 v142, s18, 8, v148
	v_lshlrev_b64 v[154:155], 12, v[144:145]
	v_ashrrev_i32_e32 v143, 31, v142
	v_lshl_add_u64 v[154:155], s[0:1], 0, v[154:155]
	v_lshl_add_u64 v[154:155], v[142:143], 1, v[154:155]
	global_load_dwordx4 v[172:175], v[154:155], off
	s_waitcnt vmcnt(0)
	v_lshlrev_b32_e32 v156, 16, v172
	v_and_b32_e32 v157, 0xffff0000, v172
	v_lshlrev_b32_e32 v158, 16, v173
	v_and_b32_e32 v159, 0xffff0000, v173
	v_lshlrev_b32_e32 v164, 16, v174
	v_and_b32_e32 v165, 0xffff0000, v174
	v_lshlrev_b32_e32 v172, 16, v175
	v_and_b32_e32 v173, 0xffff0000, v175
	v_pk_add_f32 v[128:129], v[128:129], v[156:157]
	v_pk_add_f32 v[130:131], v[130:131], v[158:159]
	v_pk_add_f32 v[156:157], v[126:127], v[172:173]
	v_pk_add_f32 v[124:125], v[124:125], v[164:165]
	v_cvt_pk_bf16_f32 v126, v128, v129
	v_cvt_pk_bf16_f32 v127, v130, v131
	s_nop 0
	v_cvt_pk_bf16_f32 v128, v124, v125
	v_cvt_pk_bf16_f32 v129, v156, v157
	global_load_dwordx4 v[172:175], v[154:155], off offset:256
	v_lshlrev_b32_e32 v130, 16, v126
	global_store_dwordx4 v[154:155], v[126:129], off
	v_lshlrev_b32_e32 v131, 16, v127
	v_lshlrev_b32_e32 v153, 16, v128
	v_and_b32_e32 v126, 0xffff0000, v126
	v_and_b32_e32 v127, 0xffff0000, v127
	v_and_b32_e32 v128, 0xffff0000, v128
	v_mul_f32_e32 v126, v126, v126
	v_mul_f32_e32 v127, v127, v127
	v_lshlrev_b32_e32 v156, 16, v129
	v_and_b32_e32 v129, 0xffff0000, v129
	v_mul_f32_e32 v128, v128, v128
	v_fmac_f32_e32 v126, v130, v130
	v_fmac_f32_e32 v127, v131, v131
	v_mul_f32_e32 v129, v129, v129
	v_fmac_f32_e32 v128, v153, v153
	v_add_f32_e32 v126, v126, v127
	v_fmac_f32_e32 v129, v156, v156
	v_add_f32_e32 v126, v126, v128
	v_add_f32_e32 v153, v126, v129
	v_and_b32_e32 v125, 64, v204
	v_xor_b32_e32 v124, 16, v204
	v_add_u32_e32 v125, 64, v125
	v_cmp_lt_i32_e32 vcc, v124, v125
	s_waitcnt vmcnt(1)
	v_lshlrev_b32_e32 v126, 16, v172
	v_and_b32_e32 v127, 0xffff0000, v172
	v_lshlrev_b32_e32 v128, 16, v173
	v_and_b32_e32 v129, 0xffff0000, v173
	v_lshlrev_b32_e32 v130, 16, v174
	v_and_b32_e32 v131, 0xffff0000, v174
	v_lshlrev_b32_e32 v156, 16, v175
	v_and_b32_e32 v157, 0xffff0000, v175
	v_pk_add_f32 v[122:123], v[122:123], v[128:129]
	v_pk_add_f32 v[120:121], v[120:121], v[126:127]
	v_pk_add_f32 v[118:119], v[118:119], v[156:157]
	v_pk_add_f32 v[116:117], v[116:117], v[130:131]
	v_cvt_pk_bf16_f32 v120, v120, v121
	v_cvt_pk_bf16_f32 v121, v122, v123
	v_cndmask_b32_e32 v124, v204, v124, vcc
	v_cvt_pk_bf16_f32 v122, v116, v117
	v_cvt_pk_bf16_f32 v123, v118, v119
	v_and_b32_e32 v117, 0xffff0000, v120
	v_and_b32_e32 v119, 0xffff0000, v121
	v_lshlrev_b32_e32 v116, 16, v120
	v_lshlrev_b32_e32 v118, 16, v121
	v_and_b32_e32 v127, 0xffff0000, v122
	v_mul_f32_e32 v117, v117, v117
	v_mul_f32_e32 v119, v119, v119
	v_lshlrev_b32_e32 v126, 16, v122
	v_and_b32_e32 v129, 0xffff0000, v123
	v_mul_f32_e32 v127, v127, v127
	v_fmac_f32_e32 v117, v116, v116
	v_fmac_f32_e32 v119, v118, v118
	v_lshlrev_b32_e32 v128, 16, v123
	v_mul_f32_e32 v129, v129, v129
	v_fmac_f32_e32 v127, v126, v126
	v_add_f32_e32 v116, v117, v119
	v_fmac_f32_e32 v129, v128, v128
	v_add_f32_e32 v116, v116, v127
	v_add_f32_e32 v116, v116, v129
	v_lshlrev_b32_e32 v124, 2, v124
	v_add_f32_e32 v116, v153, v116
	ds_bpermute_b32 v117, v124, v116
	v_xor_b32_e32 v118, 32, v204
	v_cmp_lt_i32_e32 vcc, v118, v125
	global_store_dwordx4 v[154:155], v[120:123], off offset:256
	s_waitcnt lgkmcnt(0)
	v_add_f32_e32 v117, v116, v117
	v_cndmask_b32_e32 v118, v204, v118, vcc
	v_lshlrev_b32_e32 v116, 2, v118
	ds_bpermute_b32 v118, v116, v117
	s_and_saveexec_b64 s[36:37], s[38:39]
	s_cbranch_execz .LBB0_603
	s_waitcnt lgkmcnt(0)
	v_add_f32_e32 v117, v117, v118
	ds_write_b32 v150, v117

; template <class Epi, class Sched, bool ALIGN_EPI = false, bool SP2 = false>
; __device__ __forceinline__ void gemm_phase(PG8_LAS unsigned char* lds, const Gemm g, const Sched& S, const Epi& E) {
;     ...
; #pragma unroll
;         for (int a = 0; a < 2; ++a)
; #pragma unroll
;             for (int b = 0; b < 2; ++b)
; #pragma unroll
;                 for (int m = 0; m < 4; ++m)
; #pragma unroll
;                     for (int n = 0; n < 2; ++n) acc[a][b][m][n] = (f32x4){0.f, 0.f, 0.f, 0.f};
;         cur = nxt; cA = nA; cB = nB; ++ui;
.LBB0_1759:
	s_ashr_i32 s53, s52, 31
	s_lshl_b64 s[4:5], s[52:53], 18
	s_add_u32 s64, s18, s4
	s_addc_u32 s65, s19, s5
	s_and_b64 s[4:5], s[42:43], exec
	s_cselect_b32 s4, s65, s67
	s_cselect_b32 s5, s64, s66
	s_add_u32 s42, s62, 0x80080
	s_addc_u32 s43, s63, 0
	s_add_u32 s6, s66, 0x100
	v_mov_b32_e32 v4, 0
	s_addc_u32 s7, s67, 0
	s_mov_b32 s21, -2
	s_waitcnt lgkmcnt(0)
	v_mov_b32_e32 v5, v4
	v_mov_b32_e32 v6, v4
	v_mov_b32_e32 v7, v4
	v_mov_b32_e32 v8, v4
	v_mov_b32_e32 v9, v4
	v_mov_b32_e32 v10, v4
	v_mov_b32_e32 v11, v4
	v_mov_b32_e32 v20, v4
	v_mov_b32_e32 v21, v4
	v_mov_b32_e32 v22, v4
	v_mov_b32_e32 v23, v4
	v_mov_b32_e32 v24, v4
	v_mov_b32_e32 v25, v4
	v_mov_b32_e32 v26, v4
	v_mov_b32_e32 v27, v4
	v_mov_b32_e32 v36, v4
	v_mov_b32_e32 v37, v4
	v_mov_b32_e32 v38, v4
	v_mov_b32_e32 v39, v4
	v_mov_b32_e32 v40, v4
	v_mov_b32_e32 v41, v4
	v_mov_b32_e32 v42, v4
	v_mov_b32_e32 v43, v4
	v_mov_b32_e32 v52, v4
	v_mov_b32_e32 v53, v4
	v_mov_b32_e32 v54, v4
	v_mov_b32_e32 v55, v4
	v_mov_b32_e32 v56, v4
	v_mov_b32_e32 v57, v4
	v_mov_b32_e32 v58, v4
	v_mov_b32_e32 v59, v4
	v_mov_b32_e32 v12, v4
	v_mov_b32_e32 v13, v4
	v_mov_b32_e32 v14, v4
	v_mov_b32_e32 v15, v4
	v_mov_b32_e32 v16, v4
	v_mov_b32_e32 v17, v4
	v_mov_b32_e32 v18, v4
	v_mov_b32_e32 v19, v4
	v_mov_b32_e32 v28, v4
	v_mov_b32_e32 v29, v4
	v_mov_b32_e32 v30, v4
	v_mov_b32_e32 v31, v4
	v_mov_b32_e32 v32, v4
	v_mov_b32_e32 v33, v4
	v_mov_b32_e32 v34, v4
	v_mov_b32_e32 v35, v4
	v_mov_b32_e32 v44, v4
	v_mov_b32_e32 v45, v4
	v_mov_b32_e32 v46, v4
	v_mov_b32_e32 v47, v4
	v_mov_b32_e32 v48, v4
	v_mov_b32_e32 v49, v4
	v_mov_b32_e32 v50, v4
	v_mov_b32_e32 v51, v4
	v_mov_b32_e32 v60, v4
	v_mov_b32_e32 v61, v4
	v_mov_b32_e32 v62, v4
	v_mov_b32_e32 v63, v4
	v_mov_b32_e32 v64, v4
	v_mov_b32_e32 v65, v4
	v_mov_b32_e32 v66, v4
	v_mov_b32_e32 v67, v4
	v_mov_b32_e32 v68, v4
	v_mov_b32_e32 v69, v4
	v_mov_b32_e32 v70, v4
	v_mov_b32_e32 v71, v4
	v_mov_b32_e32 v72, v4
	v_mov_b32_e32 v73, v4
	v_mov_b32_e32 v74, v4
	v_mov_b32_e32 v75, v4
	v_mov_b32_e32 v100, v4
	v_mov_b32_e32 v101, v4
	v_mov_b32_e32 v102, v4
	v_mov_b32_e32 v103, v4
	v_mov_b32_e32 v104, v4
	v_mov_b32_e32 v105, v4
	v_mov_b32_e32 v106, v4
	v_mov_b32_e32 v107, v4
	v_mov_b32_e32 v116, v4
	v_mov_b32_e32 v117, v4
	v_mov_b32_e32 v118, v4
	v_mov_b32_e32 v119, v4
	v_mov_b32_e32 v120, v4
	v_mov_b32_e32 v121, v4
	v_mov_b32_e32 v122, v4
	v_mov_b32_e32 v123, v4
	v_mov_b32_e32 v132, v4
	v_mov_b32_e32 v133, v4
	v_mov_b32_e32 v134, v4
	v_mov_b32_e32 v135, v4
	v_mov_b32_e32 v136, v4
	v_mov_b32_e32 v137, v4
	v_mov_b32_e32 v138, v4
	v_mov_b32_e32 v139, v4
	v_mov_b32_e32 v92, v4
	v_mov_b32_e32 v93, v4
	v_mov_b32_e32 v94, v4
	v_mov_b32_e32 v95, v4
	v_mov_b32_e32 v96, v4
	v_mov_b32_e32 v97, v4
	v_mov_b32_e32 v98, v4
	v_mov_b32_e32 v99, v4
	v_mov_b32_e32 v108, v4
	v_mov_b32_e32 v109, v4
	v_mov_b32_e32 v110, v4
	v_mov_b32_e32 v111, v4
	v_mov_b32_e32 v112, v4
	v_mov_b32_e32 v113, v4
	v_mov_b32_e32 v114, v4
	v_mov_b32_e32 v115, v4
	v_mov_b32_e32 v124, v4
	v_mov_b32_e32 v125, v4
	v_mov_b32_e32 v126, v4
	v_mov_b32_e32 v127, v4
	v_mov_b32_e32 v128, v4
	v_mov_b32_e32 v129, v4
	v_mov_b32_e32 v130, v4
	v_mov_b32_e32 v131, v4
	v_mov_b32_e32 v140, v4
	v_mov_b32_e32 v141, v4
	v_mov_b32_e32 v142, v4
	v_mov_b32_e32 v143, v4
	v_mov_b32_e32 v144, v4
	v_mov_b32_e32 v145, v4
	v_mov_b32_e32 v146, v4
	v_mov_b32_e32 v147, v4
	s_nop 0
	s_nop 0
	v_readfirstlane_b32 s98, v0
	s_nop 3
	s_lshr_b32 s98, s98, 6
	s_cmp_ge_u32 s98, 4
	s_cbranch_scc0 .Lprio_g2
	s_setprio 1

; #define PG8_STAGE(bufoff, gbase, voff) do { _Pragma("unroll") for (int _i = 0; _i < 2; ++_i) \
;         __builtin_amdgcn_global_load_lds((const unsigned*)((const char*)(gbase) + (voff)[_i]), (PG8_LAS unsigned*)(lds + (bufoff) + ldsw + _i * 8192), 16, 0, 0); } while (0)
; #define PG8_LDA(dst, b, h) do { _Pragma("unroll") for (int m = 0; m < 4; ++m) _Pragma("unroll") for (int k = 0; k < 2; ++k) dst[m][k] = *(const PG8_LAS bf16x8*)(lds + PG8_SA(b, h) + aoff + m * 2048 + k * 1024); } while (0)
; #define PG8_LDB(dst, b, h) do { _Pragma("unroll") for (int n = 0; n < 2; ++n) _Pragma("unroll") for (int k = 0; k < 2; ++k) dst[n][k] = *(const PG8_LAS bf16x8*)(lds + PG8_SB(b, h) + boff + n * 2048 + k * 1024); } while (0)
; #define PG8_MMA(ai, bj, At, Bt) do { __builtin_amdgcn_s_setprio(1); _Pragma("unroll") for (int m = 0; m < 4; ++m) _Pragma("unroll") for (int n = 0; n < 2; ++n) _Pragma("unroll") for (int k = 0; k < 2; ++k) \
;         acc[ai][bj][m][n] = __builtin_amdgcn_mfma_f32_16x16x32_bf16(Bt[n][k], At[m][k], acc[ai][bj][m][n], 0, 0, 0); __builtin_amdgcn_s_setprio(0); } while (0)
; #define PG8_WAIT_V(n) asm volatile("s_waitcnt vmcnt(" #n ")" ::: "memory")
; #define PG8_WAIT_L(n) asm volatile("s_waitcnt lgkmcnt(" #n ")" ::: "memory")
; #define PG8_BAR __builtin_amdgcn_s_barrier()
; #define PG8_SCHED __builtin_amdgcn_sched_barrier(0)
; template <class Epi, class Sched, bool ALIGN_EPI = false, bool SP2 = false>
; __device__ __forceinline__ void gemm_phase(PG8_LAS unsigned char* lds, const Gemm g, const Sched& S, const Epi& E) {
;     ...
;             PG8_LDB(B0, 0, 0); PG8_LDB(B1, 0, 1); PG8_SCHED; PG8_LDA(At, 0, 0); PG8_STAGE(PG8_SA(1, 1), a1 + hstepA, voffA);
;             PG8_WAIT_V(8); PG8_WAIT_L(0); PG8_BAR; PG8_MMA(0, 0, At, B0); PG8_MMA(0, 1, At, B1); PG8_BAR; PG8_SCHED;
;             PG8_LDA(At, 0, 1); PG8_STAGE(PG8_SB(0, 0), b2, voffB); PG8_STAGE(PG8_SB(0, 1), b2 + hstepB, voffB); PG8_STAGE(PG8_SA(0, 0), a2, voffA);
;             PG8_WAIT_V(8); PG8_WAIT_L(0); PG8_BAR; PG8_MMA(1, 0, At, B0); PG8_MMA(1, 1, At, B1); PG8_BAR; PG8_SCHED;
.LBB0_1760:
	s_add_u32 s8, s42, 0xfff80080
	s_addc_u32 s9, s43, -1
	s_add_i32 s14, 0, 0x10000
	s_cmp_eq_u32 s21, 4
	s_cselect_b32 s67, s59, s9
	s_cselect_b32 s66, s58, s8
	s_cselect_b32 s63, s4, s7
	s_cselect_b32 s62, s5, s6
	s_add_i32 s15, 0, 0x14000
	v_add_u32_e32 v88, s14, v179
	v_add_u32_e32 v156, s15, v179
	ds_read_b128 v[76:79], v88
	ds_read_b128 v[80:83], v88 offset:1024
	ds_read_b128 v[84:87], v88 offset:2048
	ds_read_b128 v[88:91], v88 offset:3072
	ds_read_b128 v[174:177], v156
	ds_read_b128 v[186:189], v156 offset:1024
	ds_read_b128 v[190:193], v156 offset:2048
	ds_read_b128 v[194:197], v156 offset:3072
	v_lshl_add_u64 v[156:157], s[42:43], 0, v[154:155]
	s_add_i32 m0, s57, 0xc000
	ds_read_b128 v[208:211], v183
	ds_read_b128 v[212:215], v183 offset:1024
	ds_read_b128 v[216:219], v183 offset:2048
	ds_read_b128 v[220:223], v183 offset:3072
	ds_read_b128 v[224:227], v183 offset:4096
	ds_read_b128 v[228:231], v183 offset:5120
	ds_read_b128 v[232:235], v183 offset:6144
	ds_read_b128 v[236:239], v183 offset:7168
	global_load_lds_dwordx4 v[156:157], off
	v_lshl_add_u64 v[156:157], s[42:43], 0, v[172:173]
	s_add_i32 m0, s57, 0xe000
	s_nop 0
	global_load_lds_dwordx4 v[156:157], off
	s_waitcnt vmcnt(8)
	s_waitcnt lgkmcnt(0)
	s_barrier
	s_waitcnt lgkmcnt(0)
	v_mfma_f32_16x16x32_bf16 v[144:147], v[76:79], v[208:211], v[144:147]
	v_mfma_f32_16x16x32_bf16 v[140:143], v[84:87], v[208:211], v[140:143]
	v_mfma_f32_16x16x32_bf16 v[128:131], v[76:79], v[216:219], v[128:131]
	v_mfma_f32_16x16x32_bf16 v[124:127], v[84:87], v[216:219], v[124:127]
	v_mfma_f32_16x16x32_bf16 v[112:115], v[76:79], v[224:227], v[112:115]
	v_mfma_f32_16x16x32_bf16 v[108:111], v[84:87], v[224:227], v[108:111]
	v_mfma_f32_16x16x32_bf16 v[96:99], v[76:79], v[232:235], v[96:99]
	v_mfma_f32_16x16x32_bf16 v[92:95], v[84:87], v[232:235], v[92:95]
	v_mfma_f32_16x16x32_bf16 v[144:147], v[80:83], v[212:215], v[144:147]
	v_mfma_f32_16x16x32_bf16 v[140:143], v[88:91], v[212:215], v[140:143]
	v_mfma_f32_16x16x32_bf16 v[128:131], v[80:83], v[220:223], v[128:131]
	v_mfma_f32_16x16x32_bf16 v[124:127], v[88:91], v[220:223], v[124:127]
	v_mfma_f32_16x16x32_bf16 v[112:115], v[80:83], v[228:231], v[112:115]
	v_mfma_f32_16x16x32_bf16 v[108:111], v[88:91], v[228:231], v[108:111]
	v_mfma_f32_16x16x32_bf16 v[96:99], v[80:83], v[236:239], v[96:99]
	v_mfma_f32_16x16x32_bf16 v[92:95], v[88:91], v[236:239], v[92:95]
	v_mfma_f32_16x16x32_bf16 v[136:139], v[174:177], v[208:211], v[136:139]
	v_mfma_f32_16x16x32_bf16 v[132:135], v[190:193], v[208:211], v[132:135]
	v_mfma_f32_16x16x32_bf16 v[120:123], v[174:177], v[216:219], v[120:123]
	v_mfma_f32_16x16x32_bf16 v[116:119], v[190:193], v[216:219], v[116:119]
	v_mfma_f32_16x16x32_bf16 v[104:107], v[174:177], v[224:227], v[104:107]
	v_mfma_f32_16x16x32_bf16 v[100:103], v[190:193], v[224:227], v[100:103]
	v_mfma_f32_16x16x32_bf16 v[72:75], v[174:177], v[232:235], v[72:75]
	v_mfma_f32_16x16x32_bf16 v[68:71], v[190:193], v[232:235], v[68:71]
	v_mfma_f32_16x16x32_bf16 v[136:139], v[186:189], v[212:215], v[136:139]
	v_mfma_f32_16x16x32_bf16 v[132:135], v[194:197], v[212:215], v[132:135]
	v_mfma_f32_16x16x32_bf16 v[120:123], v[186:189], v[220:223], v[120:123]
	v_mfma_f32_16x16x32_bf16 v[116:119], v[194:197], v[220:223], v[116:119]
	v_mfma_f32_16x16x32_bf16 v[104:107], v[186:189], v[228:231], v[104:107]
	v_mfma_f32_16x16x32_bf16 v[100:103], v[194:197], v[228:231], v[100:103]
	v_mfma_f32_16x16x32_bf16 v[72:75], v[186:189], v[236:239], v[72:75]
	v_mfma_f32_16x16x32_bf16 v[68:71], v[194:197], v[236:239], v[68:71]
	s_barrier
	s_add_i32 s8, s14, s82
	v_lshl_add_u64 v[156:157], s[62:63], 0, v[2:3]
	s_mov_b32 m0, s8
	ds_read_b128 v[208:211], v183 offset:16384
	ds_read_b128 v[212:215], v183 offset:17408
	ds_read_b128 v[216:219], v183 offset:18432
	ds_read_b128 v[220:223], v183 offset:19456
	ds_read_b128 v[224:227], v183 offset:20480
	ds_read_b128 v[228:231], v183 offset:21504
	ds_read_b128 v[232:235], v183 offset:22528
	ds_read_b128 v[236:239], v183 offset:23552
	global_load_lds_dwordx4 v[156:157], off
	s_add_i32 m0, s8, 0x2000
	s_add_u32 s8, s62, 0x20000
	v_lshl_add_u64 v[158:159], s[62:63], 0, v[152:153]
	s_addc_u32 s9, s63, 0
	s_add_i32 s14, s15, s82
	global_load_lds_dwordx4 v[158:159], off
	v_lshl_add_u64 v[164:165], s[8:9], 0, v[2:3]
	s_mov_b32 m0, s14
	v_lshl_add_u64 v[200:201], s[66:67], 0, v[150:151]
	global_load_lds_dwordx4 v[164:165], off
	v_lshl_add_u64 v[164:165], s[8:9], 0, v[152:153]
	s_add_i32 m0, s14, 0x2000
	s_nop 0
	global_load_lds_dwordx4 v[164:165], off
	v_lshl_add_u64 v[164:165], s[66:67], 0, v[148:149]
	s_mov_b32 m0, s57
	s_nop 0
	global_load_lds_dwordx4 v[164:165], off
	s_mov_b32 m0, s83
	s_nop 0
	global_load_lds_dwordx4 v[200:201], off
	s_waitcnt vmcnt(8)
	s_waitcnt lgkmcnt(0)
	s_barrier
; #define PG8_STAGE(bufoff, gbase, voff) do { _Pragma("unroll") for (int _i = 0; _i < 2; ++_i) \
;         __builtin_amdgcn_global_load_lds((const unsigned*)((const char*)(gbase) + (voff)[_i]), (PG8_LAS unsigned*)(lds + (bufoff) + ldsw + _i * 8192), 16, 0, 0); } while (0)
; #define PG8_LDA(dst, b, h) do { _Pragma("unroll") for (int m = 0; m < 4; ++m) _Pragma("unroll") for (int k = 0; k < 2; ++k) dst[m][k] = *(const PG8_LAS bf16x8*)(lds + PG8_SA(b, h) + aoff + m * 2048 + k * 1024); } while (0)
; #define PG8_LDB(dst, b, h) do { _Pragma("unroll") for (int n = 0; n < 2; ++n) _Pragma("unroll") for (int k = 0; k < 2; ++k) dst[n][k] = *(const PG8_LAS bf16x8*)(lds + PG8_SB(b, h) + boff + n * 2048 + k * 1024); } while (0)
; #define PG8_MMA(ai, bj, At, Bt) do { __builtin_amdgcn_s_setprio(1); _Pragma("unroll") for (int m = 0; m < 4; ++m) _Pragma("unroll") for (int n = 0; n < 2; ++n) _Pragma("unroll") for (int k = 0; k < 2; ++k) \
;         acc[ai][bj][m][n] = __builtin_amdgcn_mfma_f32_16x16x32_bf16(Bt[n][k], At[m][k], acc[ai][bj][m][n], 0, 0, 0); __builtin_amdgcn_s_setprio(0); } while (0)
; #define PG8_WAIT_V(n) asm volatile("s_waitcnt vmcnt(" #n ")" ::: "memory")
; #define PG8_WAIT_L(n) asm volatile("s_waitcnt lgkmcnt(" #n ")" ::: "memory")
; #define PG8_BAR __builtin_amdgcn_s_barrier()
; #define PG8_SCHED __builtin_amdgcn_sched_barrier(0)
; template <class Epi, class Sched, bool ALIGN_EPI = false, bool SP2 = false>
; __device__ __forceinline__ void gemm_phase(PG8_LAS unsigned char* lds, const Gemm g, const Sched& S, const Epi& E) {
;     ...
;             PG8_WAIT_V(8); PG8_WAIT_L(0); PG8_BAR; PG8_MMA(1, 0, At, B0); PG8_MMA(1, 1, At, B1); PG8_BAR; PG8_SCHED;
;             PG8_LDB(B0, 1, 0); PG8_LDB(B1, 1, 1); PG8_SCHED; PG8_LDA(At, 1, 0); PG8_STAGE(PG8_SA(0, 1), a2 + hstepA, voffA);
;             PG8_WAIT_V(8); PG8_WAIT_L(0); PG8_BAR; PG8_MMA(0, 0, At, B0); PG8_MMA(0, 1, At, B1); PG8_BAR; PG8_SCHED;
	s_waitcnt lgkmcnt(0)
	v_mfma_f32_16x16x32_bf16 v[64:67], v[76:79], v[208:211], v[64:67]
	v_mfma_f32_16x16x32_bf16 v[60:63], v[84:87], v[208:211], v[60:63]
	v_mfma_f32_16x16x32_bf16 v[48:51], v[76:79], v[216:219], v[48:51]
	v_mfma_f32_16x16x32_bf16 v[44:47], v[84:87], v[216:219], v[44:47]
	v_mfma_f32_16x16x32_bf16 v[32:35], v[76:79], v[224:227], v[32:35]
	v_mfma_f32_16x16x32_bf16 v[28:31], v[84:87], v[224:227], v[28:31]
	v_mfma_f32_16x16x32_bf16 v[16:19], v[76:79], v[232:235], v[16:19]
	v_mfma_f32_16x16x32_bf16 v[12:15], v[84:87], v[232:235], v[12:15]
	v_mfma_f32_16x16x32_bf16 v[64:67], v[80:83], v[212:215], v[64:67]
	v_mfma_f32_16x16x32_bf16 v[60:63], v[88:91], v[212:215], v[60:63]
	v_mfma_f32_16x16x32_bf16 v[48:51], v[80:83], v[220:223], v[48:51]
	v_mfma_f32_16x16x32_bf16 v[44:47], v[88:91], v[220:223], v[44:47]
	v_mfma_f32_16x16x32_bf16 v[32:35], v[80:83], v[228:231], v[32:35]
	v_mfma_f32_16x16x32_bf16 v[28:31], v[88:91], v[228:231], v[28:31]
	v_mfma_f32_16x16x32_bf16 v[16:19], v[80:83], v[236:239], v[16:19]
	v_mfma_f32_16x16x32_bf16 v[12:15], v[88:91], v[236:239], v[12:15]
	v_mfma_f32_16x16x32_bf16 v[56:59], v[174:177], v[208:211], v[56:59]
	v_mfma_f32_16x16x32_bf16 v[52:55], v[190:193], v[208:211], v[52:55]
	v_mfma_f32_16x16x32_bf16 v[40:43], v[174:177], v[216:219], v[40:43]
	v_mfma_f32_16x16x32_bf16 v[36:39], v[190:193], v[216:219], v[36:39]
	v_mfma_f32_16x16x32_bf16 v[24:27], v[174:177], v[224:227], v[24:27]
	v_mfma_f32_16x16x32_bf16 v[20:23], v[190:193], v[224:227], v[20:23]
	v_mfma_f32_16x16x32_bf16 v[8:11], v[174:177], v[232:235], v[8:11]
	v_mfma_f32_16x16x32_bf16 v[4:7], v[190:193], v[232:235], v[4:7]
	v_mfma_f32_16x16x32_bf16 v[56:59], v[186:189], v[212:215], v[56:59]
	v_mfma_f32_16x16x32_bf16 v[52:55], v[194:197], v[212:215], v[52:55]
	v_mfma_f32_16x16x32_bf16 v[40:43], v[186:189], v[220:223], v[40:43]
	v_mfma_f32_16x16x32_bf16 v[36:39], v[194:197], v[220:223], v[36:39]
	v_mfma_f32_16x16x32_bf16 v[24:27], v[186:189], v[228:231], v[24:27]
	v_mfma_f32_16x16x32_bf16 v[20:23], v[194:197], v[228:231], v[20:23]
	v_mfma_f32_16x16x32_bf16 v[8:11], v[186:189], v[236:239], v[8:11]
	v_mfma_f32_16x16x32_bf16 v[4:7], v[194:197], v[236:239], v[4:7]
	s_barrier
	s_add_i32 s14, 0, 0x18000
	s_add_i32 s15, 0, 0x1c000
	v_add_u32_e32 v88, s14, v179
	v_add_u32_e32 v185, s15, v179
	ds_read_b128 v[76:79], v88
	ds_read_b128 v[80:83], v88 offset:1024
	ds_read_b128 v[84:87], v88 offset:2048
	ds_read_b128 v[88:91], v88 offset:3072
	ds_read_b128 v[174:177], v185
	ds_read_b128 v[186:189], v185 offset:1024
	ds_read_b128 v[190:193], v185 offset:2048
	ds_read_b128 v[194:197], v185 offset:3072
	s_add_u32 s8, s66, 0x80000
	s_addc_u32 s9, s67, 0
	s_mov_b32 m0, s84
	v_lshl_add_u64 v[240:241], s[8:9], 0, v[148:149]
	ds_read_b128 v[208:211], v183 offset:32768
	ds_read_b128 v[212:215], v183 offset:33792
	ds_read_b128 v[216:219], v183 offset:34816
	ds_read_b128 v[220:223], v183 offset:35840
	ds_read_b128 v[224:227], v183 offset:36864
	ds_read_b128 v[228:231], v183 offset:37888
	ds_read_b128 v[232:235], v183 offset:38912
	ds_read_b128 v[236:239], v183 offset:39936
	global_load_lds_dwordx4 v[240:241], off
	v_lshl_add_u64 v[240:241], s[8:9], 0, v[150:151]
	s_mov_b32 m0, s85
	s_nop 0
	global_load_lds_dwordx4 v[240:241], off
	s_waitcnt vmcnt(8)
	s_waitcnt lgkmcnt(0)
	s_barrier
	s_waitcnt lgkmcnt(0)
	v_mfma_f32_16x16x32_bf16 v[144:147], v[76:79], v[208:211], v[144:147]
	v_mfma_f32_16x16x32_bf16 v[140:143], v[84:87], v[208:211], v[140:143]
	v_mfma_f32_16x16x32_bf16 v[128:131], v[76:79], v[216:219], v[128:131]
	v_mfma_f32_16x16x32_bf16 v[124:127], v[84:87], v[216:219], v[124:127]
	v_mfma_f32_16x16x32_bf16 v[112:115], v[76:79], v[224:227], v[112:115]
	v_mfma_f32_16x16x32_bf16 v[108:111], v[84:87], v[224:227], v[108:111]
	v_mfma_f32_16x16x32_bf16 v[96:99], v[76:79], v[232:235], v[96:99]
	v_mfma_f32_16x16x32_bf16 v[92:95], v[84:87], v[232:235], v[92:95]
	v_mfma_f32_16x16x32_bf16 v[144:147], v[80:83], v[212:215], v[144:147]
	v_mfma_f32_16x16x32_bf16 v[140:143], v[88:91], v[212:215], v[140:143]
	v_mfma_f32_16x16x32_bf16 v[128:131], v[80:83], v[220:223], v[128:131]
	v_mfma_f32_16x16x32_bf16 v[124:127], v[88:91], v[220:223], v[124:127]
	v_mfma_f32_16x16x32_bf16 v[112:115], v[80:83], v[228:231], v[112:115]
	v_mfma_f32_16x16x32_bf16 v[108:111], v[88:91], v[228:231], v[108:111]
	v_mfma_f32_16x16x32_bf16 v[96:99], v[80:83], v[236:239], v[96:99]
	v_mfma_f32_16x16x32_bf16 v[92:95], v[88:91], v[236:239], v[92:95]
	v_mfma_f32_16x16x32_bf16 v[136:139], v[174:177], v[208:211], v[136:139]
	v_mfma_f32_16x16x32_bf16 v[132:135], v[190:193], v[208:211], v[132:135]
	v_mfma_f32_16x16x32_bf16 v[120:123], v[174:177], v[216:219], v[120:123]
	v_mfma_f32_16x16x32_bf16 v[116:119], v[190:193], v[216:219], v[116:119]
	v_mfma_f32_16x16x32_bf16 v[104:107], v[174:177], v[224:227], v[104:107]
	v_mfma_f32_16x16x32_bf16 v[100:103], v[190:193], v[224:227], v[100:103]
	v_mfma_f32_16x16x32_bf16 v[72:75], v[174:177], v[232:235], v[72:75]
	v_mfma_f32_16x16x32_bf16 v[68:71], v[190:193], v[232:235], v[68:71]
	v_mfma_f32_16x16x32_bf16 v[136:139], v[186:189], v[212:215], v[136:139]
	v_mfma_f32_16x16x32_bf16 v[132:135], v[194:197], v[212:215], v[132:135]
	v_mfma_f32_16x16x32_bf16 v[120:123], v[186:189], v[220:223], v[120:123]
	v_mfma_f32_16x16x32_bf16 v[116:119], v[194:197], v[220:223], v[116:119]
	v_mfma_f32_16x16x32_bf16 v[104:107], v[186:189], v[228:231], v[104:107]
	v_mfma_f32_16x16x32_bf16 v[100:103], v[194:197], v[228:231], v[100:103]
	v_mfma_f32_16x16x32_bf16 v[72:75], v[186:189], v[236:239], v[72:75]
	v_mfma_f32_16x16x32_bf16 v[68:71], v[194:197], v[236:239], v[68:71]
	s_barrier
; #define PG8_WAIT_V(n) asm volatile("s_waitcnt vmcnt(" #n ")" ::: "memory")
; template <class Epi, class Sched, bool ALIGN_EPI = false, bool SP2 = false>
; __device__ __forceinline__ void gemm_phase(PG8_LAS unsigned char* lds, const Gemm g, const Sched& S, const Epi& E) {
;     ...
;             PG8_LDA(At, 1, 1); PG8_STAGE(PG8_SB(1, 0), b3, voffB); PG8_STAGE(PG8_SB(1, 1), b3 + hstepB, voffB); PG8_STAGE(PG8_SA(1, 0), a3, voffA);
;             PG8_WAIT_V(8); PG8_WAIT_L(0); PG8_BAR; PG8_MMA(1, 0, At, B0); PG8_MMA(1, 1, At, B1); PG8_BAR; PG8_SCHED;
;             } else {
;             PG8_LDB(B0, 0, 0); PG8_SCHED; PG8_LDA(At, 0, 0); PG8_STAGE(PG8_SA(1, 1), a1 + hstepA, voffA);
;             PG8_WAIT_L(8); PG8_BAR; PG8_WAIT_L(0); PG8_MMA(0, 0, At, B0); PG8_BAR; PG8_SCHED;
;             PG8_LDB(B1, 0, 1); PG8_STAGE(PG8_SB(0, 0), b2, voffB);
;             PG8_BAR; PG8_WAIT_L(0); PG8_MMA(0, 1, At, B1); PG8_BAR;
;             PG8_LDA(At, 0, 1); PG8_STAGE(PG8_SA(0, 0), a2, voffA);
;             PG8_BAR; PG8_WAIT_L(0); PG8_MMA(1, 0, At, B0); PG8_BAR; PG8_SCHED;
;             PG8_STAGE(PG8_SB(0, 1), b2 + hstepB, voffB);
;             PG8_WAIT_V(6); PG8_BAR; PG8_MMA(1, 1, At, B1); PG8_BAR;
;             PG8_LDB(B0, 1, 0); PG8_SCHED; PG8_LDA(At, 1, 0); PG8_STAGE(PG8_SA(0, 1), a2 + hstepA, voffA);
;             PG8_WAIT_L(8); PG8_BAR; PG8_WAIT_L(0); PG8_MMA(0, 0, At, B0); PG8_BAR; PG8_SCHED;
;             PG8_LDB(B1, 1, 1); PG8_STAGE(PG8_SB(1, 0), b3, voffB);
;             PG8_BAR; PG8_WAIT_L(0); PG8_MMA(0, 1, At, B1); PG8_BAR;
;             PG8_LDA(At, 1, 1); PG8_STAGE(PG8_SA(1, 0), a3, voffA);
;             PG8_BAR; PG8_WAIT_L(0); PG8_MMA(1, 0, At, B0); PG8_BAR; PG8_SCHED;
;             PG8_STAGE(PG8_SB(1, 1), b3 + hstepB, voffB);
;             PG8_WAIT_V(6); PG8_BAR; PG8_MMA(1, 1, At, B1); PG8_BAR;
;             }
;         }
;         if constexpr (ALIGN_EPI) { if (wr == 0) PG8_BAR; }
;     __device__ __forceinline__ void operator()(const f32x4 (&acc)[2][2][4][2], const Unit& u, int wr, int wc, int fr, int fq, const float (&rsv)[2][4]) const {
;         const int row0 = u.pm * BM + wr * 64 + fr, col0 = u.pn * BM + wc * 32 + 8 * fq;
;         f32x4 cv[2][2];
; #pragma unroll
;         for (int bj = 0; bj < 2; ++bj)
; #pragma unroll
;             for (int n = 0; n < 2; ++n) cv[bj][n] = cs ? *(const f32x4*)(cs + col0 + bj * HALF + 4 * n) : (f32x4){1.f, 1.f, 1.f, 1.f};
	s_add_i32 s8, s14, s82
	v_lshl_add_u64 v[156:157], v[156:157], 0, s[24:25]
	s_mov_b32 m0, s8
	ds_read_b128 v[208:211], v183 offset:49152
	ds_read_b128 v[212:215], v183 offset:50176
	ds_read_b128 v[216:219], v183 offset:51200
	ds_read_b128 v[220:223], v183 offset:52224
	ds_read_b128 v[224:227], v183 offset:53248
	ds_read_b128 v[228:231], v183 offset:54272
	ds_read_b128 v[232:235], v183 offset:55296
	ds_read_b128 v[236:239], v183 offset:56320
	global_load_lds_dwordx4 v[156:157], off
	s_add_i32 m0, s8, 0x2000
	s_add_u32 s8, s62, 0x20080
	v_lshl_add_u64 v[156:157], v[158:159], 0, s[24:25]
	s_addc_u32 s9, s63, 0
	s_add_i32 s14, s15, s82
	global_load_lds_dwordx4 v[156:157], off
	v_lshl_add_u64 v[156:157], s[8:9], 0, v[2:3]
	s_mov_b32 m0, s14
	s_nop 0
	global_load_lds_dwordx4 v[156:157], off
	v_lshl_add_u64 v[156:157], s[8:9], 0, v[152:153]
	s_add_i32 m0, s14, 0x2000
	s_nop 0
	global_load_lds_dwordx4 v[156:157], off
	v_lshl_add_u64 v[156:157], v[164:165], 0, s[24:25]
	s_mov_b32 m0, s86
	s_nop 0
	global_load_lds_dwordx4 v[156:157], off
	v_lshl_add_u64 v[156:157], v[200:201], 0, s[24:25]
	s_mov_b32 m0, s87
	s_nop 0
	global_load_lds_dwordx4 v[156:157], off
	s_waitcnt vmcnt(8)
	s_waitcnt lgkmcnt(0)
	s_barrier
	s_waitcnt lgkmcnt(0)
	v_mfma_f32_16x16x32_bf16 v[64:67], v[76:79], v[208:211], v[64:67]
	v_mfma_f32_16x16x32_bf16 v[60:63], v[84:87], v[208:211], v[60:63]
	v_mfma_f32_16x16x32_bf16 v[48:51], v[76:79], v[216:219], v[48:51]
	v_mfma_f32_16x16x32_bf16 v[44:47], v[84:87], v[216:219], v[44:47]
	v_mfma_f32_16x16x32_bf16 v[32:35], v[76:79], v[224:227], v[32:35]
	v_mfma_f32_16x16x32_bf16 v[28:31], v[84:87], v[224:227], v[28:31]
	v_mfma_f32_16x16x32_bf16 v[16:19], v[76:79], v[232:235], v[16:19]
	v_mfma_f32_16x16x32_bf16 v[12:15], v[84:87], v[232:235], v[12:15]
	v_mfma_f32_16x16x32_bf16 v[64:67], v[80:83], v[212:215], v[64:67]
	v_mfma_f32_16x16x32_bf16 v[60:63], v[88:91], v[212:215], v[60:63]
	v_mfma_f32_16x16x32_bf16 v[48:51], v[80:83], v[220:223], v[48:51]
	v_mfma_f32_16x16x32_bf16 v[44:47], v[88:91], v[220:223], v[44:47]
	v_mfma_f32_16x16x32_bf16 v[32:35], v[80:83], v[228:231], v[32:35]
	v_mfma_f32_16x16x32_bf16 v[28:31], v[88:91], v[228:231], v[28:31]
	v_mfma_f32_16x16x32_bf16 v[16:19], v[80:83], v[236:239], v[16:19]
	v_mfma_f32_16x16x32_bf16 v[12:15], v[88:91], v[236:239], v[12:15]
	v_mfma_f32_16x16x32_bf16 v[56:59], v[174:177], v[208:211], v[56:59]
	v_mfma_f32_16x16x32_bf16 v[52:55], v[190:193], v[208:211], v[52:55]
	v_mfma_f32_16x16x32_bf16 v[40:43], v[174:177], v[216:219], v[40:43]
	v_mfma_f32_16x16x32_bf16 v[36:39], v[190:193], v[216:219], v[36:39]
	v_mfma_f32_16x16x32_bf16 v[24:27], v[174:177], v[224:227], v[24:27]
	v_mfma_f32_16x16x32_bf16 v[20:23], v[190:193], v[224:227], v[20:23]
	v_mfma_f32_16x16x32_bf16 v[8:11], v[174:177], v[232:235], v[8:11]
	v_mfma_f32_16x16x32_bf16 v[4:7], v[190:193], v[232:235], v[4:7]
	v_mfma_f32_16x16x32_bf16 v[56:59], v[186:189], v[212:215], v[56:59]
	v_mfma_f32_16x16x32_bf16 v[52:55], v[194:197], v[212:215], v[52:55]
	v_mfma_f32_16x16x32_bf16 v[40:43], v[186:189], v[220:223], v[40:43]
	v_mfma_f32_16x16x32_bf16 v[36:39], v[194:197], v[220:223], v[36:39]
	v_mfma_f32_16x16x32_bf16 v[24:27], v[186:189], v[228:231], v[24:27]
	v_mfma_f32_16x16x32_bf16 v[20:23], v[194:197], v[228:231], v[20:23]
	v_mfma_f32_16x16x32_bf16 v[8:11], v[186:189], v[236:239], v[8:11]
	v_mfma_f32_16x16x32_bf16 v[4:7], v[194:197], v[236:239], v[4:7]
	s_barrier
	s_add_i32 s21, s21, 2
	s_add_u32 s42, s42, 0x100
	s_addc_u32 s43, s43, 0
	s_add_u32 s6, s6, 0x100
	s_addc_u32 s7, s7, 0
	s_cmp_gt_u32 s21, 5
	s_cbranch_scc0 .LBB0_1760
	s_and_b64 vcc, exec, s[48:49]
	s_cbranch_vccz .LBB0_1763
	s_barrier
.LBB0_1763:
	s_setprio 0
	v_lshl_or_b32 v174, s20, 8, v180
	v_ashrrev_i32_e32 v175, 31, v174
	v_cndmask_b32_e64 v76, 0, 1, s[50:51]
	v_lshl_add_u64 v[176:177], v[174:175], 2, s[0:1]
	v_mov_b32_e32 v84, 1.0
	v_cmp_ne_u32_e64 s[42:43], 1, v76
	s_andn2_b64 vcc, exec, s[50:51]
	v_mov_b32_e32 v88, 1.0
	v_mov_b32_e32 v89, 1.0
	v_mov_b32_e32 v90, 1.0
	v_mov_b32_e32 v91, 1.0
	s_cbranch_vccnz .LBB0_1765
	global_load_dwordx4 v[88:91], v[176:177], off

; template <class Epi, class Sched, bool ALIGN_EPI = false, bool SP2 = false>
; __device__ __forceinline__ void gemm_phase(PG8_LAS unsigned char* lds, const Gemm g, const Sched& S, const Epi& E) {
;     ...
; #pragma unroll
;         for (int a = 0; a < 2; ++a)
; #pragma unroll
;             for (int b = 0; b < 2; ++b)
; #pragma unroll
;                 for (int m = 0; m < 4; ++m)
; #pragma unroll
;                     for (int n = 0; n < 2; ++n) acc[a][b][m][n] = (f32x4){0.f, 0.f, 0.f, 0.f};
;         cur = nxt; cA = nA; cB = nB; ++ui;
.LBB0_1885:
	s_ashr_i32 s53, s52, 31
	s_lshl_b64 s[4:5], s[52:53], 20
	s_add_u32 s56, s78, s4
	s_addc_u32 s57, s79, s5
	s_and_b64 s[4:5], s[38:39], exec
	s_cselect_b32 s3, s57, s37
	s_cselect_b32 s4, s56, s36
	s_ashr_i32 s21, s20, 31
	s_lshl_b64 s[6:7], s[20:21], 20
	s_add_u32 s58, s46, s6
	s_addc_u32 s59, s47, s7
	s_and_b64 s[6:7], s[38:39], exec
	s_cselect_b32 s5, s59, s43
	s_cselect_b32 s6, s58, s42
	s_add_u32 s36, s36, 0x80080
	s_addc_u32 s37, s37, 0
	s_add_u32 s7, s42, 0x100
	v_mov_b32_e32 v4, 0
	s_addc_u32 s21, s43, 0
	s_mov_b32 s41, -2
	v_mov_b32_e32 v5, v4
	v_mov_b32_e32 v6, v4
	v_mov_b32_e32 v7, v4
	v_mov_b32_e32 v8, v4
	v_mov_b32_e32 v9, v4
	v_mov_b32_e32 v10, v4
	v_mov_b32_e32 v11, v4
	v_mov_b32_e32 v20, v4
	v_mov_b32_e32 v21, v4
	v_mov_b32_e32 v22, v4
	v_mov_b32_e32 v23, v4
	v_mov_b32_e32 v28, v4
	v_mov_b32_e32 v29, v4
	v_mov_b32_e32 v30, v4
	v_mov_b32_e32 v31, v4
	v_mov_b32_e32 v52, v4
	v_mov_b32_e32 v53, v4
	v_mov_b32_e32 v54, v4
	v_mov_b32_e32 v55, v4
	v_mov_b32_e32 v56, v4
	v_mov_b32_e32 v57, v4
	v_mov_b32_e32 v58, v4
	v_mov_b32_e32 v59, v4
	v_mov_b32_e32 v68, v4
	v_mov_b32_e32 v69, v4
	v_mov_b32_e32 v70, v4
	v_mov_b32_e32 v71, v4
	v_mov_b32_e32 v72, v4
	v_mov_b32_e32 v73, v4
	v_mov_b32_e32 v74, v4
	v_mov_b32_e32 v75, v4
	v_mov_b32_e32 v12, v4
	v_mov_b32_e32 v13, v4
	v_mov_b32_e32 v14, v4
	v_mov_b32_e32 v15, v4
	v_mov_b32_e32 v16, v4
	v_mov_b32_e32 v17, v4
	v_mov_b32_e32 v18, v4
	v_mov_b32_e32 v19, v4
	v_mov_b32_e32 v40, v4
	v_mov_b32_e32 v41, v4
	v_mov_b32_e32 v42, v4
	v_mov_b32_e32 v43, v4
	v_mov_b32_e32 v48, v4
	v_mov_b32_e32 v49, v4
	v_mov_b32_e32 v50, v4
	v_mov_b32_e32 v51, v4
	v_mov_b32_e32 v60, v4
	v_mov_b32_e32 v61, v4
	v_mov_b32_e32 v62, v4
	v_mov_b32_e32 v63, v4
	v_mov_b32_e32 v64, v4
	v_mov_b32_e32 v65, v4
	v_mov_b32_e32 v66, v4
	v_mov_b32_e32 v67, v4
	v_mov_b32_e32 v76, v4
	v_mov_b32_e32 v77, v4
	v_mov_b32_e32 v78, v4
	v_mov_b32_e32 v79, v4
	v_mov_b32_e32 v80, v4
	v_mov_b32_e32 v81, v4
	v_mov_b32_e32 v82, v4
	v_mov_b32_e32 v83, v4
	v_mov_b32_e32 v84, v4
	v_mov_b32_e32 v85, v4
	v_mov_b32_e32 v86, v4
	v_mov_b32_e32 v87, v4
	v_mov_b32_e32 v88, v4
	v_mov_b32_e32 v89, v4
	v_mov_b32_e32 v90, v4
	v_mov_b32_e32 v91, v4
	v_mov_b32_e32 v100, v4
	v_mov_b32_e32 v101, v4
	v_mov_b32_e32 v102, v4
	v_mov_b32_e32 v103, v4
	v_mov_b32_e32 v104, v4
	v_mov_b32_e32 v105, v4
	v_mov_b32_e32 v106, v4
	v_mov_b32_e32 v107, v4
	v_mov_b32_e32 v116, v4
	v_mov_b32_e32 v117, v4
	v_mov_b32_e32 v118, v4
	v_mov_b32_e32 v119, v4
	v_mov_b32_e32 v120, v4
	v_mov_b32_e32 v121, v4
	v_mov_b32_e32 v122, v4
	v_mov_b32_e32 v123, v4
	v_mov_b32_e32 v132, v4
	v_mov_b32_e32 v133, v4
	v_mov_b32_e32 v134, v4
	v_mov_b32_e32 v135, v4
	v_mov_b32_e32 v136, v4
	v_mov_b32_e32 v137, v4
	v_mov_b32_e32 v138, v4
	v_mov_b32_e32 v139, v4
	v_mov_b32_e32 v92, v4
	v_mov_b32_e32 v93, v4
	v_mov_b32_e32 v94, v4
	v_mov_b32_e32 v95, v4
	v_mov_b32_e32 v96, v4
	v_mov_b32_e32 v97, v4
	v_mov_b32_e32 v98, v4
	v_mov_b32_e32 v99, v4
	v_mov_b32_e32 v108, v4
	v_mov_b32_e32 v109, v4
	v_mov_b32_e32 v110, v4
	v_mov_b32_e32 v111, v4
	v_mov_b32_e32 v112, v4
	v_mov_b32_e32 v113, v4
	v_mov_b32_e32 v114, v4
	v_mov_b32_e32 v115, v4
	v_mov_b32_e32 v124, v4
	v_mov_b32_e32 v125, v4
	v_mov_b32_e32 v126, v4
	v_mov_b32_e32 v127, v4
	v_mov_b32_e32 v128, v4
	v_mov_b32_e32 v129, v4
	v_mov_b32_e32 v130, v4
	v_mov_b32_e32 v131, v4
	v_mov_b32_e32 v140, v4
	v_mov_b32_e32 v141, v4
	v_mov_b32_e32 v142, v4
	v_mov_b32_e32 v143, v4
	v_mov_b32_e32 v144, v4
	v_mov_b32_e32 v145, v4
	v_mov_b32_e32 v146, v4
	v_mov_b32_e32 v147, v4
	s_nop 0
	v_readfirstlane_b32 s98, v0
	s_nop 3
	s_lshr_b32 s98, s98, 6
	s_cmp_ge_u32 s98, 4
	s_cbranch_scc0 .Lprio_g3
	s_setprio 1

; #define PG8_STAGE(bufoff, gbase, voff) do { _Pragma("unroll") for (int _i = 0; _i < 2; ++_i) \
;         __builtin_amdgcn_global_load_lds((const unsigned*)((const char*)(gbase) + (voff)[_i]), (PG8_LAS unsigned*)(lds + (bufoff) + ldsw + _i * 8192), 16, 0, 0); } while (0)
; #define PG8_LDA(dst, b, h) do { _Pragma("unroll") for (int m = 0; m < 4; ++m) _Pragma("unroll") for (int k = 0; k < 2; ++k) dst[m][k] = *(const PG8_LAS bf16x8*)(lds + PG8_SA(b, h) + aoff + m * 2048 + k * 1024); } while (0)
; #define PG8_LDB(dst, b, h) do { _Pragma("unroll") for (int n = 0; n < 2; ++n) _Pragma("unroll") for (int k = 0; k < 2; ++k) dst[n][k] = *(const PG8_LAS bf16x8*)(lds + PG8_SB(b, h) + boff + n * 2048 + k * 1024); } while (0)
; #define PG8_MMA(ai, bj, At, Bt) do { __builtin_amdgcn_s_setprio(1); _Pragma("unroll") for (int m = 0; m < 4; ++m) _Pragma("unroll") for (int n = 0; n < 2; ++n) _Pragma("unroll") for (int k = 0; k < 2; ++k) \
;         acc[ai][bj][m][n] = __builtin_amdgcn_mfma_f32_16x16x32_bf16(Bt[n][k], At[m][k], acc[ai][bj][m][n], 0, 0, 0); __builtin_amdgcn_s_setprio(0); } while (0)
; #define PG8_WAIT_V(n) asm volatile("s_waitcnt vmcnt(" #n ")" ::: "memory")
; #define PG8_WAIT_L(n) asm volatile("s_waitcnt lgkmcnt(" #n ")" ::: "memory")
; #define PG8_BAR __builtin_amdgcn_s_barrier()
; #define PG8_SCHED __builtin_amdgcn_sched_barrier(0)
; template <class Epi, class Sched, bool ALIGN_EPI = false, bool SP2 = false>
; __device__ __forceinline__ void gemm_phase(PG8_LAS unsigned char* lds, const Gemm g, const Sched& S, const Epi& E) {
;     ...
;             PG8_LDB(B0, 0, 0); PG8_LDB(B1, 0, 1); PG8_SCHED; PG8_LDA(At, 0, 0); PG8_STAGE(PG8_SA(1, 1), a1 + hstepA, voffA);
;             PG8_WAIT_V(8); PG8_WAIT_L(0); PG8_BAR; PG8_MMA(0, 0, At, B0); PG8_MMA(0, 1, At, B1); PG8_BAR; PG8_SCHED;
;             PG8_LDA(At, 0, 1); PG8_STAGE(PG8_SB(0, 0), b2, voffB); PG8_STAGE(PG8_SB(0, 1), b2 + hstepB, voffB); PG8_STAGE(PG8_SA(0, 0), a2, voffA);
;             PG8_WAIT_V(8); PG8_WAIT_L(0); PG8_BAR; PG8_MMA(1, 0, At, B0); PG8_MMA(1, 1, At, B1); PG8_BAR; PG8_SCHED;
.LBB0_1886:
	s_add_u32 s8, s36, 0xfff80080
	s_addc_u32 s9, s37, -1
	s_add_i32 s14, 0, 0x10000
	s_cmp_eq_u32 s41, 28
	s_cselect_b32 s63, s3, s9
	s_cselect_b32 s62, s4, s8
	s_cselect_b32 s43, s5, s21
	s_cselect_b32 s42, s6, s7
	s_add_i32 s15, 0, 0x14000
	v_add_u32_e32 v44, s14, v208
	v_add_u32_e32 v156, s15, v208
	ds_read_b128 v[24:27], v44
	ds_read_b128 v[32:35], v44 offset:1024
	ds_read_b128 v[36:39], v44 offset:2048
	ds_read_b128 v[44:47], v44 offset:3072
	ds_read_b128 v[148:151], v156
	ds_read_b128 v[152:155], v156 offset:1024
	ds_read_b128 v[212:215], v156 offset:2048
	ds_read_b128 v[216:219], v156 offset:3072
	v_lshl_add_u64 v[252:253], s[36:37], 0, v[178:179]
	s_add_i32 m0, s81, 0xc000
	ds_read_b128 v[220:223], v210
	ds_read_b128 v[224:227], v210 offset:1024
	ds_read_b128 v[228:231], v210 offset:2048
	ds_read_b128 v[232:235], v210 offset:3072
	ds_read_b128 v[236:239], v210 offset:4096
	ds_read_b128 v[240:243], v210 offset:5120
	ds_read_b128 v[244:247], v210 offset:6144
	ds_read_b128 v[248:251], v210 offset:7168
	global_load_lds_dwordx4 v[252:253], off
	v_lshl_add_u64 v[252:253], s[36:37], 0, v[180:181]
	s_add_i32 m0, s81, 0xe000
	s_nop 0
	global_load_lds_dwordx4 v[252:253], off
	s_waitcnt vmcnt(8)
	s_waitcnt lgkmcnt(0)
	s_barrier
	s_waitcnt lgkmcnt(0)
	v_mfma_f32_16x16x32_bf16 v[144:147], v[24:27], v[220:223], v[144:147]
	v_mfma_f32_16x16x32_bf16 v[140:143], v[36:39], v[220:223], v[140:143]
	v_mfma_f32_16x16x32_bf16 v[128:131], v[24:27], v[228:231], v[128:131]
	v_mfma_f32_16x16x32_bf16 v[124:127], v[36:39], v[228:231], v[124:127]
	v_mfma_f32_16x16x32_bf16 v[112:115], v[24:27], v[236:239], v[112:115]
	v_mfma_f32_16x16x32_bf16 v[108:111], v[36:39], v[236:239], v[108:111]
	v_mfma_f32_16x16x32_bf16 v[96:99], v[24:27], v[244:247], v[96:99]
	v_mfma_f32_16x16x32_bf16 v[92:95], v[36:39], v[244:247], v[92:95]
	v_mfma_f32_16x16x32_bf16 v[144:147], v[32:35], v[224:227], v[144:147]
	v_mfma_f32_16x16x32_bf16 v[140:143], v[44:47], v[224:227], v[140:143]
	v_mfma_f32_16x16x32_bf16 v[128:131], v[32:35], v[232:235], v[128:131]
	v_mfma_f32_16x16x32_bf16 v[124:127], v[44:47], v[232:235], v[124:127]
	v_mfma_f32_16x16x32_bf16 v[112:115], v[32:35], v[240:243], v[112:115]
	v_mfma_f32_16x16x32_bf16 v[108:111], v[44:47], v[240:243], v[108:111]
	v_mfma_f32_16x16x32_bf16 v[96:99], v[32:35], v[248:251], v[96:99]
	v_mfma_f32_16x16x32_bf16 v[92:95], v[44:47], v[248:251], v[92:95]
	v_mfma_f32_16x16x32_bf16 v[136:139], v[148:151], v[220:223], v[136:139]
	v_mfma_f32_16x16x32_bf16 v[132:135], v[212:215], v[220:223], v[132:135]
	v_mfma_f32_16x16x32_bf16 v[120:123], v[148:151], v[228:231], v[120:123]
	v_mfma_f32_16x16x32_bf16 v[116:119], v[212:215], v[228:231], v[116:119]
	v_mfma_f32_16x16x32_bf16 v[104:107], v[148:151], v[236:239], v[104:107]
	v_mfma_f32_16x16x32_bf16 v[100:103], v[212:215], v[236:239], v[100:103]
	v_mfma_f32_16x16x32_bf16 v[88:91], v[148:151], v[244:247], v[88:91]
	v_mfma_f32_16x16x32_bf16 v[84:87], v[212:215], v[244:247], v[84:87]
	v_mfma_f32_16x16x32_bf16 v[136:139], v[152:155], v[224:227], v[136:139]
	v_mfma_f32_16x16x32_bf16 v[132:135], v[216:219], v[224:227], v[132:135]
	v_mfma_f32_16x16x32_bf16 v[120:123], v[152:155], v[232:235], v[120:123]
	v_mfma_f32_16x16x32_bf16 v[116:119], v[216:219], v[232:235], v[116:119]
	v_mfma_f32_16x16x32_bf16 v[104:107], v[152:155], v[240:243], v[104:107]
	v_mfma_f32_16x16x32_bf16 v[100:103], v[216:219], v[240:243], v[100:103]
	v_mfma_f32_16x16x32_bf16 v[88:91], v[152:155], v[248:251], v[88:91]
	v_mfma_f32_16x16x32_bf16 v[84:87], v[216:219], v[248:251], v[84:87]
	s_barrier
	s_add_i32 s8, s14, s80
	v_lshl_add_u64 v[252:253], s[42:43], 0, v[2:3]
	s_mov_b32 m0, s8
	ds_read_b128 v[220:223], v210 offset:16384
	ds_read_b128 v[224:227], v210 offset:17408
	ds_read_b128 v[228:231], v210 offset:18432
	ds_read_b128 v[232:235], v210 offset:19456
	ds_read_b128 v[236:239], v210 offset:20480
	ds_read_b128 v[240:243], v210 offset:21504
	ds_read_b128 v[244:247], v210 offset:22528
	ds_read_b128 v[248:251], v210 offset:23552
	global_load_lds_dwordx4 v[252:253], off
	s_add_i32 m0, s8, 0x2000
	s_add_u32 s8, s42, 0x80000
	v_lshl_add_u64 v[200:201], s[42:43], 0, v[176:177]
	s_addc_u32 s9, s43, 0
	s_add_i32 s14, s15, s80
	global_load_lds_dwordx4 v[200:201], off
	v_lshl_add_u64 v[156:157], s[8:9], 0, v[2:3]
	s_mov_b32 m0, s14
	v_lshl_add_u64 v[158:159], s[62:63], 0, v[174:175]
	global_load_lds_dwordx4 v[156:157], off
	v_lshl_add_u64 v[156:157], s[8:9], 0, v[176:177]
	s_add_i32 m0, s14, 0x2000
	s_nop 0
	global_load_lds_dwordx4 v[156:157], off
	v_lshl_add_u64 v[156:157], s[62:63], 0, v[172:173]
	s_mov_b32 m0, s81
	s_nop 0
	global_load_lds_dwordx4 v[156:157], off
	s_mov_b32 m0, s82
	s_nop 0
	global_load_lds_dwordx4 v[158:159], off
	s_waitcnt vmcnt(8)
	s_waitcnt lgkmcnt(0)
	s_barrier
; #define PG8_STAGE(bufoff, gbase, voff) do { _Pragma("unroll") for (int _i = 0; _i < 2; ++_i) \
;         __builtin_amdgcn_global_load_lds((const unsigned*)((const char*)(gbase) + (voff)[_i]), (PG8_LAS unsigned*)(lds + (bufoff) + ldsw + _i * 8192), 16, 0, 0); } while (0)
; #define PG8_LDA(dst, b, h) do { _Pragma("unroll") for (int m = 0; m < 4; ++m) _Pragma("unroll") for (int k = 0; k < 2; ++k) dst[m][k] = *(const PG8_LAS bf16x8*)(lds + PG8_SA(b, h) + aoff + m * 2048 + k * 1024); } while (0)
; #define PG8_LDB(dst, b, h) do { _Pragma("unroll") for (int n = 0; n < 2; ++n) _Pragma("unroll") for (int k = 0; k < 2; ++k) dst[n][k] = *(const PG8_LAS bf16x8*)(lds + PG8_SB(b, h) + boff + n * 2048 + k * 1024); } while (0)
; #define PG8_MMA(ai, bj, At, Bt) do { __builtin_amdgcn_s_setprio(1); _Pragma("unroll") for (int m = 0; m < 4; ++m) _Pragma("unroll") for (int n = 0; n < 2; ++n) _Pragma("unroll") for (int k = 0; k < 2; ++k) \
;         acc[ai][bj][m][n] = __builtin_amdgcn_mfma_f32_16x16x32_bf16(Bt[n][k], At[m][k], acc[ai][bj][m][n], 0, 0, 0); __builtin_amdgcn_s_setprio(0); } while (0)
; #define PG8_WAIT_V(n) asm volatile("s_waitcnt vmcnt(" #n ")" ::: "memory")
; #define PG8_WAIT_L(n) asm volatile("s_waitcnt lgkmcnt(" #n ")" ::: "memory")
; #define PG8_BAR __builtin_amdgcn_s_barrier()
; #define PG8_SCHED __builtin_amdgcn_sched_barrier(0)
; template <class Epi, class Sched, bool ALIGN_EPI = false, bool SP2 = false>
; __device__ __forceinline__ void gemm_phase(PG8_LAS unsigned char* lds, const Gemm g, const Sched& S, const Epi& E) {
;     ...
;             PG8_WAIT_V(8); PG8_WAIT_L(0); PG8_BAR; PG8_MMA(1, 0, At, B0); PG8_MMA(1, 1, At, B1); PG8_BAR; PG8_SCHED;
;             PG8_LDB(B0, 1, 0); PG8_LDB(B1, 1, 1); PG8_SCHED; PG8_LDA(At, 1, 0); PG8_STAGE(PG8_SA(0, 1), a2 + hstepA, voffA);
;             PG8_WAIT_V(8); PG8_WAIT_L(0); PG8_BAR; PG8_MMA(0, 0, At, B0); PG8_MMA(0, 1, At, B1); PG8_BAR; PG8_SCHED;
	s_waitcnt lgkmcnt(0)
	v_mfma_f32_16x16x32_bf16 v[80:83], v[24:27], v[220:223], v[80:83]
	v_mfma_f32_16x16x32_bf16 v[76:79], v[36:39], v[220:223], v[76:79]
	v_mfma_f32_16x16x32_bf16 v[64:67], v[24:27], v[228:231], v[64:67]
	v_mfma_f32_16x16x32_bf16 v[60:63], v[36:39], v[228:231], v[60:63]
	v_mfma_f32_16x16x32_bf16 v[48:51], v[24:27], v[236:239], v[48:51]
	v_mfma_f32_16x16x32_bf16 v[40:43], v[36:39], v[236:239], v[40:43]
	v_mfma_f32_16x16x32_bf16 v[16:19], v[24:27], v[244:247], v[16:19]
	v_mfma_f32_16x16x32_bf16 v[12:15], v[36:39], v[244:247], v[12:15]
	v_mfma_f32_16x16x32_bf16 v[80:83], v[32:35], v[224:227], v[80:83]
	v_mfma_f32_16x16x32_bf16 v[76:79], v[44:47], v[224:227], v[76:79]
	v_mfma_f32_16x16x32_bf16 v[64:67], v[32:35], v[232:235], v[64:67]
	v_mfma_f32_16x16x32_bf16 v[60:63], v[44:47], v[232:235], v[60:63]
	v_mfma_f32_16x16x32_bf16 v[48:51], v[32:35], v[240:243], v[48:51]
	v_mfma_f32_16x16x32_bf16 v[40:43], v[44:47], v[240:243], v[40:43]
	v_mfma_f32_16x16x32_bf16 v[16:19], v[32:35], v[248:251], v[16:19]
	v_mfma_f32_16x16x32_bf16 v[12:15], v[44:47], v[248:251], v[12:15]
	v_mfma_f32_16x16x32_bf16 v[28:31], v[148:151], v[236:239], v[28:31]
	v_mfma_f32_16x16x32_bf16 v[20:23], v[212:215], v[236:239], v[20:23]
	v_mfma_f32_16x16x32_bf16 v[8:11], v[148:151], v[244:247], v[8:11]
	v_mfma_f32_16x16x32_bf16 v[4:7], v[212:215], v[244:247], v[4:7]
	v_mfma_f32_16x16x32_bf16 v[24:27], v[148:151], v[220:223], v[72:75]
	v_mfma_f32_16x16x32_bf16 v[32:35], v[212:215], v[220:223], v[68:71]
	v_mfma_f32_16x16x32_bf16 v[36:39], v[148:151], v[228:231], v[56:59]
	v_mfma_f32_16x16x32_bf16 v[44:47], v[212:215], v[228:231], v[52:55]
	v_mfma_f32_16x16x32_bf16 v[28:31], v[152:155], v[240:243], v[28:31]
	v_mfma_f32_16x16x32_bf16 v[20:23], v[216:219], v[240:243], v[20:23]
	v_mfma_f32_16x16x32_bf16 v[8:11], v[152:155], v[248:251], v[8:11]
	v_mfma_f32_16x16x32_bf16 v[4:7], v[216:219], v[248:251], v[4:7]
	v_mfma_f32_16x16x32_bf16 v[24:27], v[152:155], v[224:227], v[24:27]
	v_mfma_f32_16x16x32_bf16 v[32:35], v[216:219], v[224:227], v[32:35]
	v_mfma_f32_16x16x32_bf16 v[36:39], v[152:155], v[232:235], v[36:39]
	v_mfma_f32_16x16x32_bf16 v[44:47], v[216:219], v[232:235], v[44:47]
	s_barrier
	s_add_i32 s14, 0, 0x18000
	s_add_i32 s15, 0, 0x1c000
	v_add_u32_e32 v72, s14, v208
	v_add_u32_e32 v164, s15, v208
	ds_read_b128 v[52:55], v72
	ds_read_b128 v[56:59], v72 offset:1024
	ds_read_b128 v[68:71], v72 offset:2048
	ds_read_b128 v[72:75], v72 offset:3072
	ds_read_b128 v[148:151], v164
	ds_read_b128 v[152:155], v164 offset:1024
	ds_read_b128 v[212:215], v164 offset:2048
	ds_read_b128 v[216:219], v164 offset:3072
	s_add_u32 s8, s62, 0x80000
	s_addc_u32 s9, s63, 0
	s_mov_b32 m0, s83
	v_lshl_add_u64 v[164:165], s[8:9], 0, v[172:173]
	ds_read_b128 v[220:223], v210 offset:32768
	ds_read_b128 v[224:227], v210 offset:33792
	ds_read_b128 v[228:231], v210 offset:34816
	ds_read_b128 v[232:235], v210 offset:35840
	ds_read_b128 v[236:239], v210 offset:36864
	ds_read_b128 v[240:243], v210 offset:37888
	ds_read_b128 v[244:247], v210 offset:38912
	ds_read_b128 v[248:251], v210 offset:39936
	global_load_lds_dwordx4 v[164:165], off
	v_lshl_add_u64 v[164:165], s[8:9], 0, v[174:175]
	s_mov_b32 m0, s84
	s_nop 0
	global_load_lds_dwordx4 v[164:165], off
	s_waitcnt vmcnt(8)
	s_waitcnt lgkmcnt(0)
	s_barrier
	s_waitcnt lgkmcnt(0)
	v_mfma_f32_16x16x32_bf16 v[144:147], v[52:55], v[220:223], v[144:147]
	v_mfma_f32_16x16x32_bf16 v[140:143], v[68:71], v[220:223], v[140:143]
	v_mfma_f32_16x16x32_bf16 v[128:131], v[52:55], v[228:231], v[128:131]
	v_mfma_f32_16x16x32_bf16 v[124:127], v[68:71], v[228:231], v[124:127]
	v_mfma_f32_16x16x32_bf16 v[112:115], v[52:55], v[236:239], v[112:115]
	v_mfma_f32_16x16x32_bf16 v[108:111], v[68:71], v[236:239], v[108:111]
	v_mfma_f32_16x16x32_bf16 v[96:99], v[52:55], v[244:247], v[96:99]
	v_mfma_f32_16x16x32_bf16 v[92:95], v[68:71], v[244:247], v[92:95]
	v_mfma_f32_16x16x32_bf16 v[144:147], v[56:59], v[224:227], v[144:147]
	v_mfma_f32_16x16x32_bf16 v[140:143], v[72:75], v[224:227], v[140:143]
	v_mfma_f32_16x16x32_bf16 v[128:131], v[56:59], v[232:235], v[128:131]
	v_mfma_f32_16x16x32_bf16 v[124:127], v[72:75], v[232:235], v[124:127]
	v_mfma_f32_16x16x32_bf16 v[112:115], v[56:59], v[240:243], v[112:115]
	v_mfma_f32_16x16x32_bf16 v[108:111], v[72:75], v[240:243], v[108:111]
	v_mfma_f32_16x16x32_bf16 v[96:99], v[56:59], v[248:251], v[96:99]
	v_mfma_f32_16x16x32_bf16 v[92:95], v[72:75], v[248:251], v[92:95]
	v_mfma_f32_16x16x32_bf16 v[136:139], v[148:151], v[220:223], v[136:139]
	v_mfma_f32_16x16x32_bf16 v[132:135], v[212:215], v[220:223], v[132:135]
	v_mfma_f32_16x16x32_bf16 v[120:123], v[148:151], v[228:231], v[120:123]
	v_mfma_f32_16x16x32_bf16 v[116:119], v[212:215], v[228:231], v[116:119]
	v_mfma_f32_16x16x32_bf16 v[104:107], v[148:151], v[236:239], v[104:107]
	v_mfma_f32_16x16x32_bf16 v[100:103], v[212:215], v[236:239], v[100:103]
	v_mfma_f32_16x16x32_bf16 v[88:91], v[148:151], v[244:247], v[88:91]
	v_mfma_f32_16x16x32_bf16 v[84:87], v[212:215], v[244:247], v[84:87]
	v_mfma_f32_16x16x32_bf16 v[136:139], v[152:155], v[224:227], v[136:139]
	v_mfma_f32_16x16x32_bf16 v[132:135], v[216:219], v[224:227], v[132:135]
	v_mfma_f32_16x16x32_bf16 v[120:123], v[152:155], v[232:235], v[120:123]
	v_mfma_f32_16x16x32_bf16 v[116:119], v[216:219], v[232:235], v[116:119]
	v_mfma_f32_16x16x32_bf16 v[104:107], v[152:155], v[240:243], v[104:107]
	v_mfma_f32_16x16x32_bf16 v[100:103], v[216:219], v[240:243], v[100:103]
	v_mfma_f32_16x16x32_bf16 v[88:91], v[152:155], v[248:251], v[88:91]
	v_mfma_f32_16x16x32_bf16 v[84:87], v[216:219], v[248:251], v[84:87]
	s_barrier
; #define PG8_BAR __builtin_amdgcn_s_barrier()
; template <class Epi, class Sched, bool ALIGN_EPI = false, bool SP2 = false>
; __device__ __forceinline__ void gemm_phase(PG8_LAS unsigned char* lds, const Gemm g, const Sched& S, const Epi& E) {
;     ...
;             PG8_LDA(At, 1, 1); PG8_STAGE(PG8_SB(1, 0), b3, voffB); PG8_STAGE(PG8_SB(1, 1), b3 + hstepB, voffB); PG8_STAGE(PG8_SA(1, 0), a3, voffA);
;             PG8_WAIT_V(8); PG8_WAIT_L(0); PG8_BAR; PG8_MMA(1, 0, At, B0); PG8_MMA(1, 1, At, B1); PG8_BAR; PG8_SCHED;
;             } else {
;             PG8_LDB(B0, 0, 0); PG8_SCHED; PG8_LDA(At, 0, 0); PG8_STAGE(PG8_SA(1, 1), a1 + hstepA, voffA);
;             PG8_WAIT_L(8); PG8_BAR; PG8_WAIT_L(0); PG8_MMA(0, 0, At, B0); PG8_BAR; PG8_SCHED;
;             PG8_LDB(B1, 0, 1); PG8_STAGE(PG8_SB(0, 0), b2, voffB);
;             PG8_BAR; PG8_WAIT_L(0); PG8_MMA(0, 1, At, B1); PG8_BAR;
;             PG8_LDA(At, 0, 1); PG8_STAGE(PG8_SA(0, 0), a2, voffA);
;             PG8_BAR; PG8_WAIT_L(0); PG8_MMA(1, 0, At, B0); PG8_BAR; PG8_SCHED;
;             PG8_STAGE(PG8_SB(0, 1), b2 + hstepB, voffB);
;             PG8_WAIT_V(6); PG8_BAR; PG8_MMA(1, 1, At, B1); PG8_BAR;
;             PG8_LDB(B0, 1, 0); PG8_SCHED; PG8_LDA(At, 1, 0); PG8_STAGE(PG8_SA(0, 1), a2 + hstepA, voffA);
;             PG8_WAIT_L(8); PG8_BAR; PG8_WAIT_L(0); PG8_MMA(0, 0, At, B0); PG8_BAR; PG8_SCHED;
;             PG8_LDB(B1, 1, 1); PG8_STAGE(PG8_SB(1, 0), b3, voffB);
;             PG8_BAR; PG8_WAIT_L(0); PG8_MMA(0, 1, At, B1); PG8_BAR;
;             PG8_LDA(At, 1, 1); PG8_STAGE(PG8_SA(1, 0), a3, voffA);
;             PG8_BAR; PG8_WAIT_L(0); PG8_MMA(1, 0, At, B0); PG8_BAR; PG8_SCHED;
;             PG8_STAGE(PG8_SB(1, 1), b3 + hstepB, voffB);
;             PG8_WAIT_V(6); PG8_BAR; PG8_MMA(1, 1, At, B1); PG8_BAR;
;             }
;         }
;         if constexpr (ALIGN_EPI) { if (wr == 0) PG8_BAR; }
;     __device__ __forceinline__ void operator()(const f32x4 (&acc)[2][2][4][2], const Unit& u, int wr, int wc, int fr, int fq, const float (&rsv)[2][4]) const {
;         const int seg = u.pn >> 3, row0 = u.pm * BM + wr * 64 + fr, col0 = (u.pn & 7) * BM + wc * 32 + 8 * fq;
;         f32x4 lbv[2][2];
;         if (seg == 1) {
; #pragma unroll
;             for (int bj = 0; bj < 2; ++bj)
; #pragma unroll
;                 for (int n = 0; n < 2; ++n) lbv[bj][n] = *(const f32x4*)(lb + col0 + bj * HALF + 4 * n);
;         }
	s_add_i32 s8, s14, s80
	v_lshl_add_u64 v[164:165], v[252:253], 0, s[24:25]
	s_mov_b32 m0, s8
	ds_read_b128 v[220:223], v210 offset:49152
	ds_read_b128 v[224:227], v210 offset:50176
	ds_read_b128 v[228:231], v210 offset:51200
	ds_read_b128 v[232:235], v210 offset:52224
	ds_read_b128 v[236:239], v210 offset:53248
	ds_read_b128 v[240:243], v210 offset:54272
	ds_read_b128 v[244:247], v210 offset:55296
	ds_read_b128 v[248:251], v210 offset:56320
	global_load_lds_dwordx4 v[164:165], off
	s_add_i32 m0, s8, 0x2000
	s_add_u32 s8, s42, 0x80080
	v_lshl_add_u64 v[164:165], v[200:201], 0, s[24:25]
	s_addc_u32 s9, s43, 0
	s_add_i32 s14, s15, s80
	global_load_lds_dwordx4 v[164:165], off
	v_lshl_add_u64 v[164:165], s[8:9], 0, v[2:3]
	s_mov_b32 m0, s14
	v_lshl_add_u64 v[156:157], v[156:157], 0, s[24:25]
	global_load_lds_dwordx4 v[164:165], off
	v_lshl_add_u64 v[164:165], s[8:9], 0, v[176:177]
	s_add_i32 m0, s14, 0x2000
	s_nop 0
	global_load_lds_dwordx4 v[164:165], off
	s_mov_b32 m0, s85
	s_nop 0
	global_load_lds_dwordx4 v[156:157], off
	v_lshl_add_u64 v[156:157], v[158:159], 0, s[24:25]
	s_mov_b32 m0, s86
	s_nop 0
	global_load_lds_dwordx4 v[156:157], off
	s_waitcnt vmcnt(8)
	s_waitcnt lgkmcnt(0)
	s_barrier
	s_waitcnt lgkmcnt(0)
	v_mfma_f32_16x16x32_bf16 v[80:83], v[52:55], v[220:223], v[80:83]
	v_mfma_f32_16x16x32_bf16 v[76:79], v[68:71], v[220:223], v[76:79]
	v_mfma_f32_16x16x32_bf16 v[64:67], v[52:55], v[228:231], v[64:67]
	v_mfma_f32_16x16x32_bf16 v[60:63], v[68:71], v[228:231], v[60:63]
	v_mfma_f32_16x16x32_bf16 v[48:51], v[52:55], v[236:239], v[48:51]
	v_mfma_f32_16x16x32_bf16 v[40:43], v[68:71], v[236:239], v[40:43]
	v_mfma_f32_16x16x32_bf16 v[16:19], v[52:55], v[244:247], v[16:19]
	v_mfma_f32_16x16x32_bf16 v[12:15], v[68:71], v[244:247], v[12:15]
	v_mfma_f32_16x16x32_bf16 v[80:83], v[56:59], v[224:227], v[80:83]
	v_mfma_f32_16x16x32_bf16 v[76:79], v[72:75], v[224:227], v[76:79]
	v_mfma_f32_16x16x32_bf16 v[64:67], v[56:59], v[232:235], v[64:67]
	v_mfma_f32_16x16x32_bf16 v[60:63], v[72:75], v[232:235], v[60:63]
	v_mfma_f32_16x16x32_bf16 v[48:51], v[56:59], v[240:243], v[48:51]
	v_mfma_f32_16x16x32_bf16 v[40:43], v[72:75], v[240:243], v[40:43]
	v_mfma_f32_16x16x32_bf16 v[16:19], v[56:59], v[248:251], v[16:19]
	v_mfma_f32_16x16x32_bf16 v[12:15], v[72:75], v[248:251], v[12:15]
	v_mfma_f32_16x16x32_bf16 v[24:27], v[148:151], v[220:223], v[24:27]
	v_mfma_f32_16x16x32_bf16 v[72:75], v[152:155], v[224:227], v[24:27]
	v_mfma_f32_16x16x32_bf16 v[24:27], v[212:215], v[220:223], v[32:35]
	v_mfma_f32_16x16x32_bf16 v[68:71], v[216:219], v[224:227], v[24:27]
	v_mfma_f32_16x16x32_bf16 v[24:27], v[148:151], v[228:231], v[36:39]
	v_mfma_f32_16x16x32_bf16 v[56:59], v[152:155], v[232:235], v[24:27]
	v_mfma_f32_16x16x32_bf16 v[24:27], v[212:215], v[228:231], v[44:47]
	v_mfma_f32_16x16x32_bf16 v[52:55], v[216:219], v[232:235], v[24:27]
	v_mfma_f32_16x16x32_bf16 v[24:27], v[148:151], v[236:239], v[28:31]
	v_mfma_f32_16x16x32_bf16 v[20:23], v[212:215], v[236:239], v[20:23]
	v_mfma_f32_16x16x32_bf16 v[8:11], v[148:151], v[244:247], v[8:11]
	v_mfma_f32_16x16x32_bf16 v[4:7], v[212:215], v[244:247], v[4:7]
	v_mfma_f32_16x16x32_bf16 v[28:31], v[152:155], v[240:243], v[24:27]
	v_mfma_f32_16x16x32_bf16 v[20:23], v[216:219], v[240:243], v[20:23]
	v_mfma_f32_16x16x32_bf16 v[8:11], v[152:155], v[248:251], v[8:11]
	v_mfma_f32_16x16x32_bf16 v[4:7], v[216:219], v[248:251], v[4:7]
	s_barrier
	s_add_i32 s41, s41, 2
	s_add_u32 s36, s36, 0x100
	s_addc_u32 s37, s37, 0
	s_add_u32 s7, s7, 0x100
	s_addc_u32 s21, s21, 0
	s_cmp_gt_u32 s41, 29
	s_cbranch_scc0 .LBB0_1886
	s_and_b64 vcc, exec, s[18:19]
	s_cbranch_vccz .LBB0_1889
	s_barrier
.LBB0_1889:
	s_setprio 0
	s_lshl_b32 s4, s40, 8
	s_ashr_i32 s3, s40, 3
	s_and_b32 s4, s4, 0x700
	s_cmp_lg_u32 s3, 1
	s_cselect_b64 s[36:37], -1, 0
	v_or_b32_e32 v211, s4, v209
	s_and_b64 vcc, exec, s[36:37]
	s_cbranch_vccnz .LBB0_1891
	v_lshlrev_b32_e32 v32, 2, v211
	global_load_dwordx4 v[36:39], v32, s[44:45] offset:16
	global_load_dwordx4 v[44:47], v32, s[44:45]
	global_load_dwordx4 v[24:27], v32, s[44:45] offset:528
	s_nop 0
	global_load_dwordx4 v[32:35], v32, s[44:45] offset:512

; template <class Epi, class Sched, bool ALIGN_EPI = false, bool SP2 = false>
; __device__ __forceinline__ void gemm_phase(PG8_LAS unsigned char* lds, const Gemm g, const Sched& S, const Epi& E) {
;     ...
; #pragma unroll
;         for (int a = 0; a < 2; ++a)
; #pragma unroll
;             for (int b = 0; b < 2; ++b)
; #pragma unroll
;                 for (int m = 0; m < 4; ++m)
; #pragma unroll
;                     for (int n = 0; n < 2; ++n) acc[a][b][m][n] = (f32x4){0.f, 0.f, 0.f, 0.f};
;         cur = nxt; cA = nA; cB = nB; ++ui;
.LBB0_2661:
	s_ashr_i32 s45, s44, 31
	s_lshl_b64 s[4:5], s[44:45], 20
	s_add_u32 s46, s64, s4
	s_addc_u32 s47, s65, s5
	s_and_b64 s[4:5], s[38:39], exec
	s_cselect_b32 s4, s47, s51
	s_cselect_b32 s5, s46, s50
	s_ashr_i32 s43, s42, 31
	s_lshl_b64 s[6:7], s[42:43], 20
	s_add_u32 s48, s12, s6
	s_addc_u32 s49, s13, s7
	s_and_b64 s[6:7], s[38:39], exec
	s_cselect_b32 s6, s49, s53
	s_cselect_b32 s7, s48, s52
	s_add_u32 s50, s50, 0x80080
	s_addc_u32 s51, s51, 0
	s_add_u32 s43, s52, 0x100
	v_mov_b32_e32 v4, 0
	s_addc_u32 s45, s53, 0
	s_mov_b32 s70, -2
	v_mov_b32_e32 v5, v4
	v_mov_b32_e32 v6, v4
	v_mov_b32_e32 v7, v4
	v_mov_b32_e32 v8, v4
	v_mov_b32_e32 v9, v4
	v_mov_b32_e32 v10, v4
	v_mov_b32_e32 v11, v4
	v_mov_b32_e32 v20, v4
	v_mov_b32_e32 v21, v4
	v_mov_b32_e32 v22, v4
	v_mov_b32_e32 v23, v4
	v_mov_b32_e32 v24, v4
	v_mov_b32_e32 v25, v4
	v_mov_b32_e32 v26, v4
	v_mov_b32_e32 v27, v4
	v_mov_b32_e32 v36, v4
	v_mov_b32_e32 v37, v4
	v_mov_b32_e32 v38, v4
	v_mov_b32_e32 v39, v4
	v_mov_b32_e32 v40, v4
	v_mov_b32_e32 v41, v4
	v_mov_b32_e32 v42, v4
	v_mov_b32_e32 v43, v4
	v_mov_b32_e32 v52, v4
	v_mov_b32_e32 v53, v4
	v_mov_b32_e32 v54, v4
	v_mov_b32_e32 v55, v4
	v_mov_b32_e32 v56, v4
	v_mov_b32_e32 v57, v4
	v_mov_b32_e32 v58, v4
	v_mov_b32_e32 v59, v4
	v_mov_b32_e32 v12, v4
	v_mov_b32_e32 v13, v4
	v_mov_b32_e32 v14, v4
	v_mov_b32_e32 v15, v4
	v_mov_b32_e32 v16, v4
	v_mov_b32_e32 v17, v4
	v_mov_b32_e32 v18, v4
	v_mov_b32_e32 v19, v4
	v_mov_b32_e32 v28, v4
	v_mov_b32_e32 v29, v4
	v_mov_b32_e32 v30, v4
	v_mov_b32_e32 v31, v4
	v_mov_b32_e32 v32, v4
	v_mov_b32_e32 v33, v4
	v_mov_b32_e32 v34, v4
	v_mov_b32_e32 v35, v4
	v_mov_b32_e32 v44, v4
	v_mov_b32_e32 v45, v4
	v_mov_b32_e32 v46, v4
	v_mov_b32_e32 v47, v4
	v_mov_b32_e32 v48, v4
	v_mov_b32_e32 v49, v4
	v_mov_b32_e32 v50, v4
	v_mov_b32_e32 v51, v4
	v_mov_b32_e32 v60, v4
	v_mov_b32_e32 v61, v4
	v_mov_b32_e32 v62, v4
	v_mov_b32_e32 v63, v4
	v_mov_b32_e32 v64, v4
	v_mov_b32_e32 v65, v4
	v_mov_b32_e32 v66, v4
	v_mov_b32_e32 v67, v4
	v_mov_b32_e32 v68, v4
	v_mov_b32_e32 v69, v4
	v_mov_b32_e32 v70, v4
	v_mov_b32_e32 v71, v4
	v_mov_b32_e32 v72, v4
	v_mov_b32_e32 v73, v4
	v_mov_b32_e32 v74, v4
	v_mov_b32_e32 v75, v4
	v_mov_b32_e32 v84, v4
	v_mov_b32_e32 v85, v4
	v_mov_b32_e32 v86, v4
	v_mov_b32_e32 v87, v4
	v_mov_b32_e32 v88, v4
	v_mov_b32_e32 v89, v4
	v_mov_b32_e32 v90, v4
	v_mov_b32_e32 v91, v4
	v_mov_b32_e32 v100, v4
	v_mov_b32_e32 v101, v4
	v_mov_b32_e32 v102, v4
	v_mov_b32_e32 v103, v4
	v_mov_b32_e32 v104, v4
	v_mov_b32_e32 v105, v4
	v_mov_b32_e32 v106, v4
	v_mov_b32_e32 v107, v4
	v_mov_b32_e32 v116, v4
	v_mov_b32_e32 v117, v4
	v_mov_b32_e32 v118, v4
	v_mov_b32_e32 v119, v4
	v_mov_b32_e32 v120, v4
	v_mov_b32_e32 v121, v4
	v_mov_b32_e32 v122, v4
	v_mov_b32_e32 v123, v4
	v_mov_b32_e32 v76, v4
	v_mov_b32_e32 v77, v4
	v_mov_b32_e32 v78, v4
	v_mov_b32_e32 v79, v4
	v_mov_b32_e32 v80, v4
	v_mov_b32_e32 v81, v4
	v_mov_b32_e32 v82, v4
	v_mov_b32_e32 v83, v4
	v_mov_b32_e32 v92, v4
	v_mov_b32_e32 v93, v4
	v_mov_b32_e32 v94, v4
	v_mov_b32_e32 v95, v4
	v_mov_b32_e32 v96, v4
	v_mov_b32_e32 v97, v4
	v_mov_b32_e32 v98, v4
	v_mov_b32_e32 v99, v4
	v_mov_b32_e32 v108, v4
	v_mov_b32_e32 v109, v4
	v_mov_b32_e32 v110, v4
	v_mov_b32_e32 v111, v4
	v_mov_b32_e32 v112, v4
	v_mov_b32_e32 v113, v4
	v_mov_b32_e32 v114, v4
	v_mov_b32_e32 v115, v4
	v_mov_b32_e32 v124, v4
	v_mov_b32_e32 v125, v4
	v_mov_b32_e32 v126, v4
	v_mov_b32_e32 v127, v4
	v_mov_b32_e32 v128, v4
	v_mov_b32_e32 v129, v4
	v_mov_b32_e32 v130, v4
	v_mov_b32_e32 v131, v4
	s_nop 0
	s_nop 0
	s_nop 0
	s_nop 0
	s_nop 0
	s_nop 0
	s_nop 0
	s_nop 0
	s_nop 0
	s_nop 0
	s_nop 0
	s_nop 0
	s_nop 0
	s_nop 0
	s_nop 0
	v_readfirstlane_b32 s98, v0
	s_nop 3
	s_lshr_b32 s98, s98, 6
	s_cmp_ge_u32 s98, 4
	s_cbranch_scc0 .Lprio_g5
	s_setprio 1

; #define PG8_STAGE(bufoff, gbase, voff) do { _Pragma("unroll") for (int _i = 0; _i < 2; ++_i) \
;         __builtin_amdgcn_global_load_lds((const unsigned*)((const char*)(gbase) + (voff)[_i]), (PG8_LAS unsigned*)(lds + (bufoff) + ldsw + _i * 8192), 16, 0, 0); } while (0)
; #define PG8_LDA(dst, b, h) do { _Pragma("unroll") for (int m = 0; m < 4; ++m) _Pragma("unroll") for (int k = 0; k < 2; ++k) dst[m][k] = *(const PG8_LAS bf16x8*)(lds + PG8_SA(b, h) + aoff + m * 2048 + k * 1024); } while (0)
; #define PG8_LDB(dst, b, h) do { _Pragma("unroll") for (int n = 0; n < 2; ++n) _Pragma("unroll") for (int k = 0; k < 2; ++k) dst[n][k] = *(const PG8_LAS bf16x8*)(lds + PG8_SB(b, h) + boff + n * 2048 + k * 1024); } while (0)
; #define PG8_MMA(ai, bj, At, Bt) do { __builtin_amdgcn_s_setprio(1); _Pragma("unroll") for (int m = 0; m < 4; ++m) _Pragma("unroll") for (int n = 0; n < 2; ++n) _Pragma("unroll") for (int k = 0; k < 2; ++k) \
;         acc[ai][bj][m][n] = __builtin_amdgcn_mfma_f32_16x16x32_bf16(Bt[n][k], At[m][k], acc[ai][bj][m][n], 0, 0, 0); __builtin_amdgcn_s_setprio(0); } while (0)
; #define PG8_WAIT_V(n) asm volatile("s_waitcnt vmcnt(" #n ")" ::: "memory")
; #define PG8_WAIT_L(n) asm volatile("s_waitcnt lgkmcnt(" #n ")" ::: "memory")
; #define PG8_BAR __builtin_amdgcn_s_barrier()
; #define PG8_SCHED __builtin_amdgcn_sched_barrier(0)
; template <class Epi, class Sched, bool ALIGN_EPI = false, bool SP2 = false>
; __device__ __forceinline__ void gemm_phase(PG8_LAS unsigned char* lds, const Gemm g, const Sched& S, const Epi& E) {
;     ...
;             PG8_LDB(B0, 0, 0); PG8_LDB(B1, 0, 1); PG8_SCHED; PG8_LDA(At, 0, 0); PG8_STAGE(PG8_SA(1, 1), a1 + hstepA, voffA);
;             PG8_WAIT_V(8); PG8_WAIT_L(0); PG8_BAR; PG8_MMA(0, 0, At, B0); PG8_MMA(0, 1, At, B1); PG8_BAR; PG8_SCHED;
;             PG8_LDA(At, 0, 1); PG8_STAGE(PG8_SB(0, 0), b2, voffB); PG8_STAGE(PG8_SB(0, 1), b2 + hstepB, voffB); PG8_STAGE(PG8_SA(0, 0), a2, voffA);
;             PG8_WAIT_V(8); PG8_WAIT_L(0); PG8_BAR; PG8_MMA(1, 0, At, B0); PG8_MMA(1, 1, At, B1); PG8_BAR; PG8_SCHED;
.LBB0_2662:
	s_add_u32 s8, s50, 0xfff80080
	s_addc_u32 s9, s51, -1
	s_add_i32 s14, 0, 0x10000
	s_cmp_eq_u32 s70, 28
	s_cselect_b32 s57, s4, s9
	s_cselect_b32 s56, s5, s8
	v_add_u32_e32 v151, s14, v145
	s_cselect_b32 s53, s6, s45
	s_cselect_b32 s52, s7, s43
	s_add_i32 s15, 0, 0x14000
	ds_read_b128 v[174:177], v151
	ds_read_b128 v[178:181], v151 offset:1024
	ds_read_b128 v[182:185], v151 offset:2048
	ds_read_b128 v[186:189], v151 offset:3072
	v_add_u32_e32 v151, s15, v145
	ds_read_b128 v[190:193], v151
	ds_read_b128 v[194:197], v151 offset:1024
	ds_read_b128 v[208:211], v151 offset:2048
	ds_read_b128 v[212:215], v151 offset:3072
	v_lshl_add_u64 v[156:157], s[50:51], 0, v[138:139]
	s_add_i32 m0, s77, 0xc000
	ds_read_b128 v[216:219], v149
	ds_read_b128 v[220:223], v149 offset:1024
	ds_read_b128 v[224:227], v149 offset:2048
	ds_read_b128 v[228:231], v149 offset:3072
	ds_read_b128 v[232:235], v149 offset:4096
	ds_read_b128 v[236:239], v149 offset:5120
	ds_read_b128 v[240:243], v149 offset:6144
	ds_read_b128 v[244:247], v149 offset:7168
	global_load_lds_dwordx4 v[156:157], off
	v_lshl_add_u64 v[156:157], s[50:51], 0, v[140:141]
	s_add_i32 m0, s77, 0xe000
	s_nop 0
	global_load_lds_dwordx4 v[156:157], off
	s_waitcnt vmcnt(8)
	s_waitcnt lgkmcnt(0)
	s_barrier
	s_waitcnt lgkmcnt(0)
	v_mfma_f32_16x16x32_bf16 v[128:131], v[174:177], v[216:219], v[128:131]
	v_mfma_f32_16x16x32_bf16 v[124:127], v[182:185], v[216:219], v[124:127]
	v_mfma_f32_16x16x32_bf16 v[112:115], v[174:177], v[224:227], v[112:115]
	v_mfma_f32_16x16x32_bf16 v[108:111], v[182:185], v[224:227], v[108:111]
	v_mfma_f32_16x16x32_bf16 v[96:99], v[174:177], v[232:235], v[96:99]
	v_mfma_f32_16x16x32_bf16 v[92:95], v[182:185], v[232:235], v[92:95]
	v_mfma_f32_16x16x32_bf16 v[80:83], v[174:177], v[240:243], v[80:83]
	v_mfma_f32_16x16x32_bf16 v[76:79], v[182:185], v[240:243], v[76:79]
	v_mfma_f32_16x16x32_bf16 v[128:131], v[178:181], v[220:223], v[128:131]
	v_mfma_f32_16x16x32_bf16 v[124:127], v[186:189], v[220:223], v[124:127]
	v_mfma_f32_16x16x32_bf16 v[112:115], v[178:181], v[228:231], v[112:115]
	v_mfma_f32_16x16x32_bf16 v[108:111], v[186:189], v[228:231], v[108:111]
	v_mfma_f32_16x16x32_bf16 v[96:99], v[178:181], v[236:239], v[96:99]
	v_mfma_f32_16x16x32_bf16 v[92:95], v[186:189], v[236:239], v[92:95]
	v_mfma_f32_16x16x32_bf16 v[80:83], v[178:181], v[244:247], v[80:83]
	v_mfma_f32_16x16x32_bf16 v[76:79], v[186:189], v[244:247], v[76:79]
	v_mfma_f32_16x16x32_bf16 v[120:123], v[190:193], v[216:219], v[120:123]
	v_mfma_f32_16x16x32_bf16 v[116:119], v[208:211], v[216:219], v[116:119]
	v_mfma_f32_16x16x32_bf16 v[104:107], v[190:193], v[224:227], v[104:107]
	v_mfma_f32_16x16x32_bf16 v[100:103], v[208:211], v[224:227], v[100:103]
	v_mfma_f32_16x16x32_bf16 v[88:91], v[190:193], v[232:235], v[88:91]
	v_mfma_f32_16x16x32_bf16 v[84:87], v[208:211], v[232:235], v[84:87]
	v_mfma_f32_16x16x32_bf16 v[72:75], v[190:193], v[240:243], v[72:75]
	v_mfma_f32_16x16x32_bf16 v[68:71], v[208:211], v[240:243], v[68:71]
	v_mfma_f32_16x16x32_bf16 v[120:123], v[194:197], v[220:223], v[120:123]
	v_mfma_f32_16x16x32_bf16 v[116:119], v[212:215], v[220:223], v[116:119]
	v_mfma_f32_16x16x32_bf16 v[104:107], v[194:197], v[228:231], v[104:107]
	v_mfma_f32_16x16x32_bf16 v[100:103], v[212:215], v[228:231], v[100:103]
	v_mfma_f32_16x16x32_bf16 v[88:91], v[194:197], v[236:239], v[88:91]
	v_mfma_f32_16x16x32_bf16 v[84:87], v[212:215], v[236:239], v[84:87]
	v_mfma_f32_16x16x32_bf16 v[72:75], v[194:197], v[244:247], v[72:75]
	v_mfma_f32_16x16x32_bf16 v[68:71], v[212:215], v[244:247], v[68:71]
	s_barrier
	s_add_i32 s8, s14, s66
	v_lshl_add_u64 v[156:157], s[52:53], 0, v[2:3]
	s_mov_b32 m0, s8
	ds_read_b128 v[216:219], v149 offset:16384
	ds_read_b128 v[220:223], v149 offset:17408
	ds_read_b128 v[224:227], v149 offset:18432
	ds_read_b128 v[228:231], v149 offset:19456
	ds_read_b128 v[232:235], v149 offset:20480
	ds_read_b128 v[236:239], v149 offset:21504
	ds_read_b128 v[240:243], v149 offset:22528
	ds_read_b128 v[244:247], v149 offset:23552
	global_load_lds_dwordx4 v[156:157], off
	s_add_i32 m0, s8, 0x2000
	s_add_u32 s8, s52, 0x80000
	v_lshl_add_u64 v[158:159], s[52:53], 0, v[132:133]
	s_addc_u32 s9, s53, 0
	s_add_i32 s14, s15, s66
	global_load_lds_dwordx4 v[158:159], off
	v_lshl_add_u64 v[164:165], s[8:9], 0, v[2:3]
	s_mov_b32 m0, s14
	v_lshl_add_u64 v[200:201], s[56:57], 0, v[134:135]
	global_load_lds_dwordx4 v[164:165], off
	v_lshl_add_u64 v[164:165], s[8:9], 0, v[132:133]
	s_add_i32 m0, s14, 0x2000
	s_nop 0
	global_load_lds_dwordx4 v[164:165], off
	v_lshl_add_u64 v[164:165], s[56:57], 0, v[136:137]
	s_mov_b32 m0, s77
	s_nop 0
	global_load_lds_dwordx4 v[164:165], off
	s_mov_b32 m0, s78
	s_nop 0
	global_load_lds_dwordx4 v[200:201], off
	s_waitcnt vmcnt(8)
	s_waitcnt lgkmcnt(0)
	s_barrier
; #define PG8_STAGE(bufoff, gbase, voff) do { _Pragma("unroll") for (int _i = 0; _i < 2; ++_i) \
;         __builtin_amdgcn_global_load_lds((const unsigned*)((const char*)(gbase) + (voff)[_i]), (PG8_LAS unsigned*)(lds + (bufoff) + ldsw + _i * 8192), 16, 0, 0); } while (0)
; #define PG8_LDA(dst, b, h) do { _Pragma("unroll") for (int m = 0; m < 4; ++m) _Pragma("unroll") for (int k = 0; k < 2; ++k) dst[m][k] = *(const PG8_LAS bf16x8*)(lds + PG8_SA(b, h) + aoff + m * 2048 + k * 1024); } while (0)
; #define PG8_LDB(dst, b, h) do { _Pragma("unroll") for (int n = 0; n < 2; ++n) _Pragma("unroll") for (int k = 0; k < 2; ++k) dst[n][k] = *(const PG8_LAS bf16x8*)(lds + PG8_SB(b, h) + boff + n * 2048 + k * 1024); } while (0)
; #define PG8_MMA(ai, bj, At, Bt) do { __builtin_amdgcn_s_setprio(1); _Pragma("unroll") for (int m = 0; m < 4; ++m) _Pragma("unroll") for (int n = 0; n < 2; ++n) _Pragma("unroll") for (int k = 0; k < 2; ++k) \
;         acc[ai][bj][m][n] = __builtin_amdgcn_mfma_f32_16x16x32_bf16(Bt[n][k], At[m][k], acc[ai][bj][m][n], 0, 0, 0); __builtin_amdgcn_s_setprio(0); } while (0)
; #define PG8_WAIT_V(n) asm volatile("s_waitcnt vmcnt(" #n ")" ::: "memory")
; #define PG8_WAIT_L(n) asm volatile("s_waitcnt lgkmcnt(" #n ")" ::: "memory")
; #define PG8_BAR __builtin_amdgcn_s_barrier()
; #define PG8_SCHED __builtin_amdgcn_sched_barrier(0)
; template <class Epi, class Sched, bool ALIGN_EPI = false, bool SP2 = false>
; __device__ __forceinline__ void gemm_phase(PG8_LAS unsigned char* lds, const Gemm g, const Sched& S, const Epi& E) {
;     ...
;             PG8_WAIT_V(8); PG8_WAIT_L(0); PG8_BAR; PG8_MMA(1, 0, At, B0); PG8_MMA(1, 1, At, B1); PG8_BAR; PG8_SCHED;
;             PG8_LDB(B0, 1, 0); PG8_LDB(B1, 1, 1); PG8_SCHED; PG8_LDA(At, 1, 0); PG8_STAGE(PG8_SA(0, 1), a2 + hstepA, voffA);
;             PG8_WAIT_V(8); PG8_WAIT_L(0); PG8_BAR; PG8_MMA(0, 0, At, B0); PG8_MMA(0, 1, At, B1); PG8_BAR; PG8_SCHED;
	s_waitcnt lgkmcnt(0)
	v_mfma_f32_16x16x32_bf16 v[64:67], v[174:177], v[216:219], v[64:67]
	v_mfma_f32_16x16x32_bf16 v[60:63], v[182:185], v[216:219], v[60:63]
	v_mfma_f32_16x16x32_bf16 v[48:51], v[174:177], v[224:227], v[48:51]
	v_mfma_f32_16x16x32_bf16 v[44:47], v[182:185], v[224:227], v[44:47]
	v_mfma_f32_16x16x32_bf16 v[32:35], v[174:177], v[232:235], v[32:35]
	v_mfma_f32_16x16x32_bf16 v[28:31], v[182:185], v[232:235], v[28:31]
	v_mfma_f32_16x16x32_bf16 v[16:19], v[174:177], v[240:243], v[16:19]
	v_mfma_f32_16x16x32_bf16 v[12:15], v[182:185], v[240:243], v[12:15]
	v_mfma_f32_16x16x32_bf16 v[64:67], v[178:181], v[220:223], v[64:67]
	v_mfma_f32_16x16x32_bf16 v[60:63], v[186:189], v[220:223], v[60:63]
	v_mfma_f32_16x16x32_bf16 v[48:51], v[178:181], v[228:231], v[48:51]
	v_mfma_f32_16x16x32_bf16 v[44:47], v[186:189], v[228:231], v[44:47]
	v_mfma_f32_16x16x32_bf16 v[32:35], v[178:181], v[236:239], v[32:35]
	v_mfma_f32_16x16x32_bf16 v[28:31], v[186:189], v[236:239], v[28:31]
	v_mfma_f32_16x16x32_bf16 v[16:19], v[178:181], v[244:247], v[16:19]
	v_mfma_f32_16x16x32_bf16 v[12:15], v[186:189], v[244:247], v[12:15]
	v_mfma_f32_16x16x32_bf16 v[56:59], v[190:193], v[216:219], v[56:59]
	v_mfma_f32_16x16x32_bf16 v[52:55], v[208:211], v[216:219], v[52:55]
	v_mfma_f32_16x16x32_bf16 v[40:43], v[190:193], v[224:227], v[40:43]
	v_mfma_f32_16x16x32_bf16 v[36:39], v[208:211], v[224:227], v[36:39]
	v_mfma_f32_16x16x32_bf16 v[24:27], v[190:193], v[232:235], v[24:27]
	v_mfma_f32_16x16x32_bf16 v[20:23], v[208:211], v[232:235], v[20:23]
	v_mfma_f32_16x16x32_bf16 v[8:11], v[190:193], v[240:243], v[8:11]
	v_mfma_f32_16x16x32_bf16 v[4:7], v[208:211], v[240:243], v[4:7]
	v_mfma_f32_16x16x32_bf16 v[56:59], v[194:197], v[220:223], v[56:59]
	v_mfma_f32_16x16x32_bf16 v[52:55], v[212:215], v[220:223], v[52:55]
	v_mfma_f32_16x16x32_bf16 v[40:43], v[194:197], v[228:231], v[40:43]
	v_mfma_f32_16x16x32_bf16 v[36:39], v[212:215], v[228:231], v[36:39]
	v_mfma_f32_16x16x32_bf16 v[24:27], v[194:197], v[236:239], v[24:27]
	v_mfma_f32_16x16x32_bf16 v[20:23], v[212:215], v[236:239], v[20:23]
	v_mfma_f32_16x16x32_bf16 v[8:11], v[194:197], v[244:247], v[8:11]
	v_mfma_f32_16x16x32_bf16 v[4:7], v[212:215], v[244:247], v[4:7]
	s_barrier
	s_add_i32 s14, 0, 0x18000
	v_add_u32_e32 v151, s14, v145
	s_add_i32 s15, 0, 0x1c000
	ds_read_b128 v[174:177], v151
	ds_read_b128 v[178:181], v151 offset:1024
	ds_read_b128 v[182:185], v151 offset:2048
	ds_read_b128 v[186:189], v151 offset:3072
	v_add_u32_e32 v151, s15, v145
	ds_read_b128 v[190:193], v151
	ds_read_b128 v[194:197], v151 offset:1024
	ds_read_b128 v[208:211], v151 offset:2048
	ds_read_b128 v[212:215], v151 offset:3072
	s_add_u32 s8, s56, 0x80000
	s_addc_u32 s9, s57, 0
	s_mov_b32 m0, s79
	v_lshl_add_u64 v[248:249], s[8:9], 0, v[136:137]
	ds_read_b128 v[216:219], v149 offset:32768
	ds_read_b128 v[220:223], v149 offset:33792
	ds_read_b128 v[224:227], v149 offset:34816
	ds_read_b128 v[228:231], v149 offset:35840
	ds_read_b128 v[232:235], v149 offset:36864
	ds_read_b128 v[236:239], v149 offset:37888
	ds_read_b128 v[240:243], v149 offset:38912
	ds_read_b128 v[244:247], v149 offset:39936
	global_load_lds_dwordx4 v[248:249], off
	v_lshl_add_u64 v[248:249], s[8:9], 0, v[134:135]
	s_mov_b32 m0, s80
	s_nop 0
	global_load_lds_dwordx4 v[248:249], off
	s_waitcnt vmcnt(8)
	s_waitcnt lgkmcnt(0)
	s_barrier
	s_waitcnt lgkmcnt(0)
	v_mfma_f32_16x16x32_bf16 v[128:131], v[174:177], v[216:219], v[128:131]
	v_mfma_f32_16x16x32_bf16 v[124:127], v[182:185], v[216:219], v[124:127]
	v_mfma_f32_16x16x32_bf16 v[112:115], v[174:177], v[224:227], v[112:115]
	v_mfma_f32_16x16x32_bf16 v[108:111], v[182:185], v[224:227], v[108:111]
	v_mfma_f32_16x16x32_bf16 v[96:99], v[174:177], v[232:235], v[96:99]
	v_mfma_f32_16x16x32_bf16 v[92:95], v[182:185], v[232:235], v[92:95]
	v_mfma_f32_16x16x32_bf16 v[80:83], v[174:177], v[240:243], v[80:83]
	v_mfma_f32_16x16x32_bf16 v[76:79], v[182:185], v[240:243], v[76:79]
	v_mfma_f32_16x16x32_bf16 v[128:131], v[178:181], v[220:223], v[128:131]
	v_mfma_f32_16x16x32_bf16 v[124:127], v[186:189], v[220:223], v[124:127]
	v_mfma_f32_16x16x32_bf16 v[112:115], v[178:181], v[228:231], v[112:115]
	v_mfma_f32_16x16x32_bf16 v[108:111], v[186:189], v[228:231], v[108:111]
	v_mfma_f32_16x16x32_bf16 v[96:99], v[178:181], v[236:239], v[96:99]
	v_mfma_f32_16x16x32_bf16 v[92:95], v[186:189], v[236:239], v[92:95]
	v_mfma_f32_16x16x32_bf16 v[80:83], v[178:181], v[244:247], v[80:83]
	v_mfma_f32_16x16x32_bf16 v[76:79], v[186:189], v[244:247], v[76:79]
	v_mfma_f32_16x16x32_bf16 v[120:123], v[190:193], v[216:219], v[120:123]
	v_mfma_f32_16x16x32_bf16 v[116:119], v[208:211], v[216:219], v[116:119]
	v_mfma_f32_16x16x32_bf16 v[104:107], v[190:193], v[224:227], v[104:107]
	v_mfma_f32_16x16x32_bf16 v[100:103], v[208:211], v[224:227], v[100:103]
	v_mfma_f32_16x16x32_bf16 v[88:91], v[190:193], v[232:235], v[88:91]
	v_mfma_f32_16x16x32_bf16 v[84:87], v[208:211], v[232:235], v[84:87]
	v_mfma_f32_16x16x32_bf16 v[72:75], v[190:193], v[240:243], v[72:75]
	v_mfma_f32_16x16x32_bf16 v[68:71], v[208:211], v[240:243], v[68:71]
	v_mfma_f32_16x16x32_bf16 v[120:123], v[194:197], v[220:223], v[120:123]
	v_mfma_f32_16x16x32_bf16 v[116:119], v[212:215], v[220:223], v[116:119]
	v_mfma_f32_16x16x32_bf16 v[104:107], v[194:197], v[228:231], v[104:107]
	v_mfma_f32_16x16x32_bf16 v[100:103], v[212:215], v[228:231], v[100:103]
	v_mfma_f32_16x16x32_bf16 v[88:91], v[194:197], v[236:239], v[88:91]
	v_mfma_f32_16x16x32_bf16 v[84:87], v[212:215], v[236:239], v[84:87]
	v_mfma_f32_16x16x32_bf16 v[72:75], v[194:197], v[244:247], v[72:75]
	v_mfma_f32_16x16x32_bf16 v[68:71], v[212:215], v[244:247], v[68:71]
	s_barrier
; #define PG8_BAR __builtin_amdgcn_s_barrier()
; template <class Epi, class Sched, bool ALIGN_EPI = false, bool SP2 = false>
; __device__ __forceinline__ void gemm_phase(PG8_LAS unsigned char* lds, const Gemm g, const Sched& S, const Epi& E) {
;     ...
;             PG8_LDA(At, 1, 1); PG8_STAGE(PG8_SB(1, 0), b3, voffB); PG8_STAGE(PG8_SB(1, 1), b3 + hstepB, voffB); PG8_STAGE(PG8_SA(1, 0), a3, voffA);
;             PG8_WAIT_V(8); PG8_WAIT_L(0); PG8_BAR; PG8_MMA(1, 0, At, B0); PG8_MMA(1, 1, At, B1); PG8_BAR; PG8_SCHED;
;             } else {
;             PG8_LDB(B0, 0, 0); PG8_SCHED; PG8_LDA(At, 0, 0); PG8_STAGE(PG8_SA(1, 1), a1 + hstepA, voffA);
;             PG8_WAIT_L(8); PG8_BAR; PG8_WAIT_L(0); PG8_MMA(0, 0, At, B0); PG8_BAR; PG8_SCHED;
;             PG8_LDB(B1, 0, 1); PG8_STAGE(PG8_SB(0, 0), b2, voffB);
;             PG8_BAR; PG8_WAIT_L(0); PG8_MMA(0, 1, At, B1); PG8_BAR;
;             PG8_LDA(At, 0, 1); PG8_STAGE(PG8_SA(0, 0), a2, voffA);
;             PG8_BAR; PG8_WAIT_L(0); PG8_MMA(1, 0, At, B0); PG8_BAR; PG8_SCHED;
;             PG8_STAGE(PG8_SB(0, 1), b2 + hstepB, voffB);
;             PG8_WAIT_V(6); PG8_BAR; PG8_MMA(1, 1, At, B1); PG8_BAR;
;             PG8_LDB(B0, 1, 0); PG8_SCHED; PG8_LDA(At, 1, 0); PG8_STAGE(PG8_SA(0, 1), a2 + hstepA, voffA);
;             PG8_WAIT_L(8); PG8_BAR; PG8_WAIT_L(0); PG8_MMA(0, 0, At, B0); PG8_BAR; PG8_SCHED;
;             PG8_LDB(B1, 1, 1); PG8_STAGE(PG8_SB(1, 0), b3, voffB);
;             PG8_BAR; PG8_WAIT_L(0); PG8_MMA(0, 1, At, B1); PG8_BAR;
;             PG8_LDA(At, 1, 1); PG8_STAGE(PG8_SA(1, 0), a3, voffA);
;             PG8_BAR; PG8_WAIT_L(0); PG8_MMA(1, 0, At, B0); PG8_BAR; PG8_SCHED;
;             PG8_STAGE(PG8_SB(1, 1), b3 + hstepB, voffB);
;             PG8_WAIT_V(6); PG8_BAR; PG8_MMA(1, 1, At, B1); PG8_BAR;
;             }
;         }
;         if constexpr (ALIGN_EPI) { if (wr == 0) PG8_BAR; }
;     __device__ __forceinline__ void operator()(const f32x4 (&acc)[2][2][4][2], const Unit& u, int wr, int wc, int fr, int fq, const float (&rsv)[2][4]) const {
;         const int row0 = u.pm * BM + wr * 64 + fr, col0 = u.pn * HALF + wc * 32 + 8 * fq;
; #pragma unroll
;         for (int ai = 0; ai < 2; ++ai)
; #pragma unroll
;             for (int m = 0; m < 4; ++m) { const int row = row0 + ai * HALF + m * 16; const float rs = rsv[ai][m];
;                 float g[8], sg[8]; f32x4 o[2];
; #pragma unroll
	s_add_i32 s8, s14, s66
	v_lshl_add_u64 v[156:157], v[156:157], 0, s[24:25]
	s_mov_b32 m0, s8
	ds_read_b128 v[216:219], v149 offset:49152
	ds_read_b128 v[220:223], v149 offset:50176
	ds_read_b128 v[224:227], v149 offset:51200
	ds_read_b128 v[228:231], v149 offset:52224
	ds_read_b128 v[232:235], v149 offset:53248
	ds_read_b128 v[236:239], v149 offset:54272
	ds_read_b128 v[240:243], v149 offset:55296
	ds_read_b128 v[244:247], v149 offset:56320
	global_load_lds_dwordx4 v[156:157], off
	s_add_i32 m0, s8, 0x2000
	s_add_u32 s8, s52, 0x80080
	v_lshl_add_u64 v[156:157], v[158:159], 0, s[24:25]
	s_addc_u32 s9, s53, 0
	s_add_i32 s14, s15, s66
	global_load_lds_dwordx4 v[156:157], off
	v_lshl_add_u64 v[156:157], s[8:9], 0, v[2:3]
	s_mov_b32 m0, s14
	s_nop 0
	global_load_lds_dwordx4 v[156:157], off
	v_lshl_add_u64 v[156:157], s[8:9], 0, v[132:133]
	s_add_i32 m0, s14, 0x2000
	s_nop 0
	global_load_lds_dwordx4 v[156:157], off
	v_lshl_add_u64 v[156:157], v[164:165], 0, s[24:25]
	s_mov_b32 m0, s81
	s_nop 0
	global_load_lds_dwordx4 v[156:157], off
	v_lshl_add_u64 v[156:157], v[200:201], 0, s[24:25]
	s_mov_b32 m0, s82
	s_nop 0
	global_load_lds_dwordx4 v[156:157], off
	s_waitcnt vmcnt(8)
	s_waitcnt lgkmcnt(0)
	s_barrier
	s_waitcnt lgkmcnt(0)
	v_mfma_f32_16x16x32_bf16 v[64:67], v[174:177], v[216:219], v[64:67]
	v_mfma_f32_16x16x32_bf16 v[60:63], v[182:185], v[216:219], v[60:63]
	v_mfma_f32_16x16x32_bf16 v[48:51], v[174:177], v[224:227], v[48:51]
	v_mfma_f32_16x16x32_bf16 v[44:47], v[182:185], v[224:227], v[44:47]
	v_mfma_f32_16x16x32_bf16 v[32:35], v[174:177], v[232:235], v[32:35]
	v_mfma_f32_16x16x32_bf16 v[28:31], v[182:185], v[232:235], v[28:31]
	v_mfma_f32_16x16x32_bf16 v[16:19], v[174:177], v[240:243], v[16:19]
	v_mfma_f32_16x16x32_bf16 v[12:15], v[182:185], v[240:243], v[12:15]
	v_mfma_f32_16x16x32_bf16 v[64:67], v[178:181], v[220:223], v[64:67]
	v_mfma_f32_16x16x32_bf16 v[60:63], v[186:189], v[220:223], v[60:63]
	v_mfma_f32_16x16x32_bf16 v[48:51], v[178:181], v[228:231], v[48:51]
	v_mfma_f32_16x16x32_bf16 v[44:47], v[186:189], v[228:231], v[44:47]
	v_mfma_f32_16x16x32_bf16 v[32:35], v[178:181], v[236:239], v[32:35]
	v_mfma_f32_16x16x32_bf16 v[28:31], v[186:189], v[236:239], v[28:31]
	v_mfma_f32_16x16x32_bf16 v[16:19], v[178:181], v[244:247], v[16:19]
	v_mfma_f32_16x16x32_bf16 v[12:15], v[186:189], v[244:247], v[12:15]
	v_mfma_f32_16x16x32_bf16 v[56:59], v[190:193], v[216:219], v[56:59]
	v_mfma_f32_16x16x32_bf16 v[52:55], v[208:211], v[216:219], v[52:55]
	v_mfma_f32_16x16x32_bf16 v[40:43], v[190:193], v[224:227], v[40:43]
	v_mfma_f32_16x16x32_bf16 v[36:39], v[208:211], v[224:227], v[36:39]
	v_mfma_f32_16x16x32_bf16 v[24:27], v[190:193], v[232:235], v[24:27]
	v_mfma_f32_16x16x32_bf16 v[20:23], v[208:211], v[232:235], v[20:23]
	v_mfma_f32_16x16x32_bf16 v[8:11], v[190:193], v[240:243], v[8:11]
	v_mfma_f32_16x16x32_bf16 v[4:7], v[208:211], v[240:243], v[4:7]
	v_mfma_f32_16x16x32_bf16 v[56:59], v[194:197], v[220:223], v[56:59]
	v_mfma_f32_16x16x32_bf16 v[52:55], v[212:215], v[220:223], v[52:55]
	v_mfma_f32_16x16x32_bf16 v[40:43], v[194:197], v[228:231], v[40:43]
	v_mfma_f32_16x16x32_bf16 v[36:39], v[212:215], v[228:231], v[36:39]
	v_mfma_f32_16x16x32_bf16 v[24:27], v[194:197], v[236:239], v[24:27]
	v_mfma_f32_16x16x32_bf16 v[20:23], v[212:215], v[236:239], v[20:23]
	v_mfma_f32_16x16x32_bf16 v[8:11], v[194:197], v[244:247], v[8:11]
	v_mfma_f32_16x16x32_bf16 v[4:7], v[212:215], v[244:247], v[4:7]
	s_barrier
	s_add_i32 s70, s70, 2
	s_add_u32 s50, s50, 0x100
	s_addc_u32 s51, s51, 0
	s_add_u32 s43, s43, 0x100
	s_addc_u32 s45, s45, 0
	s_cmp_gt_u32 s70, 29
	s_cbranch_scc0 .LBB0_2662
	s_and_b64 vcc, exec, s[40:41]
	s_cbranch_vccz .LBB0_2665
	s_barrier
.LBB0_2665:
	s_setprio 0
	v_mov_b32_e32 v156, v120
	v_mov_b32_e32 v157, v128
	v_mov_b32_e32 v128, v121
	v_mov_b32_e32 v120, v122
	v_mov_b32_e32 v121, v130
	v_pk_mul_f32 v[158:159], v[172:173], v[120:121] op_sel_hi:[0,1]
	v_mov_b32_e32 v121, v124
	v_mov_b32_e32 v124, v117
	v_mov_b32_e32 v130, v123
	v_mov_b32_e32 v120, v116
	v_pk_mul_f32 v[116:117], v[172:173], v[124:125] op_sel_hi:[0,1]
	v_pk_mul_f32 v[156:157], v[172:173], v[156:157] op_sel_hi:[0,1]
	v_pk_mul_f32 v[128:129], v[172:173], v[128:129] op_sel_hi:[0,1]
	v_pk_mul_f32 v[122:123], v[172:173], v[130:131] op_sel_hi:[0,1]
	v_pk_mul_f32 v[130:131], v[172:173], v[120:121] op_sel_hi:[0,1]
	v_mul_f32_e32 v173, 0xbfb8aa3b, v117
	v_mov_b32_e32 v120, v118
	v_mov_b32_e32 v121, v126
	v_mov_b32_e32 v126, v119
	v_pk_mul_f32 v[124:125], v[172:173], v[120:121] op_sel_hi:[0,1]
	v_pk_mul_f32 v[118:119], v[172:173], v[126:127] op_sel_hi:[0,1]
	v_mul_f32_e32 v151, 0xbfb8aa3b, v157
	v_mul_f32_e32 v153, 0xbfb8aa3b, v129
	v_mul_f32_e32 v155, 0xbfb8aa3b, v159
	v_mul_f32_e32 v164, 0xbfb8aa3b, v123
	v_mul_f32_e32 v165, 0xbfb8aa3b, v131
	v_mul_f32_e32 v120, 0xbfb8aa3b, v125
	v_mul_f32_e32 v121, 0xbfb8aa3b, v119
	s_andn2_b64 vcc, exec, s[38:39]
	v_exp_f32_e32 v126, v151
	v_exp_f32_e32 v127, v153
	v_exp_f32_e32 v151, v155
	v_exp_f32_e32 v153, v164
	v_exp_f32_e32 v155, v165
	v_exp_f32_e32 v164, v173
	v_exp_f32_e32 v120, v120
	v_exp_f32_e32 v121, v121
	s_movk_i32 s70, 0x80
	v_add_f32_e32 v126, 1.0, v126
	v_add_f32_e32 v127, 1.0, v127
	v_add_f32_e32 v151, 1.0, v151
	v_add_f32_e32 v153, 1.0, v153
	v_add_f32_e32 v155, 1.0, v155
	v_add_f32_e32 v164, 1.0, v164
	v_add_f32_e32 v120, 1.0, v120
	v_add_f32_e32 v121, 1.0, v121
	s_nop 0
	v_rcp_f32_e32 v165, v126
	v_rcp_f32_e32 v172, v127
	v_rcp_f32_e32 v151, v151
	v_rcp_f32_e32 v153, v153
	v_rcp_f32_e32 v155, v155
	v_rcp_f32_e32 v164, v164
	v_rcp_f32_e32 v173, v120
	v_rcp_f32_e32 v121, v121
	v_lshl_or_b32 v126, s37, 7, v147
	v_mul_f32_e32 v117, v117, v164
; #define SG8_PIN() asm volatile("" : "+v"(e[0]), "+v"(e[1]), "+v"(e[2]), "+v"(e[3]), "+v"(e[4]), "+v"(e[5]), "+v"(e[6]), "+v"(e[7]))
; __device__ __forceinline__ u32x4 pack8(f32x4 a, f32x4 b) { u32x4 w; w.x = cvt_pk_bf16(a[0], a[1]); w.y = cvt_pk_bf16(a[2], a[3]); w.z = cvt_pk_bf16(b[0], b[1]); w.w = cvt_pk_bf16(b[2], b[3]); return w; }
; __device__ __forceinline__ void sigmoid8(const float (&x)[8], float (&sg)[8]) {
;     float e[8];
;     ...
; #pragma unroll
;     for (int j = 0; j < 8; ++j) e[j] = x[j] * -1.4426950408889634f;
;     SG8_PIN();
; #pragma unroll
;     for (int j = 0; j < 8; ++j) e[j] = __builtin_amdgcn_exp2f(e[j]);
;     SG8_PIN();
; #pragma unroll
;     for (int j = 0; j < 8; ++j) e[j] = 1.0f + e[j];
;     SG8_PIN();
; #pragma unroll
;     for (int j = 0; j < 8; ++j) e[j] = __builtin_amdgcn_rcpf(e[j]);
;     SG8_PIN();
; #pragma unroll
;     for (int j = 0; j < 8; ++j) sg[j] = e[j];
;     ...
; }
;     __device__ __forceinline__ void operator()(const f32x4 (&acc)[2][2][4][2], const Unit& u, int wr, int wc, int fr, int fq, const float (&rsv)[2][4]) const {
;         const int row0 = u.pm * BM + wr * 64 + fr, col0 = u.pn * HALF + wc * 32 + 8 * fq;
; #pragma unroll
;         for (int ai = 0; ai < 2; ++ai)
; #pragma unroll
;             for (int m = 0; m < 4; ++m) { const int row = row0 + ai * HALF + m * 16; const float rs = rsv[ai][m];
;                 float g[8], sg[8]; f32x4 o[2];
; #pragma unroll
;                 for (int j = 0; j < 8; ++j) g[j] = acc[ai][0][m][j >> 2][j & 3] * rs;
;                 sigmoid8(g, sg);
; #pragma unroll
;                 for (int j = 0; j < 8; ++j) o[j >> 2][j & 3] = (g[j] * sg[j]) * (acc[ai][1][m][j >> 2][j & 3] * rs);
;                 *(u32x4*)(H + (size_t)row * FF + col0) = pack8(o[0], o[1]); }
	v_mul_f32_e32 v129, v129, v172
	v_mul_f32_e32 v123, v123, v153
	v_mul_f32_e32 v116, v116, v117
	v_mul_f32_e32 v117, v125, v173
	v_mul_f32_e32 v157, v157, v165
	v_mul_f32_e32 v128, v128, v129
	v_mul_f32_e32 v129, v159, v151
	v_mul_f32_e32 v123, v122, v123
	v_mul_f32_e32 v122, v131, v155
	v_mul_f32_e32 v117, v124, v117
	v_mul_f32_e32 v119, v119, v121
	v_lshl_add_u32 v120, s36, 8, v143
	v_ashrrev_i32_e32 v127, 31, v126
	v_mul_f32_e32 v156, v156, v157
	v_mul_f32_e32 v129, v158, v129
	v_mul_f32_e32 v130, v130, v122
	v_mul_f32_e32 v118, v118, v119
	v_cvt_pk_bf16_f32 v122, v156, v128
	v_cvt_pk_bf16_f32 v123, v129, v123
	v_cvt_pk_bf16_f32 v124, v130, v116
	v_cvt_pk_bf16_f32 v125, v117, v118
	v_mov_b64_e32 v[116:117], s[0:1]
	v_mad_i64_i32 v[128:129], s[4:5], v120, s29, v[116:117]
	v_lshlrev_b64 v[118:119], 1, v[126:127]
	v_lshl_add_u64 v[126:127], v[128:129], 0, v[118:119]
	global_store_dwordx4 v[126:127], v[122:125], off
	s_mov_b64 s[36:37], -1
	s_nop 0
	v_mov_b32_e32 v123, v112
	v_mov_b32_e32 v112, v105
	v_mov_b32_e32 v122, v104
	v_pk_mul_f32 v[104:105], v[154:155], v[112:113] op_sel_hi:[0,1]
	v_mov_b32_e32 v113, v114
	v_mov_b32_e32 v114, v107
	v_mov_b32_e32 v112, v106
	v_pk_mul_f32 v[106:107], v[154:155], v[114:115] op_sel_hi:[0,1]
	v_mov_b32_e32 v115, v108
	v_mov_b32_e32 v108, v101
	v_mov_b32_e32 v114, v100
	v_pk_mul_f32 v[100:101], v[154:155], v[108:109] op_sel_hi:[0,1]
	v_mov_b32_e32 v108, v102
	v_mov_b32_e32 v109, v110
	v_mov_b32_e32 v110, v103
	v_pk_mul_f32 v[122:123], v[154:155], v[122:123] op_sel_hi:[0,1]
	v_pk_mul_f32 v[112:113], v[154:155], v[112:113] op_sel_hi:[0,1]
	v_pk_mul_f32 v[114:115], v[154:155], v[114:115] op_sel_hi:[0,1]
	v_pk_mul_f32 v[108:109], v[154:155], v[108:109] op_sel_hi:[0,1]
	v_pk_mul_f32 v[102:103], v[154:155], v[110:111] op_sel_hi:[0,1]
	v_mul_f32_e32 v121, 0xbfb8aa3b, v123
	v_mul_f32_e32 v124, 0xbfb8aa3b, v105
	v_mul_f32_e32 v125, 0xbfb8aa3b, v113
	v_mul_f32_e32 v126, 0xbfb8aa3b, v107
	v_mul_f32_e32 v127, 0xbfb8aa3b, v115
	v_mul_f32_e32 v128, 0xbfb8aa3b, v101
	v_mul_f32_e32 v129, 0xbfb8aa3b, v109
	v_mul_f32_e32 v110, 0xbfb8aa3b, v103
	s_nop 0
	v_exp_f32_e32 v111, v121
	v_exp_f32_e32 v121, v124
	v_exp_f32_e32 v124, v125
	v_exp_f32_e32 v125, v126
	v_exp_f32_e32 v126, v127
	v_exp_f32_e32 v127, v128
	v_exp_f32_e32 v128, v129
	v_exp_f32_e32 v110, v110
	s_nop 0
	v_add_f32_e32 v111, 1.0, v111
	v_add_f32_e32 v121, 1.0, v121
	v_add_f32_e32 v124, 1.0, v124
	v_add_f32_e32 v125, 1.0, v125
	v_add_f32_e32 v126, 1.0, v126
	v_add_f32_e32 v127, 1.0, v127
	v_add_f32_e32 v128, 1.0, v128
	v_add_f32_e32 v110, 1.0, v110
	s_nop 0
	v_rcp_f32_e32 v111, v111
	v_rcp_f32_e32 v121, v121
	v_rcp_f32_e32 v124, v124
	v_rcp_f32_e32 v125, v125
	v_rcp_f32_e32 v126, v126
	v_rcp_f32_e32 v127, v127
	v_rcp_f32_e32 v128, v128
	v_rcp_f32_e32 v110, v110
	s_nop 0
	v_mul_f32_e32 v105, v105, v121
	v_mul_f32_e32 v104, v104, v105
	v_mul_f32_e32 v105, v113, v124
	v_mul_f32_e32 v101, v101, v127
	v_mul_f32_e32 v105, v112, v105
	v_mul_f32_e32 v112, v100, v101
	v_mul_f32_e32 v100, v109, v128
	v_mul_f32_e32 v111, v123, v111
	v_mul_f32_e32 v107, v107, v125
	v_mul_f32_e32 v108, v108, v100
	v_mul_f32_e32 v100, v103, v110
	v_or_b32_e32 v109, 16, v120
	v_mul_f32_e32 v111, v122, v111
	v_mul_f32_e32 v106, v106, v107
	v_mul_f32_e32 v103, v102, v100
	v_cvt_pk_bf16_f32 v100, v111, v104
	v_cvt_pk_bf16_f32 v101, v105, v106
	v_mad_i64_i32 v[104:105], s[4:5], v109, s29, v[116:117]
	v_mul_f32_e32 v107, v115, v126
	v_lshl_add_u64 v[104:105], v[104:105], 0, v[118:119]
	v_mul_f32_e32 v107, v114, v107
	v_cvt_pk_bf16_f32 v102, v107, v112
	v_cvt_pk_bf16_f32 v103, v108, v103
	global_store_dwordx4 v[104:105], v[100:103], off
	s_nop 1
	v_mov_b32_e32 v101, v96
	v_mov_b32_e32 v96, v89
	v_mov_b32_e32 v100, v88
	v_pk_mul_f32 v[88:89], v[152:153], v[96:97] op_sel_hi:[0,1]
	v_mov_b32_e32 v97, v98
	v_mov_b32_e32 v98, v91
	v_mov_b32_e32 v96, v90
	v_pk_mul_f32 v[90:91], v[152:153], v[98:99] op_sel_hi:[0,1]
	v_mov_b32_e32 v99, v92
	v_mov_b32_e32 v92, v85
	v_mov_b32_e32 v98, v84
	v_pk_mul_f32 v[84:85], v[152:153], v[92:93] op_sel_hi:[0,1]
	v_mov_b32_e32 v92, v86
	v_mov_b32_e32 v93, v94
	v_mov_b32_e32 v94, v87
	v_pk_mul_f32 v[100:101], v[152:153], v[100:101] op_sel_hi:[0,1]
	v_pk_mul_f32 v[96:97], v[152:153], v[96:97] op_sel_hi:[0,1]
	v_pk_mul_f32 v[98:99], v[152:153], v[98:99] op_sel_hi:[0,1]
	v_pk_mul_f32 v[92:93], v[152:153], v[92:93] op_sel_hi:[0,1]
	v_pk_mul_f32 v[86:87], v[152:153], v[94:95] op_sel_hi:[0,1]
	v_mul_f32_e32 v102, 0xbfb8aa3b, v101
	v_mul_f32_e32 v103, 0xbfb8aa3b, v89
	v_mul_f32_e32 v104, 0xbfb8aa3b, v97
	v_mul_f32_e32 v105, 0xbfb8aa3b, v91
	v_mul_f32_e32 v106, 0xbfb8aa3b, v99
	v_mul_f32_e32 v107, 0xbfb8aa3b, v85
	v_mul_f32_e32 v108, 0xbfb8aa3b, v93
	v_mul_f32_e32 v94, 0xbfb8aa3b, v87
	s_nop 0
	v_exp_f32_e32 v95, v102
	v_exp_f32_e32 v102, v103
	v_exp_f32_e32 v103, v104
	v_exp_f32_e32 v104, v105
	v_exp_f32_e32 v105, v106
	v_exp_f32_e32 v106, v107
	v_exp_f32_e32 v107, v108
	v_exp_f32_e32 v94, v94
	s_nop 0
	v_add_f32_e32 v95, 1.0, v95
	v_add_f32_e32 v102, 1.0, v102
	v_add_f32_e32 v103, 1.0, v103
	v_add_f32_e32 v104, 1.0, v104
	v_add_f32_e32 v105, 1.0, v105
	v_add_f32_e32 v106, 1.0, v106
	v_add_f32_e32 v107, 1.0, v107
	v_add_f32_e32 v94, 1.0, v94
	s_nop 0
	v_rcp_f32_e32 v95, v95
	v_rcp_f32_e32 v102, v102
	v_rcp_f32_e32 v103, v103
	v_rcp_f32_e32 v104, v104
	v_rcp_f32_e32 v105, v105
	v_rcp_f32_e32 v106, v106
	v_rcp_f32_e32 v107, v107
	v_rcp_f32_e32 v94, v94
	s_nop 0
	v_mul_f32_e32 v89, v89, v102
	v_mul_f32_e32 v88, v88, v89
	v_mul_f32_e32 v89, v97, v103
	v_mul_f32_e32 v85, v85, v106
	v_mul_f32_e32 v89, v96, v89
	v_mul_f32_e32 v96, v84, v85
	v_mul_f32_e32 v84, v93, v107
; #define SG8_PIN() asm volatile("" : "+v"(e[0]), "+v"(e[1]), "+v"(e[2]), "+v"(e[3]), "+v"(e[4]), "+v"(e[5]), "+v"(e[6]), "+v"(e[7]))
; __device__ __forceinline__ u32x4 pack8(f32x4 a, f32x4 b) { u32x4 w; w.x = cvt_pk_bf16(a[0], a[1]); w.y = cvt_pk_bf16(a[2], a[3]); w.z = cvt_pk_bf16(b[0], b[1]); w.w = cvt_pk_bf16(b[2], b[3]); return w; }
; __device__ __forceinline__ void sigmoid8(const float (&x)[8], float (&sg)[8]) {
;     float e[8];
;     ...
; #pragma unroll
;     for (int j = 0; j < 8; ++j) e[j] = x[j] * -1.4426950408889634f;
;     SG8_PIN();
; #pragma unroll
;     for (int j = 0; j < 8; ++j) e[j] = __builtin_amdgcn_exp2f(e[j]);
;     SG8_PIN();
; #pragma unroll
;     for (int j = 0; j < 8; ++j) e[j] = 1.0f + e[j];
;     SG8_PIN();
; #pragma unroll
;     for (int j = 0; j < 8; ++j) e[j] = __builtin_amdgcn_rcpf(e[j]);
;     SG8_PIN();
; #pragma unroll
;     for (int j = 0; j < 8; ++j) sg[j] = e[j];
;     ...
; }
;     __device__ __forceinline__ void operator()(const f32x4 (&acc)[2][2][4][2], const Unit& u, int wr, int wc, int fr, int fq, const float (&rsv)[2][4]) const {
;         const int row0 = u.pm * BM + wr * 64 + fr, col0 = u.pn * HALF + wc * 32 + 8 * fq;
; #pragma unroll
;         for (int ai = 0; ai < 2; ++ai)
; #pragma unroll
;             for (int m = 0; m < 4; ++m) { const int row = row0 + ai * HALF + m * 16; const float rs = rsv[ai][m];
;                 float g[8], sg[8]; f32x4 o[2];
; #pragma unroll
;                 for (int j = 0; j < 8; ++j) g[j] = acc[ai][0][m][j >> 2][j & 3] * rs;
;                 sigmoid8(g, sg);
; #pragma unroll
;                 for (int j = 0; j < 8; ++j) o[j >> 2][j & 3] = (g[j] * sg[j]) * (acc[ai][1][m][j >> 2][j & 3] * rs);
;                 *(u32x4*)(H + (size_t)row * FF + col0) = pack8(o[0], o[1]); }
	v_mul_f32_e32 v95, v101, v95
	v_mul_f32_e32 v91, v91, v104
	v_mul_f32_e32 v92, v92, v84
	v_mul_f32_e32 v84, v87, v94
	v_or_b32_e32 v93, 32, v120
	v_mul_f32_e32 v95, v100, v95
	v_mul_f32_e32 v90, v90, v91
	v_mul_f32_e32 v87, v86, v84
	v_cvt_pk_bf16_f32 v84, v95, v88
	v_cvt_pk_bf16_f32 v85, v89, v90
	v_mad_i64_i32 v[88:89], s[4:5], v93, s29, v[116:117]
	v_mul_f32_e32 v91, v99, v105
	v_lshl_add_u64 v[88:89], v[88:89], 0, v[118:119]
	v_mul_f32_e32 v91, v98, v91
	v_cvt_pk_bf16_f32 v86, v91, v96
	v_cvt_pk_bf16_f32 v87, v92, v87
	global_store_dwordx4 v[88:89], v[84:87], off
	s_nop 1
	v_mov_b32_e32 v85, v80
	v_mov_b32_e32 v80, v73
	v_mov_b32_e32 v84, v72
	v_pk_mul_f32 v[72:73], v[150:151], v[80:81] op_sel_hi:[0,1]
	v_mov_b32_e32 v81, v82
	v_mov_b32_e32 v82, v75
	v_mov_b32_e32 v80, v74
	v_pk_mul_f32 v[74:75], v[150:151], v[82:83] op_sel_hi:[0,1]
	v_mov_b32_e32 v83, v76
	v_mov_b32_e32 v76, v69
	v_mov_b32_e32 v82, v68
	v_pk_mul_f32 v[68:69], v[150:151], v[76:77] op_sel_hi:[0,1]
	v_mov_b32_e32 v76, v70
	v_mov_b32_e32 v77, v78
	v_mov_b32_e32 v78, v71
	v_pk_mul_f32 v[84:85], v[150:151], v[84:85] op_sel_hi:[0,1]
	v_pk_mul_f32 v[80:81], v[150:151], v[80:81] op_sel_hi:[0,1]
	v_pk_mul_f32 v[82:83], v[150:151], v[82:83] op_sel_hi:[0,1]
	v_pk_mul_f32 v[76:77], v[150:151], v[76:77] op_sel_hi:[0,1]
	v_pk_mul_f32 v[70:71], v[150:151], v[78:79] op_sel_hi:[0,1]
	v_mul_f32_e32 v86, 0xbfb8aa3b, v85
	v_mul_f32_e32 v87, 0xbfb8aa3b, v73
	v_mul_f32_e32 v88, 0xbfb8aa3b, v81
	v_mul_f32_e32 v89, 0xbfb8aa3b, v75
	v_mul_f32_e32 v90, 0xbfb8aa3b, v83
	v_mul_f32_e32 v91, 0xbfb8aa3b, v69
	v_mul_f32_e32 v92, 0xbfb8aa3b, v77
	v_mul_f32_e32 v78, 0xbfb8aa3b, v71
	s_nop 0
	v_exp_f32_e32 v79, v86
	v_exp_f32_e32 v86, v87
	v_exp_f32_e32 v87, v88
	v_exp_f32_e32 v88, v89
	v_exp_f32_e32 v89, v90
	v_exp_f32_e32 v90, v91
	v_exp_f32_e32 v91, v92
	v_exp_f32_e32 v78, v78
	s_nop 0
	v_add_f32_e32 v79, 1.0, v79
	v_add_f32_e32 v86, 1.0, v86
	v_add_f32_e32 v87, 1.0, v87
	v_add_f32_e32 v88, 1.0, v88
	v_add_f32_e32 v89, 1.0, v89
	v_add_f32_e32 v90, 1.0, v90
	v_add_f32_e32 v91, 1.0, v91
	v_add_f32_e32 v78, 1.0, v78
	s_nop 0
	v_rcp_f32_e32 v79, v79
	v_rcp_f32_e32 v86, v86
	v_rcp_f32_e32 v87, v87
	v_rcp_f32_e32 v88, v88
	v_rcp_f32_e32 v89, v89
	v_rcp_f32_e32 v90, v90
	v_rcp_f32_e32 v91, v91
	v_rcp_f32_e32 v78, v78
	s_nop 0
	v_mul_f32_e32 v73, v73, v86
	v_mul_f32_e32 v72, v72, v73
	v_mul_f32_e32 v73, v81, v87
	v_mul_f32_e32 v69, v69, v90
	v_mul_f32_e32 v73, v80, v73
	v_mul_f32_e32 v80, v68, v69
	v_mul_f32_e32 v68, v77, v91
	v_mul_f32_e32 v79, v85, v79
	v_mul_f32_e32 v75, v75, v88
	v_mul_f32_e32 v76, v76, v68
	v_mul_f32_e32 v68, v71, v78
	v_or_b32_e32 v77, 48, v120
	v_mul_f32_e32 v79, v84, v79
	v_mul_f32_e32 v74, v74, v75
	v_mul_f32_e32 v71, v70, v68
	v_cvt_pk_bf16_f32 v68, v79, v72
	v_cvt_pk_bf16_f32 v69, v73, v74
	v_mad_i64_i32 v[72:73], s[4:5], v77, s29, v[116:117]
	v_mul_f32_e32 v75, v83, v89
	v_lshl_add_u64 v[72:73], v[72:73], 0, v[118:119]
	v_mul_f32_e32 v75, v82, v75
	v_cvt_pk_bf16_f32 v70, v75, v80
	v_cvt_pk_bf16_f32 v71, v76, v71
	global_store_dwordx4 v[72:73], v[68:71], off
	s_nop 1
	v_mov_b32_e32 v69, v64
	v_mov_b32_e32 v64, v57
	v_mov_b32_e32 v68, v56
	v_pk_mul_f32 v[56:57], v[148:149], v[64:65] op_sel_hi:[0,1]
	v_mov_b32_e32 v65, v66
	v_mov_b32_e32 v66, v59
	v_mov_b32_e32 v64, v58
	v_pk_mul_f32 v[58:59], v[148:149], v[66:67] op_sel_hi:[0,1]
	v_mov_b32_e32 v67, v60
	v_mov_b32_e32 v60, v53
	v_mov_b32_e32 v66, v52
	v_pk_mul_f32 v[52:53], v[148:149], v[60:61] op_sel_hi:[0,1]
	v_mov_b32_e32 v60, v54
	v_mov_b32_e32 v61, v62
	v_mov_b32_e32 v62, v55
	v_pk_mul_f32 v[68:69], v[148:149], v[68:69] op_sel_hi:[0,1]
	v_pk_mul_f32 v[64:65], v[148:149], v[64:65] op_sel_hi:[0,1]
	v_pk_mul_f32 v[66:67], v[148:149], v[66:67] op_sel_hi:[0,1]
	v_pk_mul_f32 v[60:61], v[148:149], v[60:61] op_sel_hi:[0,1]
	v_pk_mul_f32 v[54:55], v[148:149], v[62:63] op_sel_hi:[0,1]
	v_mul_f32_e32 v70, 0xbfb8aa3b, v69
	v_mul_f32_e32 v71, 0xbfb8aa3b, v57
	v_mul_f32_e32 v72, 0xbfb8aa3b, v65
	v_mul_f32_e32 v73, 0xbfb8aa3b, v59
	v_mul_f32_e32 v74, 0xbfb8aa3b, v67
	v_mul_f32_e32 v75, 0xbfb8aa3b, v53
	v_mul_f32_e32 v76, 0xbfb8aa3b, v61
	v_mul_f32_e32 v62, 0xbfb8aa3b, v55
	s_nop 0
	v_exp_f32_e32 v63, v70
	v_exp_f32_e32 v70, v71
	v_exp_f32_e32 v71, v72
	v_exp_f32_e32 v72, v73
	v_exp_f32_e32 v73, v74
	v_exp_f32_e32 v74, v75
	v_exp_f32_e32 v75, v76
	v_exp_f32_e32 v62, v62
	v_add_u32_e32 v76, 0x80, v120
	v_add_f32_e32 v63, 1.0, v63
	v_add_f32_e32 v70, 1.0, v70
	v_add_f32_e32 v71, 1.0, v71
	v_add_f32_e32 v72, 1.0, v72
	v_add_f32_e32 v73, 1.0, v73
	v_add_f32_e32 v74, 1.0, v74
	v_add_f32_e32 v75, 1.0, v75
	v_add_f32_e32 v62, 1.0, v62
	s_nop 0
	v_rcp_f32_e32 v63, v63
	v_rcp_f32_e32 v70, v70
	v_rcp_f32_e32 v71, v71
	v_rcp_f32_e32 v72, v72
	v_rcp_f32_e32 v73, v73
	v_rcp_f32_e32 v74, v74
	v_rcp_f32_e32 v75, v75
	v_rcp_f32_e32 v62, v62
	s_nop 0
	v_mul_f32_e32 v57, v57, v70
	v_mul_f32_e32 v56, v56, v57
	v_mul_f32_e32 v57, v65, v71
	v_mul_f32_e32 v53, v53, v74
	v_mul_f32_e32 v57, v64, v57
	v_mul_f32_e32 v64, v52, v53
	v_mul_f32_e32 v52, v61, v75
	v_mul_f32_e32 v63, v69, v63
	v_mul_f32_e32 v59, v59, v72
	v_mul_f32_e32 v60, v60, v52
	v_mul_f32_e32 v52, v55, v62
	v_mul_f32_e32 v63, v68, v63
	v_mul_f32_e32 v58, v58, v59
	v_mul_f32_e32 v55, v54, v52
	v_cvt_pk_bf16_f32 v52, v63, v56
	v_cvt_pk_bf16_f32 v53, v57, v58
	v_mad_i64_i32 v[56:57], s[4:5], v76, s29, v[116:117]
	v_mul_f32_e32 v59, v67, v73
	v_lshl_add_u64 v[56:57], v[56:57], 0, v[118:119]
	v_mul_f32_e32 v59, v66, v59
	v_cvt_pk_bf16_f32 v54, v59, v64
	v_cvt_pk_bf16_f32 v55, v60, v55
	global_store_dwordx4 v[56:57], v[52:55], off
	s_nop 1
	v_mov_b32_e32 v53, v48
	v_mov_b32_e32 v48, v41
	v_mov_b32_e32 v52, v40
; #define SG8_PIN() asm volatile("" : "+v"(e[0]), "+v"(e[1]), "+v"(e[2]), "+v"(e[3]), "+v"(e[4]), "+v"(e[5]), "+v"(e[6]), "+v"(e[7]))
; __device__ __forceinline__ u32x4 pack8(f32x4 a, f32x4 b) { u32x4 w; w.x = cvt_pk_bf16(a[0], a[1]); w.y = cvt_pk_bf16(a[2], a[3]); w.z = cvt_pk_bf16(b[0], b[1]); w.w = cvt_pk_bf16(b[2], b[3]); return w; }
; __device__ __forceinline__ void sigmoid8(const float (&x)[8], float (&sg)[8]) {
;     float e[8];
;     ...
; #pragma unroll
;     for (int j = 0; j < 8; ++j) e[j] = x[j] * -1.4426950408889634f;
;     SG8_PIN();
; #pragma unroll
;     for (int j = 0; j < 8; ++j) e[j] = __builtin_amdgcn_exp2f(e[j]);
;     SG8_PIN();
; #pragma unroll
;     for (int j = 0; j < 8; ++j) e[j] = 1.0f + e[j];
;     SG8_PIN();
; #pragma unroll
;     for (int j = 0; j < 8; ++j) e[j] = __builtin_amdgcn_rcpf(e[j]);
;     SG8_PIN();
; #pragma unroll
;     for (int j = 0; j < 8; ++j) sg[j] = e[j];
;     ...
; }
;     __device__ __forceinline__ void operator()(const f32x4 (&acc)[2][2][4][2], const Unit& u, int wr, int wc, int fr, int fq, const float (&rsv)[2][4]) const {
;         const int row0 = u.pm * BM + wr * 64 + fr, col0 = u.pn * HALF + wc * 32 + 8 * fq;
; #pragma unroll
;         for (int ai = 0; ai < 2; ++ai)
; #pragma unroll
;             for (int m = 0; m < 4; ++m) { const int row = row0 + ai * HALF + m * 16; const float rs = rsv[ai][m];
;                 float g[8], sg[8]; f32x4 o[2];
; #pragma unroll
;                 for (int j = 0; j < 8; ++j) g[j] = acc[ai][0][m][j >> 2][j & 3] * rs;
;                 sigmoid8(g, sg);
; #pragma unroll
;                 for (int j = 0; j < 8; ++j) o[j >> 2][j & 3] = (g[j] * sg[j]) * (acc[ai][1][m][j >> 2][j & 3] * rs);
;                 *(u32x4*)(H + (size_t)row * FF + col0) = pack8(o[0], o[1]); }
	v_pk_mul_f32 v[40:41], v[146:147], v[48:49] op_sel_hi:[0,1]
	v_mov_b32_e32 v49, v50
	v_mov_b32_e32 v50, v43
	v_mov_b32_e32 v48, v42
	v_pk_mul_f32 v[42:43], v[146:147], v[50:51] op_sel_hi:[0,1]
	v_mov_b32_e32 v51, v44
	v_mov_b32_e32 v44, v37
	v_mov_b32_e32 v50, v36
	v_pk_mul_f32 v[36:37], v[146:147], v[44:45] op_sel_hi:[0,1]
	v_mov_b32_e32 v44, v38
	v_mov_b32_e32 v45, v46
	v_mov_b32_e32 v46, v39
	v_pk_mul_f32 v[52:53], v[146:147], v[52:53] op_sel_hi:[0,1]
	v_pk_mul_f32 v[48:49], v[146:147], v[48:49] op_sel_hi:[0,1]
	v_pk_mul_f32 v[50:51], v[146:147], v[50:51] op_sel_hi:[0,1]
	v_pk_mul_f32 v[44:45], v[146:147], v[44:45] op_sel_hi:[0,1]
	v_pk_mul_f32 v[38:39], v[146:147], v[46:47] op_sel_hi:[0,1]
	v_mul_f32_e32 v54, 0xbfb8aa3b, v53
	v_mul_f32_e32 v55, 0xbfb8aa3b, v41
	v_mul_f32_e32 v56, 0xbfb8aa3b, v49
	v_mul_f32_e32 v57, 0xbfb8aa3b, v43
	v_mul_f32_e32 v58, 0xbfb8aa3b, v51
	v_mul_f32_e32 v59, 0xbfb8aa3b, v37
	v_mul_f32_e32 v60, 0xbfb8aa3b, v45
	v_mul_f32_e32 v46, 0xbfb8aa3b, v39
	s_nop 0
	v_exp_f32_e32 v47, v54
	v_exp_f32_e32 v54, v55
	v_exp_f32_e32 v55, v56
	v_exp_f32_e32 v56, v57
	v_exp_f32_e32 v57, v58
	v_exp_f32_e32 v58, v59
	v_exp_f32_e32 v59, v60
	v_exp_f32_e32 v46, v46
	s_nop 0
	v_add_f32_e32 v47, 1.0, v47
	v_add_f32_e32 v54, 1.0, v54
	v_add_f32_e32 v55, 1.0, v55
	v_add_f32_e32 v56, 1.0, v56
	v_add_f32_e32 v57, 1.0, v57
	v_add_f32_e32 v58, 1.0, v58
	v_add_f32_e32 v59, 1.0, v59
	v_add_f32_e32 v46, 1.0, v46
	s_nop 0
	v_rcp_f32_e32 v47, v47
	v_rcp_f32_e32 v54, v54
	v_rcp_f32_e32 v55, v55
	v_rcp_f32_e32 v56, v56
	v_rcp_f32_e32 v57, v57
	v_rcp_f32_e32 v58, v58
	v_rcp_f32_e32 v59, v59
	v_rcp_f32_e32 v46, v46
	s_nop 0
	v_mul_f32_e32 v41, v41, v54
	v_mul_f32_e32 v40, v40, v41
	v_mul_f32_e32 v41, v49, v55
	v_mul_f32_e32 v37, v37, v58
	v_mul_f32_e32 v41, v48, v41
	v_mul_f32_e32 v48, v36, v37
	v_mul_f32_e32 v36, v45, v59
	v_mul_f32_e32 v47, v53, v47
	v_mul_f32_e32 v43, v43, v56
	v_mul_f32_e32 v44, v44, v36
	v_mul_f32_e32 v36, v39, v46
	v_add_u32_e32 v45, 0x90, v120
	v_mul_f32_e32 v47, v52, v47
	v_mul_f32_e32 v42, v42, v43
	v_mul_f32_e32 v39, v38, v36
	v_cvt_pk_bf16_f32 v36, v47, v40
	v_cvt_pk_bf16_f32 v37, v41, v42
	v_mad_i64_i32 v[40:41], s[4:5], v45, s29, v[116:117]
	v_mul_f32_e32 v43, v51, v57
	v_lshl_add_u64 v[40:41], v[40:41], 0, v[118:119]
	v_mul_f32_e32 v43, v50, v43
	v_cvt_pk_bf16_f32 v38, v43, v48
	v_cvt_pk_bf16_f32 v39, v44, v39
	global_store_dwordx4 v[40:41], v[36:39], off
	s_nop 1
	v_mov_b32_e32 v37, v32
	v_mov_b32_e32 v32, v25
	v_mov_b32_e32 v36, v24
	v_pk_mul_f32 v[24:25], v[144:145], v[32:33] op_sel_hi:[0,1]
	v_mov_b32_e32 v33, v34
	v_mov_b32_e32 v34, v27
	v_mov_b32_e32 v32, v26
	v_pk_mul_f32 v[26:27], v[144:145], v[34:35] op_sel_hi:[0,1]
	v_mov_b32_e32 v35, v28
	v_mov_b32_e32 v28, v21
	v_mov_b32_e32 v34, v20
	v_pk_mul_f32 v[20:21], v[144:145], v[28:29] op_sel_hi:[0,1]
	v_mov_b32_e32 v28, v22
	v_mov_b32_e32 v29, v30
	v_mov_b32_e32 v30, v23
	v_pk_mul_f32 v[36:37], v[144:145], v[36:37] op_sel_hi:[0,1]
	v_pk_mul_f32 v[32:33], v[144:145], v[32:33] op_sel_hi:[0,1]
	v_pk_mul_f32 v[34:35], v[144:145], v[34:35] op_sel_hi:[0,1]
	v_pk_mul_f32 v[28:29], v[144:145], v[28:29] op_sel_hi:[0,1]
	v_pk_mul_f32 v[22:23], v[144:145], v[30:31] op_sel_hi:[0,1]
	v_mul_f32_e32 v38, 0xbfb8aa3b, v37
	v_mul_f32_e32 v39, 0xbfb8aa3b, v25
	v_mul_f32_e32 v40, 0xbfb8aa3b, v33
	v_mul_f32_e32 v41, 0xbfb8aa3b, v27
	v_mul_f32_e32 v42, 0xbfb8aa3b, v35
	v_mul_f32_e32 v43, 0xbfb8aa3b, v21
	v_mul_f32_e32 v44, 0xbfb8aa3b, v29
	v_mul_f32_e32 v30, 0xbfb8aa3b, v23
	s_nop 0
	v_exp_f32_e32 v31, v38
	v_exp_f32_e32 v38, v39
	v_exp_f32_e32 v39, v40
	v_exp_f32_e32 v40, v41
	v_exp_f32_e32 v41, v42
	v_exp_f32_e32 v42, v43
	v_exp_f32_e32 v43, v44
	v_exp_f32_e32 v30, v30
	s_nop 0
	v_add_f32_e32 v31, 1.0, v31
	v_add_f32_e32 v38, 1.0, v38
	v_add_f32_e32 v39, 1.0, v39
	v_add_f32_e32 v40, 1.0, v40
	v_add_f32_e32 v41, 1.0, v41
	v_add_f32_e32 v42, 1.0, v42
	v_add_f32_e32 v43, 1.0, v43
	v_add_f32_e32 v30, 1.0, v30
	s_nop 0
	v_rcp_f32_e32 v31, v31
	v_rcp_f32_e32 v38, v38
	v_rcp_f32_e32 v39, v39
	v_rcp_f32_e32 v40, v40
	v_rcp_f32_e32 v41, v41
	v_rcp_f32_e32 v42, v42
	v_rcp_f32_e32 v43, v43
	v_rcp_f32_e32 v30, v30
	s_nop 0
	v_mul_f32_e32 v25, v25, v38
	v_mul_f32_e32 v24, v24, v25
	v_mul_f32_e32 v25, v33, v39
	v_mul_f32_e32 v21, v21, v42
	v_mul_f32_e32 v25, v32, v25
	v_mul_f32_e32 v32, v20, v21
	v_mul_f32_e32 v20, v29, v43
	v_mul_f32_e32 v31, v37, v31
	v_mul_f32_e32 v27, v27, v40
	v_mul_f32_e32 v28, v28, v20
	v_mul_f32_e32 v20, v23, v30
	v_add_u32_e32 v29, 0xa0, v120
	v_mul_f32_e32 v31, v36, v31
	v_mul_f32_e32 v26, v26, v27
	v_mul_f32_e32 v23, v22, v20
; #define PG8_RS(u_) do { if constexpr (Epi::NEEDS_RS) { _Pragma("unroll") for (int ai_ = 0; ai_ < 2; ++ai_) _Pragma("unroll") for (int m_ = 0; m_ < 4; ++m_) rsv[ai_][m_] = row_scale(E.ssq, (u_).pm * BM + wr * 64 + fr + ai_ * HALF + m_ * 16); } } while (0)
; __device__ __forceinline__ u32x4 pack8(f32x4 a, f32x4 b) { u32x4 w; w.x = cvt_pk_bf16(a[0], a[1]); w.y = cvt_pk_bf16(a[2], a[3]); w.z = cvt_pk_bf16(b[0], b[1]); w.w = cvt_pk_bf16(b[2], b[3]); return w; }
; template <class Epi, class Sched, bool ALIGN_EPI = false, bool SP2 = false>
; __device__ __forceinline__ void gemm_phase(PG8_LAS unsigned char* lds, const Gemm g, const Sched& S, const Epi& E) {
;     ...
;     PG8_RS(cur);
;     __device__ __forceinline__ void operator()(const f32x4 (&acc)[2][2][4][2], const Unit& u, int wr, int wc, int fr, int fq, const float (&rsv)[2][4]) const {
;         const int row0 = u.pm * BM + wr * 64 + fr, col0 = u.pn * HALF + wc * 32 + 8 * fq;
; #pragma unroll
;         for (int ai = 0; ai < 2; ++ai)
; #pragma unroll
;             for (int m = 0; m < 4; ++m) { const int row = row0 + ai * HALF + m * 16; const float rs = rsv[ai][m];
;                 float g[8], sg[8]; f32x4 o[2];
; #pragma unroll
;                 for (int j = 0; j < 8; ++j) g[j] = acc[ai][0][m][j >> 2][j & 3] * rs;
;                 sigmoid8(g, sg);
; #pragma unroll
;                 for (int j = 0; j < 8; ++j) o[j >> 2][j & 3] = (g[j] * sg[j]) * (acc[ai][1][m][j >> 2][j & 3] * rs);
;                 *(u32x4*)(H + (size_t)row * FF + col0) = pack8(o[0], o[1]); }
	v_cvt_pk_bf16_f32 v20, v31, v24
	v_cvt_pk_bf16_f32 v21, v25, v26
	v_mad_i64_i32 v[24:25], s[4:5], v29, s29, v[116:117]
	v_mul_f32_e32 v27, v35, v41
	v_lshl_add_u64 v[24:25], v[24:25], 0, v[118:119]
	v_mul_f32_e32 v27, v34, v27
	v_cvt_pk_bf16_f32 v22, v27, v32
	v_cvt_pk_bf16_f32 v23, v28, v23
	global_store_dwordx4 v[24:25], v[20:23], off
	s_nop 1
	v_mov_b32_e32 v21, v16
	v_mov_b32_e32 v16, v9
	v_mov_b32_e32 v20, v8
	v_pk_mul_f32 v[8:9], v[142:143], v[16:17] op_sel_hi:[0,1]
	v_mov_b32_e32 v17, v18
	v_mov_b32_e32 v18, v11
	v_mov_b32_e32 v16, v10
	v_pk_mul_f32 v[10:11], v[142:143], v[18:19] op_sel_hi:[0,1]
	v_mov_b32_e32 v19, v12
	v_mov_b32_e32 v12, v5
	v_mov_b32_e32 v18, v4
	v_pk_mul_f32 v[4:5], v[142:143], v[12:13] op_sel_hi:[0,1]
	v_mov_b32_e32 v12, v6
	v_mov_b32_e32 v13, v14
	v_mov_b32_e32 v14, v7
	v_pk_mul_f32 v[20:21], v[142:143], v[20:21] op_sel_hi:[0,1]
	v_pk_mul_f32 v[16:17], v[142:143], v[16:17] op_sel_hi:[0,1]
	v_pk_mul_f32 v[18:19], v[142:143], v[18:19] op_sel_hi:[0,1]
	v_pk_mul_f32 v[12:13], v[142:143], v[12:13] op_sel_hi:[0,1]
	v_pk_mul_f32 v[6:7], v[142:143], v[14:15] op_sel_hi:[0,1]
	v_mul_f32_e32 v22, 0xbfb8aa3b, v21
	v_mul_f32_e32 v23, 0xbfb8aa3b, v9
	v_mul_f32_e32 v24, 0xbfb8aa3b, v17
	v_mul_f32_e32 v25, 0xbfb8aa3b, v11
	v_mul_f32_e32 v26, 0xbfb8aa3b, v19
	v_mul_f32_e32 v27, 0xbfb8aa3b, v5
	v_mul_f32_e32 v28, 0xbfb8aa3b, v13
	v_mul_f32_e32 v14, 0xbfb8aa3b, v7
	s_nop 0
	v_exp_f32_e32 v15, v22
	v_exp_f32_e32 v22, v23
	v_exp_f32_e32 v23, v24
	v_exp_f32_e32 v24, v25
	v_exp_f32_e32 v25, v26
	v_exp_f32_e32 v26, v27
	v_exp_f32_e32 v27, v28
	v_exp_f32_e32 v14, v14
	s_nop 0
	v_add_f32_e32 v15, 1.0, v15
	v_add_f32_e32 v22, 1.0, v22
	v_add_f32_e32 v23, 1.0, v23
	v_add_f32_e32 v24, 1.0, v24
	v_add_f32_e32 v25, 1.0, v25
	v_add_f32_e32 v26, 1.0, v26
	v_add_f32_e32 v27, 1.0, v27
	v_add_f32_e32 v14, 1.0, v14
	s_nop 0
	v_rcp_f32_e32 v15, v15
	v_rcp_f32_e32 v22, v22
	v_rcp_f32_e32 v23, v23
	v_rcp_f32_e32 v24, v24
	v_rcp_f32_e32 v25, v25
	v_rcp_f32_e32 v26, v26
	v_rcp_f32_e32 v27, v27
	v_rcp_f32_e32 v14, v14
	s_nop 0
	v_mul_f32_e32 v9, v9, v22
	v_mul_f32_e32 v8, v8, v9
	v_mul_f32_e32 v9, v17, v23
	v_mul_f32_e32 v5, v5, v26
	v_mul_f32_e32 v9, v16, v9
	v_mul_f32_e32 v16, v4, v5
	v_mul_f32_e32 v4, v13, v27
	v_mul_f32_e32 v15, v21, v15
	v_mul_f32_e32 v11, v11, v24
	v_mul_f32_e32 v12, v12, v4
	v_mul_f32_e32 v4, v7, v14
	v_add_u32_e32 v13, 0xb0, v120
	v_mul_f32_e32 v15, v20, v15
	v_mul_f32_e32 v10, v10, v11
	v_mul_f32_e32 v7, v6, v4
	v_cvt_pk_bf16_f32 v4, v15, v8
	v_cvt_pk_bf16_f32 v5, v9, v10
	v_mad_i64_i32 v[8:9], s[4:5], v13, s29, v[116:117]
	v_mul_f32_e32 v11, v19, v25
	v_lshl_add_u64 v[8:9], v[8:9], 0, v[118:119]
	v_mul_f32_e32 v11, v18, v11
	v_cvt_pk_bf16_f32 v6, v11, v16
	v_cvt_pk_bf16_f32 v7, v12, v7
	global_store_dwordx4 v[8:9], v[4:7], off
	s_cbranch_vccnz .LBB0_2658
	s_nop 0
	v_lshl_add_u32 v4, s44, 8, v143
	v_or_b32_e32 v8, 16, v4
	v_ashrrev_i32_e32 v5, 31, v4
	v_ashrrev_i32_e32 v9, 31, v8
	v_lshlrev_b64 v[6:7], 5, v[4:5]
	v_lshlrev_b64 v[8:9], 5, v[8:9]
	v_lshl_add_u64 v[6:7], s[2:3], 0, v[6:7]
	v_lshl_add_u64 v[8:9], s[2:3], 0, v[8:9]
	global_load_dwordx4 v[64:67], v[6:7], off
	global_load_dwordx4 v[60:63], v[6:7], off offset:16
	global_load_dwordx4 v[56:59], v[8:9], off
	global_load_dwordx4 v[52:55], v[8:9], off offset:16
	v_or_b32_e32 v8, 32, v4
	v_ashrrev_i32_e32 v9, 31, v8
	v_or_b32_e32 v4, 48, v4
	v_lshlrev_b64 v[8:9], 5, v[8:9]
	v_ashrrev_i32_e32 v5, 31, v4
	v_lshl_add_u64 v[8:9], s[2:3], 0, v[8:9]
	v_lshlrev_b64 v[4:5], 5, v[4:5]
	global_load_dwordx4 v[48:51], v[8:9], off
	global_load_dwordx4 v[44:47], v[8:9], off offset:16
	v_lshl_add_u64 v[4:5], s[2:3], 0, v[4:5]
	v_add_co_u32_e32 v8, vcc, s97, v6
	global_load_dwordx4 v[40:43], v[4:5], off
	global_load_dwordx4 v[36:39], v[4:5], off offset:16
	v_lshl_add_u64 v[4:5], v[6:7], 0, s[16:17]
	v_addc_co_u32_e32 v9, vcc, 0, v7, vcc
	s_mov_b64 s[4:5], 0x1200
	global_load_dwordx4 v[32:35], v[8:9], off
	global_load_dwordx4 v[28:31], v[4:5], off offset:16
	v_lshl_add_u64 v[4:5], v[6:7], 0, s[4:5]
	s_mov_b64 s[4:5], 0x1400
	v_lshl_add_u64 v[10:11], v[6:7], 0, s[4:5]
	s_mov_b64 s[4:5], 0x1600
	global_load_dwordx4 v[20:23], v[8:9], off offset:512
	global_load_dwordx4 v[12:15], v[8:9], off offset:1024
	v_lshl_add_u64 v[68:69], v[6:7], 0, s[4:5]
	global_load_dwordx4 v[24:27], v[4:5], off offset:16
	s_nop 0
	global_load_dwordx4 v[4:7], v[8:9], off offset:1536
	global_load_dwordx4 v[16:19], v[10:11], off offset:16
	s_nop 0
	global_load_dwordx4 v[8:11], v[68:69], off offset:16
	s_andn2_b64 vcc, exec, s[20:21]
	s_cbranch_vccnz .LBB0_2657
	s_barrier
	s_branch .LBB0_2657

; template <class Epi, class Sched, bool ALIGN_EPI = false, bool SP2 = false>
; __device__ __forceinline__ void gemm_phase(PG8_LAS unsigned char* lds, const Gemm g, const Sched& S, const Epi& E) {
;     ...
; #pragma unroll
;         for (int a = 0; a < 2; ++a)
; #pragma unroll
;             for (int b = 0; b < 2; ++b)
; #pragma unroll
;                 for (int m = 0; m < 4; ++m)
; #pragma unroll
;                     for (int n = 0; n < 2; ++n) acc[a][b][m][n] = (f32x4){0.f, 0.f, 0.f, 0.f};
;         cur = nxt; cA = nA; cB = nB; ++ui;
.LBB0_2769:
	s_add_u32 s4, s50, 0x100
	v_mov_b32_e32 v4, 0
	s_addc_u32 s5, s51, 0
	s_mov_b32 s6, -2
	s_waitcnt lgkmcnt(0)
	v_mov_b32_e32 v5, v4
	v_mov_b32_e32 v6, v4
	v_mov_b32_e32 v7, v4
	v_mov_b32_e32 v8, v4
	v_mov_b32_e32 v9, v4
	v_mov_b32_e32 v10, v4
	v_mov_b32_e32 v11, v4
	v_mov_b32_e32 v20, v4
	v_mov_b32_e32 v21, v4
	v_mov_b32_e32 v22, v4
	v_mov_b32_e32 v23, v4
	v_mov_b32_e32 v24, v4
	v_mov_b32_e32 v25, v4
	v_mov_b32_e32 v26, v4
	v_mov_b32_e32 v27, v4
	v_mov_b32_e32 v36, v4
	v_mov_b32_e32 v37, v4
	v_mov_b32_e32 v38, v4
	v_mov_b32_e32 v39, v4
	v_mov_b32_e32 v40, v4
	v_mov_b32_e32 v41, v4
	v_mov_b32_e32 v42, v4
	v_mov_b32_e32 v43, v4
	v_mov_b32_e32 v52, v4
	v_mov_b32_e32 v53, v4
	v_mov_b32_e32 v54, v4
	v_mov_b32_e32 v55, v4
	v_mov_b32_e32 v56, v4
	v_mov_b32_e32 v57, v4
	v_mov_b32_e32 v58, v4
	v_mov_b32_e32 v59, v4
	v_mov_b32_e32 v12, v4
	v_mov_b32_e32 v13, v4
	v_mov_b32_e32 v14, v4
	v_mov_b32_e32 v15, v4
	v_mov_b32_e32 v16, v4
	v_mov_b32_e32 v17, v4
	v_mov_b32_e32 v18, v4
	v_mov_b32_e32 v19, v4
	v_mov_b32_e32 v28, v4
	v_mov_b32_e32 v29, v4
	v_mov_b32_e32 v30, v4
	v_mov_b32_e32 v31, v4
	v_mov_b32_e32 v32, v4
	v_mov_b32_e32 v33, v4
	v_mov_b32_e32 v34, v4
	v_mov_b32_e32 v35, v4
	v_mov_b32_e32 v44, v4
	v_mov_b32_e32 v45, v4
	v_mov_b32_e32 v46, v4
	v_mov_b32_e32 v47, v4
	v_mov_b32_e32 v48, v4
	v_mov_b32_e32 v49, v4
	v_mov_b32_e32 v50, v4
	v_mov_b32_e32 v51, v4
	v_mov_b32_e32 v60, v4
	v_mov_b32_e32 v61, v4
	v_mov_b32_e32 v62, v4
	v_mov_b32_e32 v63, v4
	v_mov_b32_e32 v64, v4
	v_mov_b32_e32 v65, v4
	v_mov_b32_e32 v66, v4
	v_mov_b32_e32 v67, v4
	v_mov_b32_e32 v68, v4
	v_mov_b32_e32 v69, v4
	v_mov_b32_e32 v70, v4
	v_mov_b32_e32 v71, v4
	v_mov_b32_e32 v72, v4
	v_mov_b32_e32 v73, v4
	v_mov_b32_e32 v74, v4
	v_mov_b32_e32 v75, v4
	v_mov_b32_e32 v84, v4
	v_mov_b32_e32 v85, v4
	v_mov_b32_e32 v86, v4
	v_mov_b32_e32 v87, v4
	v_mov_b32_e32 v88, v4
	v_mov_b32_e32 v89, v4
	v_mov_b32_e32 v90, v4
	v_mov_b32_e32 v91, v4
	v_mov_b32_e32 v100, v4
	v_mov_b32_e32 v101, v4
	v_mov_b32_e32 v102, v4
	v_mov_b32_e32 v103, v4
	v_mov_b32_e32 v104, v4
	v_mov_b32_e32 v105, v4
	v_mov_b32_e32 v106, v4
	v_mov_b32_e32 v107, v4
	v_mov_b32_e32 v116, v4
	v_mov_b32_e32 v117, v4
	v_mov_b32_e32 v118, v4
	v_mov_b32_e32 v119, v4
	v_mov_b32_e32 v120, v4
	v_mov_b32_e32 v121, v4
	v_mov_b32_e32 v122, v4
	v_mov_b32_e32 v123, v4
	v_mov_b32_e32 v76, v4
	v_mov_b32_e32 v77, v4
	v_mov_b32_e32 v78, v4
	v_mov_b32_e32 v79, v4
	v_mov_b32_e32 v80, v4
	v_mov_b32_e32 v81, v4
	v_mov_b32_e32 v82, v4
	v_mov_b32_e32 v83, v4
	v_mov_b32_e32 v92, v4
	v_mov_b32_e32 v93, v4
	v_mov_b32_e32 v94, v4
	v_mov_b32_e32 v95, v4
	v_mov_b32_e32 v96, v4
	v_mov_b32_e32 v97, v4
	v_mov_b32_e32 v98, v4
	v_mov_b32_e32 v99, v4
	v_mov_b32_e32 v108, v4
	v_mov_b32_e32 v109, v4
	v_mov_b32_e32 v110, v4
	v_mov_b32_e32 v111, v4
	v_mov_b32_e32 v112, v4
	v_mov_b32_e32 v113, v4
	v_mov_b32_e32 v114, v4
	v_mov_b32_e32 v115, v4
	v_mov_b32_e32 v124, v4
	v_mov_b32_e32 v125, v4
	v_mov_b32_e32 v126, v4
	v_mov_b32_e32 v127, v4
	v_mov_b32_e32 v128, v4
	v_mov_b32_e32 v129, v4
	v_mov_b32_e32 v130, v4
	v_mov_b32_e32 v131, v4
	s_nop 0
	s_nop 0
	s_nop 0
	s_nop 0
	s_nop 0
	s_nop 0
	s_nop 0
	s_nop 0
	s_nop 0
	v_readfirstlane_b32 s98, v0
	s_nop 3
	s_lshr_b32 s98, s98, 6
	s_cmp_ge_u32 s98, 4
	s_cbranch_scc0 .Lprio_g6
	s_setprio 1

; #define PG8_STAGE(bufoff, gbase, voff) do { _Pragma("unroll") for (int _i = 0; _i < 2; ++_i) \
;         __builtin_amdgcn_global_load_lds((const unsigned*)((const char*)(gbase) + (voff)[_i]), (PG8_LAS unsigned*)(lds + (bufoff) + ldsw + _i * 8192), 16, 0, 0); } while (0)
; #define PG8_LDA(dst, b, h) do { _Pragma("unroll") for (int m = 0; m < 4; ++m) _Pragma("unroll") for (int k = 0; k < 2; ++k) dst[m][k] = *(const PG8_LAS bf16x8*)(lds + PG8_SA(b, h) + aoff + m * 2048 + k * 1024); } while (0)
; #define PG8_LDB(dst, b, h) do { _Pragma("unroll") for (int n = 0; n < 2; ++n) _Pragma("unroll") for (int k = 0; k < 2; ++k) dst[n][k] = *(const PG8_LAS bf16x8*)(lds + PG8_SB(b, h) + boff + n * 2048 + k * 1024); } while (0)
; #define PG8_MMA(ai, bj, At, Bt) do { __builtin_amdgcn_s_setprio(1); _Pragma("unroll") for (int m = 0; m < 4; ++m) _Pragma("unroll") for (int n = 0; n < 2; ++n) _Pragma("unroll") for (int k = 0; k < 2; ++k) \
;         acc[ai][bj][m][n] = __builtin_amdgcn_mfma_f32_16x16x32_bf16(Bt[n][k], At[m][k], acc[ai][bj][m][n], 0, 0, 0); __builtin_amdgcn_s_setprio(0); } while (0)
; #define PG8_WAIT_V(n) asm volatile("s_waitcnt vmcnt(" #n ")" ::: "memory")
; #define PG8_WAIT_L(n) asm volatile("s_waitcnt lgkmcnt(" #n ")" ::: "memory")
; #define PG8_BAR __builtin_amdgcn_s_barrier()
; #define PG8_SCHED __builtin_amdgcn_sched_barrier(0)
; template <class Epi, class Sched, bool ALIGN_EPI = false, bool SP2 = false>
; __device__ __forceinline__ void gemm_phase(PG8_LAS unsigned char* lds, const Gemm g, const Sched& S, const Epi& E) {
;     ...
;             PG8_LDB(B0, 0, 0); PG8_LDB(B1, 0, 1); PG8_SCHED; PG8_LDA(At, 0, 0); PG8_STAGE(PG8_SA(1, 1), a1 + hstepA, voffA);
;             PG8_WAIT_V(8); PG8_WAIT_L(0); PG8_BAR; PG8_MMA(0, 0, At, B0); PG8_MMA(0, 1, At, B1); PG8_BAR; PG8_SCHED;
;             PG8_LDA(At, 0, 1); PG8_STAGE(PG8_SB(0, 0), b2, voffB); PG8_STAGE(PG8_SB(0, 1), b2 + hstepB, voffB); PG8_STAGE(PG8_SA(0, 0), a2, voffA);
;             PG8_WAIT_V(8); PG8_WAIT_L(0); PG8_BAR; PG8_MMA(1, 0, At, B0); PG8_MMA(1, 1, At, B1); PG8_BAR; PG8_SCHED;
.LBB0_2770:
	s_add_u32 s50, s36, 0x100
	s_addc_u32 s51, s37, 0
	s_add_i32 s7, 0, 0x10000
	s_cmpk_eq_i32 s6, 0x54
	s_cselect_b32 s57, s43, s51
	s_cselect_b32 s56, s42, s50
	v_add_u32_e32 v153, s7, v147
	s_cselect_b32 s53, s49, s5
	s_cselect_b32 s52, s48, s4
	s_add_i32 s14, 0, 0x14000
	ds_read_b128 v[142:145], v153
	ds_read_b128 v[172:175], v153 offset:1024
	ds_read_b128 v[176:179], v153 offset:2048
	ds_read_b128 v[180:183], v153 offset:3072
	v_add_u32_e32 v153, s14, v147
	ds_read_b128 v[184:187], v153
	ds_read_b128 v[188:191], v153 offset:1024
	ds_read_b128 v[192:195], v153 offset:2048
	ds_read_b128 v[208:211], v153 offset:3072
	v_lshl_add_u64 v[154:155], s[36:37], 0, v[138:139]
	s_add_i32 m0, s66, 0xc000
	ds_read_b128 v[212:215], v151
	ds_read_b128 v[216:219], v151 offset:1024
	ds_read_b128 v[220:223], v151 offset:2048
	ds_read_b128 v[224:227], v151 offset:3072
	ds_read_b128 v[228:231], v151 offset:4096
	ds_read_b128 v[232:235], v151 offset:5120
	ds_read_b128 v[236:239], v151 offset:6144
	ds_read_b128 v[240:243], v151 offset:7168
	global_load_lds_dwordx4 v[154:155], off
	v_lshl_add_u64 v[154:155], s[36:37], 0, v[140:141]
	s_add_i32 m0, s66, 0xe000
	s_nop 0
	global_load_lds_dwordx4 v[154:155], off
	s_waitcnt vmcnt(8)
	s_waitcnt lgkmcnt(0)
	s_barrier
	s_waitcnt lgkmcnt(0)
	v_mfma_f32_16x16x32_bf16 v[128:131], v[142:145], v[212:215], v[128:131]
	v_mfma_f32_16x16x32_bf16 v[124:127], v[176:179], v[212:215], v[124:127]
	v_mfma_f32_16x16x32_bf16 v[112:115], v[142:145], v[220:223], v[112:115]
	v_mfma_f32_16x16x32_bf16 v[108:111], v[176:179], v[220:223], v[108:111]
	v_mfma_f32_16x16x32_bf16 v[96:99], v[142:145], v[228:231], v[96:99]
	v_mfma_f32_16x16x32_bf16 v[92:95], v[176:179], v[228:231], v[92:95]
	v_mfma_f32_16x16x32_bf16 v[80:83], v[142:145], v[236:239], v[80:83]
	v_mfma_f32_16x16x32_bf16 v[76:79], v[176:179], v[236:239], v[76:79]
	v_mfma_f32_16x16x32_bf16 v[128:131], v[172:175], v[216:219], v[128:131]
	v_mfma_f32_16x16x32_bf16 v[124:127], v[180:183], v[216:219], v[124:127]
	v_mfma_f32_16x16x32_bf16 v[112:115], v[172:175], v[224:227], v[112:115]
	v_mfma_f32_16x16x32_bf16 v[108:111], v[180:183], v[224:227], v[108:111]
	v_mfma_f32_16x16x32_bf16 v[96:99], v[172:175], v[232:235], v[96:99]
	v_mfma_f32_16x16x32_bf16 v[92:95], v[180:183], v[232:235], v[92:95]
	v_mfma_f32_16x16x32_bf16 v[80:83], v[172:175], v[240:243], v[80:83]
	v_mfma_f32_16x16x32_bf16 v[76:79], v[180:183], v[240:243], v[76:79]
	v_mfma_f32_16x16x32_bf16 v[120:123], v[184:187], v[212:215], v[120:123]
	v_mfma_f32_16x16x32_bf16 v[116:119], v[192:195], v[212:215], v[116:119]
	v_mfma_f32_16x16x32_bf16 v[104:107], v[184:187], v[220:223], v[104:107]
	v_mfma_f32_16x16x32_bf16 v[100:103], v[192:195], v[220:223], v[100:103]
	v_mfma_f32_16x16x32_bf16 v[88:91], v[184:187], v[228:231], v[88:91]
	v_mfma_f32_16x16x32_bf16 v[84:87], v[192:195], v[228:231], v[84:87]
	v_mfma_f32_16x16x32_bf16 v[72:75], v[184:187], v[236:239], v[72:75]
	v_mfma_f32_16x16x32_bf16 v[68:71], v[192:195], v[236:239], v[68:71]
	v_mfma_f32_16x16x32_bf16 v[120:123], v[188:191], v[216:219], v[120:123]
	v_mfma_f32_16x16x32_bf16 v[116:119], v[208:211], v[216:219], v[116:119]
	v_mfma_f32_16x16x32_bf16 v[104:107], v[188:191], v[224:227], v[104:107]
	v_mfma_f32_16x16x32_bf16 v[100:103], v[208:211], v[224:227], v[100:103]
	v_mfma_f32_16x16x32_bf16 v[88:91], v[188:191], v[232:235], v[88:91]
	v_mfma_f32_16x16x32_bf16 v[84:87], v[208:211], v[232:235], v[84:87]
	v_mfma_f32_16x16x32_bf16 v[72:75], v[188:191], v[240:243], v[72:75]
	v_mfma_f32_16x16x32_bf16 v[68:71], v[208:211], v[240:243], v[68:71]
	s_barrier
	s_add_i32 s7, s7, s65
	v_lshl_add_u64 v[154:155], s[52:53], 0, v[2:3]
	s_mov_b32 m0, s7
	ds_read_b128 v[212:215], v151 offset:16384
	ds_read_b128 v[216:219], v151 offset:17408
	ds_read_b128 v[220:223], v151 offset:18432
	ds_read_b128 v[224:227], v151 offset:19456
	ds_read_b128 v[228:231], v151 offset:20480
	ds_read_b128 v[232:235], v151 offset:21504
	ds_read_b128 v[236:239], v151 offset:22528
	ds_read_b128 v[240:243], v151 offset:23552
	global_load_lds_dwordx4 v[154:155], off
	s_add_i32 m0, s7, 0x2000
	s_add_u32 s8, s52, 0x160000
	v_lshl_add_u64 v[156:157], s[52:53], 0, v[136:137]
	s_addc_u32 s9, s53, 0
	s_add_i32 s7, s14, s65
	global_load_lds_dwordx4 v[156:157], off
	v_lshl_add_u64 v[158:159], s[8:9], 0, v[2:3]
	s_mov_b32 m0, s7
	v_lshl_add_u64 v[164:165], s[56:57], 0, v[134:135]
	global_load_lds_dwordx4 v[158:159], off
	v_lshl_add_u64 v[158:159], s[8:9], 0, v[136:137]
	s_add_i32 m0, s7, 0x2000
	s_nop 0
	global_load_lds_dwordx4 v[158:159], off
	v_lshl_add_u64 v[158:159], s[56:57], 0, v[132:133]
	s_mov_b32 m0, s66
	s_nop 0
	global_load_lds_dwordx4 v[158:159], off
	s_mov_b32 m0, s67
	s_nop 0
	global_load_lds_dwordx4 v[164:165], off
	s_waitcnt vmcnt(8)
	s_waitcnt lgkmcnt(0)
	s_barrier
; #define PG8_STAGE(bufoff, gbase, voff) do { _Pragma("unroll") for (int _i = 0; _i < 2; ++_i) \
;         __builtin_amdgcn_global_load_lds((const unsigned*)((const char*)(gbase) + (voff)[_i]), (PG8_LAS unsigned*)(lds + (bufoff) + ldsw + _i * 8192), 16, 0, 0); } while (0)
; #define PG8_LDA(dst, b, h) do { _Pragma("unroll") for (int m = 0; m < 4; ++m) _Pragma("unroll") for (int k = 0; k < 2; ++k) dst[m][k] = *(const PG8_LAS bf16x8*)(lds + PG8_SA(b, h) + aoff + m * 2048 + k * 1024); } while (0)
; #define PG8_LDB(dst, b, h) do { _Pragma("unroll") for (int n = 0; n < 2; ++n) _Pragma("unroll") for (int k = 0; k < 2; ++k) dst[n][k] = *(const PG8_LAS bf16x8*)(lds + PG8_SB(b, h) + boff + n * 2048 + k * 1024); } while (0)
; #define PG8_MMA(ai, bj, At, Bt) do { __builtin_amdgcn_s_setprio(1); _Pragma("unroll") for (int m = 0; m < 4; ++m) _Pragma("unroll") for (int n = 0; n < 2; ++n) _Pragma("unroll") for (int k = 0; k < 2; ++k) \
;         acc[ai][bj][m][n] = __builtin_amdgcn_mfma_f32_16x16x32_bf16(Bt[n][k], At[m][k], acc[ai][bj][m][n], 0, 0, 0); __builtin_amdgcn_s_setprio(0); } while (0)
; #define PG8_WAIT_V(n) asm volatile("s_waitcnt vmcnt(" #n ")" ::: "memory")
; #define PG8_WAIT_L(n) asm volatile("s_waitcnt lgkmcnt(" #n ")" ::: "memory")
; #define PG8_BAR __builtin_amdgcn_s_barrier()
; #define PG8_SCHED __builtin_amdgcn_sched_barrier(0)
; template <class Epi, class Sched, bool ALIGN_EPI = false, bool SP2 = false>
; __device__ __forceinline__ void gemm_phase(PG8_LAS unsigned char* lds, const Gemm g, const Sched& S, const Epi& E) {
;     ...
;             PG8_WAIT_V(8); PG8_WAIT_L(0); PG8_BAR; PG8_MMA(1, 0, At, B0); PG8_MMA(1, 1, At, B1); PG8_BAR; PG8_SCHED;
;             PG8_LDB(B0, 1, 0); PG8_LDB(B1, 1, 1); PG8_SCHED; PG8_LDA(At, 1, 0); PG8_STAGE(PG8_SA(0, 1), a2 + hstepA, voffA);
;             PG8_WAIT_V(8); PG8_WAIT_L(0); PG8_BAR; PG8_MMA(0, 0, At, B0); PG8_MMA(0, 1, At, B1); PG8_BAR; PG8_SCHED;
	s_waitcnt lgkmcnt(0)
	v_mfma_f32_16x16x32_bf16 v[64:67], v[142:145], v[212:215], v[64:67]
	v_mfma_f32_16x16x32_bf16 v[60:63], v[176:179], v[212:215], v[60:63]
	v_mfma_f32_16x16x32_bf16 v[48:51], v[142:145], v[220:223], v[48:51]
	v_mfma_f32_16x16x32_bf16 v[44:47], v[176:179], v[220:223], v[44:47]
	v_mfma_f32_16x16x32_bf16 v[32:35], v[142:145], v[228:231], v[32:35]
	v_mfma_f32_16x16x32_bf16 v[28:31], v[176:179], v[228:231], v[28:31]
	v_mfma_f32_16x16x32_bf16 v[16:19], v[142:145], v[236:239], v[16:19]
	v_mfma_f32_16x16x32_bf16 v[12:15], v[176:179], v[236:239], v[12:15]
	v_mfma_f32_16x16x32_bf16 v[64:67], v[172:175], v[216:219], v[64:67]
	v_mfma_f32_16x16x32_bf16 v[60:63], v[180:183], v[216:219], v[60:63]
	v_mfma_f32_16x16x32_bf16 v[48:51], v[172:175], v[224:227], v[48:51]
	v_mfma_f32_16x16x32_bf16 v[44:47], v[180:183], v[224:227], v[44:47]
	v_mfma_f32_16x16x32_bf16 v[32:35], v[172:175], v[232:235], v[32:35]
	v_mfma_f32_16x16x32_bf16 v[28:31], v[180:183], v[232:235], v[28:31]
	v_mfma_f32_16x16x32_bf16 v[16:19], v[172:175], v[240:243], v[16:19]
	v_mfma_f32_16x16x32_bf16 v[12:15], v[180:183], v[240:243], v[12:15]
	v_mfma_f32_16x16x32_bf16 v[56:59], v[184:187], v[212:215], v[56:59]
	v_mfma_f32_16x16x32_bf16 v[52:55], v[192:195], v[212:215], v[52:55]
	v_mfma_f32_16x16x32_bf16 v[40:43], v[184:187], v[220:223], v[40:43]
	v_mfma_f32_16x16x32_bf16 v[36:39], v[192:195], v[220:223], v[36:39]
	v_mfma_f32_16x16x32_bf16 v[24:27], v[184:187], v[228:231], v[24:27]
	v_mfma_f32_16x16x32_bf16 v[20:23], v[192:195], v[228:231], v[20:23]
	v_mfma_f32_16x16x32_bf16 v[8:11], v[184:187], v[236:239], v[8:11]
	v_mfma_f32_16x16x32_bf16 v[4:7], v[192:195], v[236:239], v[4:7]
	v_mfma_f32_16x16x32_bf16 v[56:59], v[188:191], v[216:219], v[56:59]
	v_mfma_f32_16x16x32_bf16 v[52:55], v[208:211], v[216:219], v[52:55]
	v_mfma_f32_16x16x32_bf16 v[40:43], v[188:191], v[224:227], v[40:43]
	v_mfma_f32_16x16x32_bf16 v[36:39], v[208:211], v[224:227], v[36:39]
	v_mfma_f32_16x16x32_bf16 v[24:27], v[188:191], v[232:235], v[24:27]
	v_mfma_f32_16x16x32_bf16 v[20:23], v[208:211], v[232:235], v[20:23]
	v_mfma_f32_16x16x32_bf16 v[8:11], v[188:191], v[240:243], v[8:11]
	v_mfma_f32_16x16x32_bf16 v[4:7], v[208:211], v[240:243], v[4:7]
	s_barrier
	s_add_i32 s7, 0, 0x18000
	v_add_u32_e32 v153, s7, v147
	s_add_i32 s14, 0, 0x1c000
	ds_read_b128 v[142:145], v153
	ds_read_b128 v[172:175], v153 offset:1024
	ds_read_b128 v[176:179], v153 offset:2048
	ds_read_b128 v[180:183], v153 offset:3072
	v_add_u32_e32 v153, s14, v147
	ds_read_b128 v[184:187], v153
	ds_read_b128 v[188:191], v153 offset:1024
	ds_read_b128 v[192:195], v153 offset:2048
	ds_read_b128 v[208:211], v153 offset:3072
	s_add_u32 s8, s56, 0x160000
	s_addc_u32 s9, s57, 0
	s_mov_b32 m0, s77
	v_lshl_add_u64 v[196:197], s[8:9], 0, v[132:133]
	ds_read_b128 v[212:215], v151 offset:32768
	ds_read_b128 v[216:219], v151 offset:33792
	ds_read_b128 v[220:223], v151 offset:34816
	ds_read_b128 v[224:227], v151 offset:35840
	ds_read_b128 v[228:231], v151 offset:36864
	ds_read_b128 v[232:235], v151 offset:37888
	ds_read_b128 v[236:239], v151 offset:38912
	ds_read_b128 v[240:243], v151 offset:39936
	global_load_lds_dwordx4 v[196:197], off
	v_lshl_add_u64 v[196:197], s[8:9], 0, v[134:135]
	s_mov_b32 m0, s78
	s_nop 0
	global_load_lds_dwordx4 v[196:197], off
	s_waitcnt vmcnt(8)
	s_waitcnt lgkmcnt(0)
	s_barrier
	s_waitcnt lgkmcnt(0)
	v_mfma_f32_16x16x32_bf16 v[128:131], v[142:145], v[212:215], v[128:131]
	v_mfma_f32_16x16x32_bf16 v[124:127], v[176:179], v[212:215], v[124:127]
	v_mfma_f32_16x16x32_bf16 v[112:115], v[142:145], v[220:223], v[112:115]
	v_mfma_f32_16x16x32_bf16 v[108:111], v[176:179], v[220:223], v[108:111]
	v_mfma_f32_16x16x32_bf16 v[96:99], v[142:145], v[228:231], v[96:99]
	v_mfma_f32_16x16x32_bf16 v[92:95], v[176:179], v[228:231], v[92:95]
	v_mfma_f32_16x16x32_bf16 v[80:83], v[142:145], v[236:239], v[80:83]
	v_mfma_f32_16x16x32_bf16 v[76:79], v[176:179], v[236:239], v[76:79]
	v_mfma_f32_16x16x32_bf16 v[128:131], v[172:175], v[216:219], v[128:131]
	v_mfma_f32_16x16x32_bf16 v[124:127], v[180:183], v[216:219], v[124:127]
	v_mfma_f32_16x16x32_bf16 v[112:115], v[172:175], v[224:227], v[112:115]
	v_mfma_f32_16x16x32_bf16 v[108:111], v[180:183], v[224:227], v[108:111]
	v_mfma_f32_16x16x32_bf16 v[96:99], v[172:175], v[232:235], v[96:99]
	v_mfma_f32_16x16x32_bf16 v[92:95], v[180:183], v[232:235], v[92:95]
	v_mfma_f32_16x16x32_bf16 v[80:83], v[172:175], v[240:243], v[80:83]
	v_mfma_f32_16x16x32_bf16 v[76:79], v[180:183], v[240:243], v[76:79]
	v_mfma_f32_16x16x32_bf16 v[120:123], v[184:187], v[212:215], v[120:123]
	v_mfma_f32_16x16x32_bf16 v[116:119], v[192:195], v[212:215], v[116:119]
	v_mfma_f32_16x16x32_bf16 v[104:107], v[184:187], v[220:223], v[104:107]
	v_mfma_f32_16x16x32_bf16 v[100:103], v[192:195], v[220:223], v[100:103]
	v_mfma_f32_16x16x32_bf16 v[88:91], v[184:187], v[228:231], v[88:91]
	v_mfma_f32_16x16x32_bf16 v[84:87], v[192:195], v[228:231], v[84:87]
	v_mfma_f32_16x16x32_bf16 v[72:75], v[184:187], v[236:239], v[72:75]
	v_mfma_f32_16x16x32_bf16 v[68:71], v[192:195], v[236:239], v[68:71]
	v_mfma_f32_16x16x32_bf16 v[120:123], v[188:191], v[216:219], v[120:123]
	v_mfma_f32_16x16x32_bf16 v[116:119], v[208:211], v[216:219], v[116:119]
	v_mfma_f32_16x16x32_bf16 v[104:107], v[188:191], v[224:227], v[104:107]
	v_mfma_f32_16x16x32_bf16 v[100:103], v[208:211], v[224:227], v[100:103]
	v_mfma_f32_16x16x32_bf16 v[88:91], v[188:191], v[232:235], v[88:91]
	v_mfma_f32_16x16x32_bf16 v[84:87], v[208:211], v[232:235], v[84:87]
	v_mfma_f32_16x16x32_bf16 v[72:75], v[188:191], v[240:243], v[72:75]
	v_mfma_f32_16x16x32_bf16 v[68:71], v[208:211], v[240:243], v[68:71]
	s_barrier
; #define PG8_STAGE(bufoff, gbase, voff) do { _Pragma("unroll") for (int _i = 0; _i < 2; ++_i) \
;         __builtin_amdgcn_global_load_lds((const unsigned*)((const char*)(gbase) + (voff)[_i]), (PG8_LAS unsigned*)(lds + (bufoff) + ldsw + _i * 8192), 16, 0, 0); } while (0)
; #define PG8_LDA(dst, b, h) do { _Pragma("unroll") for (int m = 0; m < 4; ++m) _Pragma("unroll") for (int k = 0; k < 2; ++k) dst[m][k] = *(const PG8_LAS bf16x8*)(lds + PG8_SA(b, h) + aoff + m * 2048 + k * 1024); } while (0)
; #define PG8_MMA(ai, bj, At, Bt) do { __builtin_amdgcn_s_setprio(1); _Pragma("unroll") for (int m = 0; m < 4; ++m) _Pragma("unroll") for (int n = 0; n < 2; ++n) _Pragma("unroll") for (int k = 0; k < 2; ++k) \
;         acc[ai][bj][m][n] = __builtin_amdgcn_mfma_f32_16x16x32_bf16(Bt[n][k], At[m][k], acc[ai][bj][m][n], 0, 0, 0); __builtin_amdgcn_s_setprio(0); } while (0)
; #define PG8_WAIT_V(n) asm volatile("s_waitcnt vmcnt(" #n ")" ::: "memory")
; #define PG8_WAIT_L(n) asm volatile("s_waitcnt lgkmcnt(" #n ")" ::: "memory")
; #define PG8_BAR __builtin_amdgcn_s_barrier()
; #define PG8_SCHED __builtin_amdgcn_sched_barrier(0)
; template <class Epi, class Sched, bool ALIGN_EPI = false, bool SP2 = false>
; __device__ __forceinline__ void gemm_phase(PG8_LAS unsigned char* lds, const Gemm g, const Sched& S, const Epi& E) {
;     ...
;         for (int t = 0; t < nt; t += 2) {
;             const bool last = (t == nt - 2);
;     ...
;             PG8_LDA(At, 1, 1); PG8_STAGE(PG8_SB(1, 0), b3, voffB); PG8_STAGE(PG8_SB(1, 1), b3 + hstepB, voffB); PG8_STAGE(PG8_SA(1, 0), a3, voffA);
;             PG8_WAIT_V(8); PG8_WAIT_L(0); PG8_BAR; PG8_MMA(1, 0, At, B0); PG8_MMA(1, 1, At, B1); PG8_BAR; PG8_SCHED;
	s_add_i32 s7, s7, s65
	v_lshl_add_u64 v[154:155], v[154:155], 0, s[24:25]
	s_mov_b32 m0, s7
	ds_read_b128 v[212:215], v151 offset:49152
	ds_read_b128 v[216:219], v151 offset:50176
	ds_read_b128 v[220:223], v151 offset:51200
	ds_read_b128 v[224:227], v151 offset:52224
	ds_read_b128 v[228:231], v151 offset:53248
	ds_read_b128 v[232:235], v151 offset:54272
	ds_read_b128 v[236:239], v151 offset:55296
	ds_read_b128 v[240:243], v151 offset:56320
	global_load_lds_dwordx4 v[154:155], off
	s_add_i32 m0, s7, 0x2000
	s_add_u32 s8, s52, 0x160080
	v_lshl_add_u64 v[154:155], v[156:157], 0, s[24:25]
	s_addc_u32 s9, s53, 0
	s_add_i32 s7, s14, s65
	global_load_lds_dwordx4 v[154:155], off
	v_lshl_add_u64 v[154:155], s[8:9], 0, v[2:3]
	s_mov_b32 m0, s7
	s_nop 0
	global_load_lds_dwordx4 v[154:155], off
	v_lshl_add_u64 v[154:155], s[8:9], 0, v[136:137]
	s_add_i32 m0, s7, 0x2000
	s_nop 0
	global_load_lds_dwordx4 v[154:155], off
	v_lshl_add_u64 v[154:155], v[158:159], 0, s[24:25]
	s_mov_b32 m0, s79
	s_nop 0
	global_load_lds_dwordx4 v[154:155], off
	v_lshl_add_u64 v[154:155], v[164:165], 0, s[24:25]
	s_mov_b32 m0, s80
	s_nop 0
	global_load_lds_dwordx4 v[154:155], off
	s_waitcnt vmcnt(8)
	s_waitcnt lgkmcnt(0)
	s_barrier
	s_waitcnt lgkmcnt(0)
	v_mfma_f32_16x16x32_bf16 v[64:67], v[142:145], v[212:215], v[64:67]
	v_mfma_f32_16x16x32_bf16 v[60:63], v[176:179], v[212:215], v[60:63]
	v_mfma_f32_16x16x32_bf16 v[48:51], v[142:145], v[220:223], v[48:51]
	v_mfma_f32_16x16x32_bf16 v[44:47], v[176:179], v[220:223], v[44:47]
	v_mfma_f32_16x16x32_bf16 v[32:35], v[142:145], v[228:231], v[32:35]
	v_mfma_f32_16x16x32_bf16 v[28:31], v[176:179], v[228:231], v[28:31]
	v_mfma_f32_16x16x32_bf16 v[16:19], v[142:145], v[236:239], v[16:19]
	v_mfma_f32_16x16x32_bf16 v[12:15], v[176:179], v[236:239], v[12:15]
	v_mfma_f32_16x16x32_bf16 v[64:67], v[172:175], v[216:219], v[64:67]
	v_mfma_f32_16x16x32_bf16 v[60:63], v[180:183], v[216:219], v[60:63]
	v_mfma_f32_16x16x32_bf16 v[48:51], v[172:175], v[224:227], v[48:51]
	v_mfma_f32_16x16x32_bf16 v[44:47], v[180:183], v[224:227], v[44:47]
	v_mfma_f32_16x16x32_bf16 v[32:35], v[172:175], v[232:235], v[32:35]
	v_mfma_f32_16x16x32_bf16 v[28:31], v[180:183], v[232:235], v[28:31]
	v_mfma_f32_16x16x32_bf16 v[16:19], v[172:175], v[240:243], v[16:19]
	v_mfma_f32_16x16x32_bf16 v[12:15], v[180:183], v[240:243], v[12:15]
	v_mfma_f32_16x16x32_bf16 v[56:59], v[184:187], v[212:215], v[56:59]
	v_mfma_f32_16x16x32_bf16 v[52:55], v[192:195], v[212:215], v[52:55]
	v_mfma_f32_16x16x32_bf16 v[40:43], v[184:187], v[220:223], v[40:43]
	v_mfma_f32_16x16x32_bf16 v[36:39], v[192:195], v[220:223], v[36:39]
	v_mfma_f32_16x16x32_bf16 v[24:27], v[184:187], v[228:231], v[24:27]
	v_mfma_f32_16x16x32_bf16 v[20:23], v[192:195], v[228:231], v[20:23]
	v_mfma_f32_16x16x32_bf16 v[8:11], v[184:187], v[236:239], v[8:11]
	v_mfma_f32_16x16x32_bf16 v[4:7], v[192:195], v[236:239], v[4:7]
	v_mfma_f32_16x16x32_bf16 v[56:59], v[188:191], v[216:219], v[56:59]
	v_mfma_f32_16x16x32_bf16 v[52:55], v[208:211], v[216:219], v[52:55]
	v_mfma_f32_16x16x32_bf16 v[40:43], v[188:191], v[224:227], v[40:43]
	v_mfma_f32_16x16x32_bf16 v[36:39], v[208:211], v[224:227], v[36:39]
	v_mfma_f32_16x16x32_bf16 v[24:27], v[188:191], v[232:235], v[24:27]
	v_mfma_f32_16x16x32_bf16 v[20:23], v[208:211], v[232:235], v[20:23]
	v_mfma_f32_16x16x32_bf16 v[8:11], v[188:191], v[240:243], v[8:11]
	v_mfma_f32_16x16x32_bf16 v[4:7], v[208:211], v[240:243], v[4:7]
	s_barrier
	s_add_i32 s6, s6, 2
	s_add_u32 s4, s4, 0x100
	s_addc_u32 s5, s5, 0
	s_cmpk_gt_u32 s6, 0x55
	s_mov_b64 s[36:37], s[50:51]
	s_cbranch_scc0 .LBB0_2770
	s_and_b64 vcc, exec, s[46:47]
	s_cbranch_vccz .LBB0_2773
	s_barrier
; __device__ __forceinline__ u32x4 pack8(f32x4 a, f32x4 b) { u32x4 w; w.x = cvt_pk_bf16(a[0], a[1]); w.y = cvt_pk_bf16(a[2], a[3]); w.z = cvt_pk_bf16(b[0], b[1]); w.w = cvt_pk_bf16(b[2], b[3]); return w; }
;     __device__ __forceinline__ void operator()(const f32x4 (&acc)[2][2][4][2], const Unit& u, int wr, int wc, int fr, int fq, const float (&rsv)[2][4]) const {
;         const int row0 = u.pm * BM + wr * 64 + fr, col0 = u.pn * BM + wc * 32 + 8 * fq;
;         f32x4 cv[2][2];
; #pragma unroll
;         for (int bj = 0; bj < 2; ++bj)
; #pragma unroll
;             for (int n = 0; n < 2; ++n) cv[bj][n] = cs ? *(const f32x4*)(cs + col0 + bj * HALF + 4 * n) : (f32x4){1.f, 1.f, 1.f, 1.f};
; #pragma unroll
;         for (int ai = 0; ai < 2; ++ai)
; #pragma unroll
;             for (int m = 0; m < 4; ++m) { const int row = row0 + ai * HALF + m * 16; float ss = 0.f;
; #pragma unroll
;                 for (int bj = 0; bj < 2; ++bj) { bf16_t* xp = XB + (size_t)row * D + col0 + bj * HALF;
;                     f32x4 a, b; unpack8(*(const u32x4*)xp, a, b);
;                     a += acc[ai][bj][m][0] * cv[bj][0]; b += acc[ai][bj][m][1] * cv[bj][1];
;                     const u32x4 w = pack8(a, b); *(u32x4*)xp = w; unpack8(w, a, b);
;                     ss += (a[0] * a[0] + a[1] * a[1]) + (a[2] * a[2] + a[3] * a[3]) + (b[0] * b[0] + b[1] * b[1]) + (b[2] * b[2] + b[3] * b[3]); }
;                 ss += __shfl_xor(ss, 16); ss += __shfl_xor(ss, 32);
;                 if (fq == 0) red[(ai * HALF + wr * 64 + m * 16 + fr) * 4 + wc] = ss;
;                 asm volatile("" ::: "memory"); }
;         asm volatile("s_waitcnt lgkmcnt(0)" ::: "memory"); __builtin_amdgcn_s_barrier(); asm volatile("" ::: "memory");
.LBB0_2773:
	s_setprio 0
	s_lshl_b32 s19, s19, 8
	v_add_u32_e32 v144, s19, v146
	v_ashrrev_i32_e32 v145, 31, v144
	v_lshl_or_b32 v142, s18, 8, v148
	v_lshlrev_b64 v[154:155], 12, v[144:145]
	v_ashrrev_i32_e32 v143, 31, v142
	v_lshl_add_u64 v[154:155], s[0:1], 0, v[154:155]
	v_lshl_add_u64 v[154:155], v[142:143], 1, v[154:155]
	global_load_dwordx4 v[172:175], v[154:155], off
	s_waitcnt vmcnt(0)
	v_lshlrev_b32_e32 v156, 16, v172
	v_and_b32_e32 v157, 0xffff0000, v172
	v_lshlrev_b32_e32 v158, 16, v173
	v_and_b32_e32 v159, 0xffff0000, v173
	v_lshlrev_b32_e32 v164, 16, v174
	v_and_b32_e32 v165, 0xffff0000, v174
	v_lshlrev_b32_e32 v172, 16, v175
	v_and_b32_e32 v173, 0xffff0000, v175
	v_pk_add_f32 v[128:129], v[128:129], v[156:157]
	v_pk_add_f32 v[130:131], v[130:131], v[158:159]
	v_pk_add_f32 v[156:157], v[126:127], v[172:173]
	v_pk_add_f32 v[124:125], v[124:125], v[164:165]
	v_cvt_pk_bf16_f32 v126, v128, v129
	v_cvt_pk_bf16_f32 v127, v130, v131
	s_nop 0
	v_cvt_pk_bf16_f32 v128, v124, v125
	v_cvt_pk_bf16_f32 v129, v156, v157
	global_load_dwordx4 v[172:175], v[154:155], off offset:256
	v_lshlrev_b32_e32 v130, 16, v126
	global_store_dwordx4 v[154:155], v[126:129], off
	v_lshlrev_b32_e32 v131, 16, v127
	v_lshlrev_b32_e32 v153, 16, v128
	v_and_b32_e32 v126, 0xffff0000, v126
	v_and_b32_e32 v127, 0xffff0000, v127
	v_and_b32_e32 v128, 0xffff0000, v128
	v_mul_f32_e32 v126, v126, v126
	v_mul_f32_e32 v127, v127, v127
	v_lshlrev_b32_e32 v156, 16, v129
	v_and_b32_e32 v129, 0xffff0000, v129
	v_mul_f32_e32 v128, v128, v128
	v_fmac_f32_e32 v126, v130, v130
	v_fmac_f32_e32 v127, v131, v131
	v_mul_f32_e32 v129, v129, v129
	v_fmac_f32_e32 v128, v153, v153
	v_add_f32_e32 v126, v126, v127
	v_fmac_f32_e32 v129, v156, v156
	v_add_f32_e32 v126, v126, v128
	v_add_f32_e32 v153, v126, v129
	v_and_b32_e32 v125, 64, v204
	v_xor_b32_e32 v124, 16, v204
	v_add_u32_e32 v125, 64, v125
	v_cmp_lt_i32_e32 vcc, v124, v125
	s_waitcnt vmcnt(1)
	v_lshlrev_b32_e32 v126, 16, v172
	v_and_b32_e32 v127, 0xffff0000, v172
	v_lshlrev_b32_e32 v128, 16, v173
	v_and_b32_e32 v129, 0xffff0000, v173
	v_lshlrev_b32_e32 v130, 16, v174
	v_and_b32_e32 v131, 0xffff0000, v174
	v_lshlrev_b32_e32 v156, 16, v175
	v_and_b32_e32 v157, 0xffff0000, v175
	v_pk_add_f32 v[122:123], v[122:123], v[128:129]
	v_pk_add_f32 v[120:121], v[120:121], v[126:127]
	v_pk_add_f32 v[118:119], v[118:119], v[156:157]
	v_pk_add_f32 v[116:117], v[116:117], v[130:131]
	v_cvt_pk_bf16_f32 v120, v120, v121
	v_cvt_pk_bf16_f32 v121, v122, v123
	v_cndmask_b32_e32 v124, v204, v124, vcc
	v_cvt_pk_bf16_f32 v122, v116, v117
	v_cvt_pk_bf16_f32 v123, v118, v119
	v_and_b32_e32 v117, 0xffff0000, v120
	v_and_b32_e32 v119, 0xffff0000, v121
	v_lshlrev_b32_e32 v116, 16, v120
	v_lshlrev_b32_e32 v118, 16, v121
	v_and_b32_e32 v127, 0xffff0000, v122
	v_mul_f32_e32 v117, v117, v117
	v_mul_f32_e32 v119, v119, v119
	v_lshlrev_b32_e32 v126, 16, v122
	v_and_b32_e32 v129, 0xffff0000, v123
	v_mul_f32_e32 v127, v127, v127
	v_fmac_f32_e32 v117, v116, v116
	v_fmac_f32_e32 v119, v118, v118
	v_lshlrev_b32_e32 v128, 16, v123
	v_mul_f32_e32 v129, v129, v129
	v_fmac_f32_e32 v127, v126, v126
	v_add_f32_e32 v116, v117, v119
	v_fmac_f32_e32 v129, v128, v128
	v_add_f32_e32 v116, v116, v127
	v_add_f32_e32 v116, v116, v129
	v_lshlrev_b32_e32 v124, 2, v124
	v_add_f32_e32 v116, v153, v116
	ds_bpermute_b32 v117, v124, v116
	v_xor_b32_e32 v118, 32, v204
	v_cmp_lt_i32_e32 vcc, v118, v125
	global_store_dwordx4 v[154:155], v[120:123], off offset:256
	s_waitcnt lgkmcnt(0)
	v_add_f32_e32 v117, v116, v117
	v_cndmask_b32_e32 v118, v204, v118, vcc
	v_lshlrev_b32_e32 v116, 2, v118
	ds_bpermute_b32 v118, v116, v117
	s_and_saveexec_b64 s[36:37], s[38:39]
	s_cbranch_execz .LBB0_2775
	s_waitcnt lgkmcnt(0)
	v_add_f32_e32 v117, v117, v118
	ds_write_b32 v150, v117
